# static s_setprio 1 for waves 4-7 at kernel entry, all per-segment flips removed (strategy: one static priority raise for the younger half)
# speedup vs baseline: 1.0056x; 1.0037x over previous
_Z6mk_fwd6Params:
	s_load_dwordx2 s[42:43], s[0:1], 0xe8
	s_add_u32 s8, s0, 0xe8
	v_and_b32_e32 v1, 0x3ff, v0
	s_addc_u32 s9, s1, 0
	v_readfirstlane_b32 s68, v1
	s_nop 3
	s_lshr_b32 s98, s68, 6
	s_cmp_ge_u32 s98, 4
	s_cbranch_scc0 .Lprio_static_done
	s_setprio 1
.Lprio_static_done:
	v_cmp_gt_u32_e32 vcc, 64, v1
	s_and_saveexec_b64 s[4:5], vcc
	v_lshl_add_u32 v2, v1, 2, 0
	v_add_u32_e32 v2, 0x21800, v2
	v_mov_b32_e32 v3, 0
	ds_write_b32 v2, v3
	v_writelane_b32 v255, s8, 0
	s_nop 1
	v_writelane_b32 v255, s9, 1
	s_or_b64 exec, exec, s[4:5]
	s_mov_b64 s[4:5], s[0:1]
	s_waitcnt lgkmcnt(0)
	s_barrier
	s_load_dwordx2 s[38:39], s[4:5], 0xe0
	s_getreg_b32 s3, hwreg(HW_REG_XCC_ID, 0, 4)
	v_cmp_eq_u32_e64 s[28:29], 0, v1
	s_waitcnt lgkmcnt(0)
	s_add_u32 s40, s38, 0x1b000000
	s_addc_u32 s41, s39, 0
	s_and_b32 s33, s3, 15
	s_and_saveexec_b64 s[4:5], s[28:29]
	s_cbranch_execz .LBB0_5
	s_mov_b64 s[6:7], exec
	v_mbcnt_lo_u32_b32 v2, s6, 0
	v_mbcnt_hi_u32_b32 v2, s7, v2
	v_cmp_eq_u32_e32 vcc, 0, v2
	s_and_b64 s[8:9], exec, vcc
	s_mov_b64 exec, s[8:9]
	s_cbranch_execz .LBB0_5
	s_lshl_b32 s3, s33, 8
	s_bcnt1_i32_b64 s6, s[6:7]
	v_mov_b32_e32 v2, s3
	v_mov_b32_e32 v3, s6
	global_atomic_add v2, v3, s[40:41] offset:1024

.LBB0_153:
	ds_read_b128 v[0:3], v145
	ds_read_b128 v[4:7], v145 offset:1024
	ds_read_b128 v[8:11], v145 offset:2048
	ds_read_b128 v[12:15], v145 offset:3072
	ds_read_b128 v[16:19], v146
	ds_read_b128 v[20:23], v146 offset:1024
	ds_read_b128 v[24:27], v146 offset:2048
	ds_read_b128 v[28:31], v146 offset:3072
	s_ashr_i32 s37, s36, 31
	s_lshl_b64 s[46:47], s[36:37], 17
	s_add_u32 s46, s44, s46
	s_addc_u32 s47, s45, s47
	s_and_b64 s[48:49], s[4:5], exec
	s_cselect_b32 s59, s47, s53
	s_cselect_b32 s58, s46, s52
	s_ashr_i32 s35, s34, 31
	s_lshl_b64 s[48:49], s[34:35], 17
	s_add_u32 s48, s60, s48
	s_addc_u32 s49, s61, s49
	s_and_b64 s[56:57], s[4:5], exec
	s_cselect_b32 s57, s49, s55
	s_cselect_b32 s56, s48, s54
	s_add_u32 s80, s52, 0x10080
	s_addc_u32 s81, s53, 0
	s_add_i32 s83, s51, 0xc000
	v_lshl_add_u64 v[64:65], s[80:81], 0, v[128:129]
	s_mov_b32 m0, s83
	s_add_i32 s35, s51, 0xe000
	ds_read_b128 v[32:35], v147
	ds_read_b128 v[36:39], v147 offset:1024
	ds_read_b128 v[40:43], v147 offset:2048
	ds_read_b128 v[44:47], v147 offset:3072
	ds_read_b128 v[48:51], v147 offset:4096
	ds_read_b128 v[52:55], v147 offset:5120
	ds_read_b128 v[56:59], v147 offset:6144
	ds_read_b128 v[60:63], v147 offset:7168
	global_load_lds_dwordx4 v[64:65], off
	v_lshl_add_u64 v[64:65], s[80:81], 0, v[132:133]
	s_mov_b32 m0, s35
	s_nop 0
	global_load_lds_dwordx4 v[64:65], off
	s_waitcnt vmcnt(8)
	s_waitcnt lgkmcnt(0)
	s_barrier
	v_mfma_f32_16x16x32_bf16 v[64:67], v[0:3], v[32:35], 0
	v_mfma_f32_16x16x32_bf16 v[68:71], v[8:11], v[32:35], 0
	v_mfma_f32_16x16x32_bf16 v[72:75], v[0:3], v[40:43], 0
	v_mfma_f32_16x16x32_bf16 v[76:79], v[8:11], v[40:43], 0
	v_mfma_f32_16x16x32_bf16 v[80:83], v[0:3], v[48:51], 0
	v_mfma_f32_16x16x32_bf16 v[84:87], v[8:11], v[48:51], 0
	v_mfma_f32_16x16x32_bf16 v[88:91], v[0:3], v[56:59], 0
	v_mfma_f32_16x16x32_bf16 v[92:95], v[8:11], v[56:59], 0
	v_mfma_f32_16x16x32_bf16 v[64:67], v[4:7], v[36:39], v[64:67]
	v_mfma_f32_16x16x32_bf16 v[68:71], v[12:15], v[36:39], v[68:71]
	v_mfma_f32_16x16x32_bf16 v[72:75], v[4:7], v[44:47], v[72:75]
	v_mfma_f32_16x16x32_bf16 v[76:79], v[12:15], v[44:47], v[76:79]
	v_mfma_f32_16x16x32_bf16 v[80:83], v[4:7], v[52:55], v[80:83]
	v_mfma_f32_16x16x32_bf16 v[84:87], v[12:15], v[52:55], v[84:87]
	v_mfma_f32_16x16x32_bf16 v[88:91], v[4:7], v[60:63], v[88:91]
	v_mfma_f32_16x16x32_bf16 v[92:95], v[12:15], v[60:63], v[92:95]
	v_mfma_f32_16x16x32_bf16 v[96:99], v[16:19], v[32:35], 0
	v_mfma_f32_16x16x32_bf16 v[32:35], v[24:27], v[32:35], 0
	v_mfma_f32_16x16x32_bf16 v[96:99], v[20:23], v[36:39], v[96:99]
	v_mfma_f32_16x16x32_bf16 v[32:35], v[28:31], v[36:39], v[32:35]
	v_mfma_f32_16x16x32_bf16 v[36:39], v[16:19], v[40:43], 0
	v_mfma_f32_16x16x32_bf16 v[40:43], v[24:27], v[40:43], 0
	v_mfma_f32_16x16x32_bf16 v[36:39], v[20:23], v[44:47], v[36:39]
	v_mfma_f32_16x16x32_bf16 v[40:43], v[28:31], v[44:47], v[40:43]
	v_mfma_f32_16x16x32_bf16 v[44:47], v[16:19], v[48:51], 0
	v_mfma_f32_16x16x32_bf16 v[48:51], v[24:27], v[48:51], 0
	v_mfma_f32_16x16x32_bf16 v[44:47], v[20:23], v[52:55], v[44:47]
	v_mfma_f32_16x16x32_bf16 v[48:51], v[28:31], v[52:55], v[48:51]
	v_mfma_f32_16x16x32_bf16 v[52:55], v[16:19], v[56:59], 0
	v_mfma_f32_16x16x32_bf16 v[56:59], v[24:27], v[56:59], 0
	v_mfma_f32_16x16x32_bf16 v[52:55], v[20:23], v[60:63], v[52:55]
	v_mfma_f32_16x16x32_bf16 v[56:59], v[28:31], v[60:63], v[56:59]
	s_barrier
	s_add_i32 s81, s72, s62
	v_lshl_add_u64 v[140:141], s[54:55], 0, v[130:131]
	s_add_i32 s37, s81, 0x2000
	v_lshl_add_u64 v[148:149], v[140:141], 0, s[18:19]
	s_mov_b32 m0, s81
	v_lshl_add_u64 v[212:213], s[54:55], 0, v[134:135]
	s_add_u32 s84, s54, 0x10100
	ds_read_b128 v[60:63], v147 offset:16384
	ds_read_b128 v[100:103], v147 offset:17408
	ds_read_b128 v[104:107], v147 offset:18432
	ds_read_b128 v[108:111], v147 offset:19456
	ds_read_b128 v[112:115], v147 offset:20480
	ds_read_b128 v[116:119], v147 offset:21504
	ds_read_b128 v[120:123], v147 offset:22528
	ds_read_b128 v[124:127], v147 offset:23552
	global_load_lds_dwordx4 v[148:149], off
	v_lshl_add_u64 v[148:149], v[212:213], 0, s[18:19]
	s_mov_b32 m0, s37
	s_addc_u32 s85, s55, 0
	s_add_i32 s79, s73, s62
	global_load_lds_dwordx4 v[148:149], off
	v_lshl_add_u64 v[148:149], s[84:85], 0, v[130:131]
	s_mov_b32 m0, s79
	s_add_i32 s80, s79, 0x2000
	global_load_lds_dwordx4 v[148:149], off
	v_lshl_add_u64 v[148:149], s[84:85], 0, v[134:135]
	s_mov_b32 m0, s80
	v_lshl_add_u64 v[214:215], s[52:53], 0, v[128:129]
	global_load_lds_dwordx4 v[148:149], off
	v_lshl_add_u64 v[148:149], v[214:215], 0, s[18:19]
	s_mov_b32 m0, s51
	v_lshl_add_u64 v[216:217], s[52:53], 0, v[132:133]
	global_load_lds_dwordx4 v[148:149], off
	v_lshl_add_u64 v[148:149], v[216:217], 0, s[18:19]
	s_mov_b32 m0, s63
	s_nop 0
	global_load_lds_dwordx4 v[148:149], off
	s_waitcnt vmcnt(8)
	s_waitcnt lgkmcnt(0)
	s_barrier
	v_mfma_f32_16x16x32_bf16 v[148:151], v[0:3], v[60:63], 0
	v_mfma_f32_16x16x32_bf16 v[156:159], v[0:3], v[104:107], 0
	v_mfma_f32_16x16x32_bf16 v[164:167], v[0:3], v[112:115], 0
	v_mfma_f32_16x16x32_bf16 v[0:3], v[0:3], v[120:123], 0
	v_mfma_f32_16x16x32_bf16 v[148:151], v[4:7], v[100:103], v[148:151]
	v_mfma_f32_16x16x32_bf16 v[156:159], v[4:7], v[108:111], v[156:159]
	v_mfma_f32_16x16x32_bf16 v[164:167], v[4:7], v[116:119], v[164:167]
	v_mfma_f32_16x16x32_bf16 v[0:3], v[4:7], v[124:127], v[0:3]
	v_mfma_f32_16x16x32_bf16 v[4:7], v[8:11], v[120:123], 0
	v_mfma_f32_16x16x32_bf16 v[152:155], v[8:11], v[60:63], 0
	v_mfma_f32_16x16x32_bf16 v[160:163], v[8:11], v[104:107], 0
	v_mfma_f32_16x16x32_bf16 v[168:171], v[8:11], v[112:115], 0
	v_mfma_f32_16x16x32_bf16 v[4:7], v[12:15], v[124:127], v[4:7]
	v_mfma_f32_16x16x32_bf16 v[152:155], v[12:15], v[100:103], v[152:155]
	v_mfma_f32_16x16x32_bf16 v[160:163], v[12:15], v[108:111], v[160:163]
	v_mfma_f32_16x16x32_bf16 v[168:171], v[12:15], v[116:119], v[168:171]
	v_mfma_f32_16x16x32_bf16 v[8:11], v[16:19], v[60:63], 0
	v_mfma_f32_16x16x32_bf16 v[12:15], v[24:27], v[60:63], 0
	v_mfma_f32_16x16x32_bf16 v[8:11], v[20:23], v[100:103], v[8:11]
	v_mfma_f32_16x16x32_bf16 v[12:15], v[28:31], v[100:103], v[12:15]
	v_mfma_f32_16x16x32_bf16 v[60:63], v[16:19], v[104:107], 0
	v_mfma_f32_16x16x32_bf16 v[100:103], v[24:27], v[104:107], 0
	v_mfma_f32_16x16x32_bf16 v[104:107], v[16:19], v[112:115], 0
	v_mfma_f32_16x16x32_bf16 v[16:19], v[16:19], v[120:123], 0
	v_mfma_f32_16x16x32_bf16 v[60:63], v[20:23], v[108:111], v[60:63]
	v_mfma_f32_16x16x32_bf16 v[100:103], v[28:31], v[108:111], v[100:103]
	v_mfma_f32_16x16x32_bf16 v[104:107], v[20:23], v[116:119], v[104:107]
	v_mfma_f32_16x16x32_bf16 v[108:111], v[24:27], v[112:115], 0
	v_mfma_f32_16x16x32_bf16 v[16:19], v[20:23], v[124:127], v[16:19]
	v_mfma_f32_16x16x32_bf16 v[20:23], v[24:27], v[120:123], 0
	v_mfma_f32_16x16x32_bf16 v[108:111], v[28:31], v[116:119], v[108:111]
	v_mfma_f32_16x16x32_bf16 v[20:23], v[28:31], v[124:127], v[20:23]
	s_barrier
	s_add_i32 s82, 0, 0x18000
	s_add_i32 s88, 0, 0x1c000
	v_add_u32_e32 v228, s82, v143
	v_add_u32_e32 v236, s88, v143
	ds_read_b128 v[24:27], v228
	ds_read_b128 v[28:31], v228 offset:1024
	ds_read_b128 v[112:115], v228 offset:2048
	ds_read_b128 v[116:119], v228 offset:3072
	ds_read_b128 v[120:123], v236
	ds_read_b128 v[124:127], v236 offset:1024
	ds_read_b128 v[172:175], v236 offset:2048
	ds_read_b128 v[176:179], v236 offset:3072
	s_add_u32 s84, s52, 0x10100
	s_addc_u32 s85, s53, 0
	s_mov_b32 m0, s64
	v_lshl_add_u64 v[218:219], s[84:85], 0, v[128:129]
	ds_read_b128 v[180:183], v147 offset:32768
	ds_read_b128 v[184:187], v147 offset:33792
	ds_read_b128 v[188:191], v147 offset:34816
	ds_read_b128 v[192:195], v147 offset:35840
	ds_read_b128 v[196:199], v147 offset:36864
	ds_read_b128 v[200:203], v147 offset:37888
	ds_read_b128 v[204:207], v147 offset:38912
	ds_read_b128 v[208:211], v147 offset:39936
	global_load_lds_dwordx4 v[218:219], off
	v_lshl_add_u64 v[218:219], s[84:85], 0, v[132:133]
	s_mov_b32 m0, s65
	s_nop 0
	global_load_lds_dwordx4 v[218:219], off
	s_waitcnt vmcnt(8)
	s_waitcnt lgkmcnt(0)
	s_barrier
	v_mfma_f32_16x16x32_bf16 v[64:67], v[24:27], v[180:183], v[64:67]
	v_mfma_f32_16x16x32_bf16 v[68:71], v[112:115], v[180:183], v[68:71]
	v_mfma_f32_16x16x32_bf16 v[72:75], v[24:27], v[188:191], v[72:75]
	v_mfma_f32_16x16x32_bf16 v[76:79], v[112:115], v[188:191], v[76:79]
	v_mfma_f32_16x16x32_bf16 v[80:83], v[24:27], v[196:199], v[80:83]
	v_mfma_f32_16x16x32_bf16 v[84:87], v[112:115], v[196:199], v[84:87]
	v_mfma_f32_16x16x32_bf16 v[88:91], v[24:27], v[204:207], v[88:91]
	v_mfma_f32_16x16x32_bf16 v[92:95], v[112:115], v[204:207], v[92:95]
	v_mfma_f32_16x16x32_bf16 v[64:67], v[28:31], v[184:187], v[64:67]
	v_mfma_f32_16x16x32_bf16 v[68:71], v[116:119], v[184:187], v[68:71]
	v_mfma_f32_16x16x32_bf16 v[72:75], v[28:31], v[192:195], v[72:75]
	v_mfma_f32_16x16x32_bf16 v[76:79], v[116:119], v[192:195], v[76:79]
	v_mfma_f32_16x16x32_bf16 v[80:83], v[28:31], v[200:203], v[80:83]
	v_mfma_f32_16x16x32_bf16 v[84:87], v[116:119], v[200:203], v[84:87]
	v_mfma_f32_16x16x32_bf16 v[88:91], v[28:31], v[208:211], v[88:91]
	v_mfma_f32_16x16x32_bf16 v[92:95], v[116:119], v[208:211], v[92:95]
	v_mfma_f32_16x16x32_bf16 v[96:99], v[120:123], v[180:183], v[96:99]
	v_mfma_f32_16x16x32_bf16 v[32:35], v[172:175], v[180:183], v[32:35]
	v_mfma_f32_16x16x32_bf16 v[36:39], v[120:123], v[188:191], v[36:39]
	v_mfma_f32_16x16x32_bf16 v[40:43], v[172:175], v[188:191], v[40:43]
	v_mfma_f32_16x16x32_bf16 v[44:47], v[120:123], v[196:199], v[44:47]
	v_mfma_f32_16x16x32_bf16 v[48:51], v[172:175], v[196:199], v[48:51]
	v_mfma_f32_16x16x32_bf16 v[52:55], v[120:123], v[204:207], v[52:55]
	v_mfma_f32_16x16x32_bf16 v[56:59], v[172:175], v[204:207], v[56:59]
	v_mfma_f32_16x16x32_bf16 v[96:99], v[124:127], v[184:187], v[96:99]
	v_mfma_f32_16x16x32_bf16 v[32:35], v[176:179], v[184:187], v[32:35]
	v_mfma_f32_16x16x32_bf16 v[36:39], v[124:127], v[192:195], v[36:39]
	v_mfma_f32_16x16x32_bf16 v[40:43], v[176:179], v[192:195], v[40:43]
	v_mfma_f32_16x16x32_bf16 v[44:47], v[124:127], v[200:203], v[44:47]
	v_mfma_f32_16x16x32_bf16 v[48:51], v[176:179], v[200:203], v[48:51]
	v_mfma_f32_16x16x32_bf16 v[52:55], v[124:127], v[208:211], v[52:55]
	v_mfma_f32_16x16x32_bf16 v[56:59], v[176:179], v[208:211], v[56:59]
	s_barrier
	s_add_i32 s84, s82, s62
	s_add_i32 s82, s84, 0x2000
	v_lshl_add_u64 v[140:141], v[140:141], 0, s[20:21]
	s_mov_b32 m0, s84
	s_add_u32 s86, s54, 0x10180
	ds_read_b128 v[180:183], v147 offset:49152
	ds_read_b128 v[184:187], v147 offset:50176
	ds_read_b128 v[188:191], v147 offset:51200
	ds_read_b128 v[192:195], v147 offset:52224
	ds_read_b128 v[196:199], v147 offset:53248
	ds_read_b128 v[200:203], v147 offset:54272
	ds_read_b128 v[204:207], v147 offset:55296
	ds_read_b128 v[208:211], v147 offset:56320
	global_load_lds_dwordx4 v[140:141], off
	v_lshl_add_u64 v[140:141], v[212:213], 0, s[20:21]
	s_mov_b32 m0, s82
	s_addc_u32 s87, s55, 0
	s_add_i32 s54, s88, s62
	global_load_lds_dwordx4 v[140:141], off
	v_lshl_add_u64 v[140:141], s[86:87], 0, v[130:131]
	s_mov_b32 m0, s54
	s_add_i32 s55, s54, 0x2000
	global_load_lds_dwordx4 v[140:141], off
	v_lshl_add_u64 v[140:141], s[86:87], 0, v[134:135]
	s_mov_b32 m0, s55
	s_nop 0
	global_load_lds_dwordx4 v[140:141], off
	v_lshl_add_u64 v[140:141], v[214:215], 0, s[20:21]
	s_mov_b32 m0, s66
	s_nop 0
	global_load_lds_dwordx4 v[140:141], off
	v_lshl_add_u64 v[140:141], v[216:217], 0, s[20:21]
	s_mov_b32 m0, s67
	s_nop 0
	global_load_lds_dwordx4 v[140:141], off
	s_waitcnt vmcnt(8)
	s_waitcnt lgkmcnt(0)
	s_barrier
	v_mfma_f32_16x16x32_bf16 v[0:3], v[24:27], v[204:207], v[0:3]
	v_mfma_f32_16x16x32_bf16 v[4:7], v[112:115], v[204:207], v[4:7]
	v_mfma_f32_16x16x32_bf16 v[148:151], v[24:27], v[180:183], v[148:151]
	v_mfma_f32_16x16x32_bf16 v[152:155], v[112:115], v[180:183], v[152:155]
	v_mfma_f32_16x16x32_bf16 v[156:159], v[24:27], v[188:191], v[156:159]
	v_mfma_f32_16x16x32_bf16 v[160:163], v[112:115], v[188:191], v[160:163]
	v_mfma_f32_16x16x32_bf16 v[164:167], v[24:27], v[196:199], v[164:167]
	v_mfma_f32_16x16x32_bf16 v[168:171], v[112:115], v[196:199], v[168:171]
	v_mfma_f32_16x16x32_bf16 v[0:3], v[28:31], v[208:211], v[0:3]
	v_mfma_f32_16x16x32_bf16 v[4:7], v[116:119], v[208:211], v[4:7]
	v_mfma_f32_16x16x32_bf16 v[148:151], v[28:31], v[184:187], v[148:151]
	v_mfma_f32_16x16x32_bf16 v[152:155], v[116:119], v[184:187], v[152:155]
	v_mfma_f32_16x16x32_bf16 v[156:159], v[28:31], v[192:195], v[156:159]
	v_mfma_f32_16x16x32_bf16 v[160:163], v[116:119], v[192:195], v[160:163]
	v_mfma_f32_16x16x32_bf16 v[164:167], v[28:31], v[200:203], v[164:167]
	v_mfma_f32_16x16x32_bf16 v[168:171], v[116:119], v[200:203], v[168:171]
	v_mfma_f32_16x16x32_bf16 v[8:11], v[120:123], v[180:183], v[8:11]
	v_mfma_f32_16x16x32_bf16 v[12:15], v[172:175], v[180:183], v[12:15]
	v_mfma_f32_16x16x32_bf16 v[24:27], v[120:123], v[188:191], v[60:63]
	v_mfma_f32_16x16x32_bf16 v[28:31], v[172:175], v[188:191], v[100:103]
	v_mfma_f32_16x16x32_bf16 v[60:63], v[120:123], v[196:199], v[104:107]
	v_mfma_f32_16x16x32_bf16 v[100:103], v[172:175], v[196:199], v[108:111]
	v_mfma_f32_16x16x32_bf16 v[16:19], v[120:123], v[204:207], v[16:19]
	v_mfma_f32_16x16x32_bf16 v[20:23], v[172:175], v[204:207], v[20:23]
	v_mfma_f32_16x16x32_bf16 v[8:11], v[124:127], v[184:187], v[8:11]
	v_mfma_f32_16x16x32_bf16 v[12:15], v[176:179], v[184:187], v[12:15]
	v_mfma_f32_16x16x32_bf16 v[24:27], v[124:127], v[192:195], v[24:27]
	v_mfma_f32_16x16x32_bf16 v[28:31], v[176:179], v[192:195], v[28:31]
	v_mfma_f32_16x16x32_bf16 v[60:63], v[124:127], v[200:203], v[60:63]
	v_mfma_f32_16x16x32_bf16 v[100:103], v[176:179], v[200:203], v[100:103]
	v_mfma_f32_16x16x32_bf16 v[16:19], v[124:127], v[208:211], v[16:19]
	v_mfma_f32_16x16x32_bf16 v[20:23], v[176:179], v[208:211], v[20:23]
	s_barrier
	ds_read_b128 v[104:107], v145
	ds_read_b128 v[108:111], v145 offset:1024
	ds_read_b128 v[112:115], v145 offset:2048
	ds_read_b128 v[116:119], v145 offset:3072
	ds_read_b128 v[120:123], v146
	ds_read_b128 v[124:127], v146 offset:1024
	ds_read_b128 v[172:175], v146 offset:2048
	ds_read_b128 v[176:179], v146 offset:3072
	s_add_u32 s52, s52, 0x10180
	s_addc_u32 s53, s53, 0
	s_mov_b32 m0, s83
	v_lshl_add_u64 v[140:141], s[52:53], 0, v[128:129]
	ds_read_b128 v[180:183], v147
	ds_read_b128 v[184:187], v147 offset:1024
	ds_read_b128 v[188:191], v147 offset:2048
	ds_read_b128 v[192:195], v147 offset:3072
	ds_read_b128 v[196:199], v147 offset:4096
	ds_read_b128 v[200:203], v147 offset:5120
	ds_read_b128 v[204:207], v147 offset:6144
	ds_read_b128 v[208:211], v147 offset:7168
	global_load_lds_dwordx4 v[140:141], off
	v_lshl_add_u64 v[140:141], s[52:53], 0, v[132:133]
	s_mov_b32 m0, s35
	s_nop 0
	global_load_lds_dwordx4 v[140:141], off
	s_waitcnt vmcnt(8)
	s_waitcnt lgkmcnt(0)
	s_barrier
	v_mfma_f32_16x16x32_bf16 v[88:91], v[104:107], v[204:207], v[88:91]
	v_mfma_f32_16x16x32_bf16 v[64:67], v[104:107], v[180:183], v[64:67]
	v_mfma_f32_16x16x32_bf16 v[68:71], v[112:115], v[180:183], v[68:71]
	v_mfma_f32_16x16x32_bf16 v[72:75], v[104:107], v[188:191], v[72:75]
	v_mfma_f32_16x16x32_bf16 v[76:79], v[112:115], v[188:191], v[76:79]
	v_mfma_f32_16x16x32_bf16 v[80:83], v[104:107], v[196:199], v[80:83]
	v_mfma_f32_16x16x32_bf16 v[84:87], v[112:115], v[196:199], v[84:87]
	v_mfma_f32_16x16x32_bf16 v[212:215], v[108:111], v[208:211], v[88:91]
	v_mfma_f32_16x16x32_bf16 v[88:91], v[112:115], v[204:207], v[92:95]
	v_mfma_f32_16x16x32_bf16 v[64:67], v[108:111], v[184:187], v[64:67]
	v_mfma_f32_16x16x32_bf16 v[68:71], v[116:119], v[184:187], v[68:71]
	v_mfma_f32_16x16x32_bf16 v[72:75], v[108:111], v[192:195], v[72:75]
	v_mfma_f32_16x16x32_bf16 v[76:79], v[116:119], v[192:195], v[76:79]
	v_mfma_f32_16x16x32_bf16 v[80:83], v[108:111], v[200:203], v[80:83]
	v_mfma_f32_16x16x32_bf16 v[84:87], v[116:119], v[200:203], v[84:87]
	v_mfma_f32_16x16x32_bf16 v[92:95], v[116:119], v[208:211], v[88:91]
	v_mfma_f32_16x16x32_bf16 v[48:51], v[172:175], v[196:199], v[48:51]
	v_mfma_f32_16x16x32_bf16 v[88:91], v[120:123], v[180:183], v[96:99]
	v_mfma_f32_16x16x32_bf16 v[32:35], v[172:175], v[180:183], v[32:35]
	v_mfma_f32_16x16x32_bf16 v[36:39], v[120:123], v[188:191], v[36:39]
	v_mfma_f32_16x16x32_bf16 v[40:43], v[172:175], v[188:191], v[40:43]
	v_mfma_f32_16x16x32_bf16 v[44:47], v[120:123], v[196:199], v[44:47]
	v_mfma_f32_16x16x32_bf16 v[180:183], v[176:179], v[200:203], v[48:51]
	v_mfma_f32_16x16x32_bf16 v[48:51], v[120:123], v[204:207], v[52:55]
	v_mfma_f32_16x16x32_bf16 v[32:35], v[176:179], v[184:187], v[32:35]
	v_mfma_f32_16x16x32_bf16 v[36:39], v[124:127], v[192:195], v[36:39]
	v_mfma_f32_16x16x32_bf16 v[40:43], v[176:179], v[192:195], v[40:43]
	v_mfma_f32_16x16x32_bf16 v[44:47], v[124:127], v[200:203], v[44:47]
	v_mfma_f32_16x16x32_bf16 v[52:55], v[124:127], v[208:211], v[48:51]
	v_mfma_f32_16x16x32_bf16 v[48:51], v[172:175], v[204:207], v[56:59]
	v_mfma_f32_16x16x32_bf16 v[220:223], v[124:127], v[184:187], v[88:91]
	v_mfma_f32_16x16x32_bf16 v[184:187], v[176:179], v[208:211], v[48:51]
	s_barrier
	s_mov_b32 m0, s81
	v_lshl_add_u64 v[140:141], s[56:57], 0, v[130:131]
	s_add_u32 s52, s56, 0x10000
	s_nop 0
	ds_read_b128 v[48:51], v147 offset:16384
	ds_read_b128 v[56:59], v147 offset:17408
	ds_read_b128 v[88:91], v147 offset:18432
	ds_read_b128 v[96:99], v147 offset:19456
	ds_read_b128 v[188:191], v147 offset:20480
	ds_read_b128 v[192:195], v147 offset:21504
	ds_read_b128 v[196:199], v147 offset:22528
	ds_read_b128 v[200:203], v147 offset:23552
	global_load_lds_dwordx4 v[140:141], off
	v_lshl_add_u64 v[252:253], s[56:57], 0, v[134:135]
	s_mov_b32 m0, s37
	s_addc_u32 s53, s57, 0
	global_load_lds_dwordx4 v[252:253], off
	v_lshl_add_u64 v[204:205], s[52:53], 0, v[130:131]
	s_mov_b32 m0, s79
	v_lshl_add_u64 v[136:137], s[58:59], 0, v[128:129]
	global_load_lds_dwordx4 v[204:205], off
	v_lshl_add_u64 v[204:205], s[52:53], 0, v[134:135]
	s_mov_b32 m0, s80
	v_lshl_add_u64 v[138:139], s[58:59], 0, v[132:133]
	global_load_lds_dwordx4 v[204:205], off
	s_mov_b32 m0, s51
	s_nop 0
	global_load_lds_dwordx4 v[136:137], off
	s_mov_b32 m0, s63
	s_nop 0
	global_load_lds_dwordx4 v[138:139], off
	s_waitcnt vmcnt(8)
	s_waitcnt lgkmcnt(0)
	s_barrier
	v_mfma_f32_16x16x32_bf16 v[0:3], v[104:107], v[196:199], v[0:3]
	v_mfma_f32_16x16x32_bf16 v[4:7], v[112:115], v[196:199], v[4:7]
	v_mfma_f32_16x16x32_bf16 v[148:151], v[104:107], v[48:51], v[148:151]
	v_mfma_f32_16x16x32_bf16 v[152:155], v[112:115], v[48:51], v[152:155]
	v_mfma_f32_16x16x32_bf16 v[156:159], v[104:107], v[88:91], v[156:159]
	v_mfma_f32_16x16x32_bf16 v[160:163], v[112:115], v[88:91], v[160:163]
	v_mfma_f32_16x16x32_bf16 v[164:167], v[104:107], v[188:191], v[164:167]
	v_mfma_f32_16x16x32_bf16 v[168:171], v[112:115], v[188:191], v[168:171]
	v_mfma_f32_16x16x32_bf16 v[0:3], v[108:111], v[200:203], v[0:3]
	v_mfma_f32_16x16x32_bf16 v[4:7], v[116:119], v[200:203], v[4:7]
	v_mfma_f32_16x16x32_bf16 v[148:151], v[108:111], v[56:59], v[148:151]
	v_mfma_f32_16x16x32_bf16 v[152:155], v[116:119], v[56:59], v[152:155]
	v_mfma_f32_16x16x32_bf16 v[156:159], v[108:111], v[96:99], v[156:159]
	v_mfma_f32_16x16x32_bf16 v[160:163], v[116:119], v[96:99], v[160:163]
	v_mfma_f32_16x16x32_bf16 v[164:167], v[108:111], v[192:195], v[164:167]
	v_mfma_f32_16x16x32_bf16 v[168:171], v[116:119], v[192:195], v[168:171]
	v_mfma_f32_16x16x32_bf16 v[12:15], v[172:175], v[48:51], v[12:15]
	v_mfma_f32_16x16x32_bf16 v[204:207], v[176:179], v[56:59], v[12:15]
	v_mfma_f32_16x16x32_bf16 v[12:15], v[120:123], v[88:91], v[24:27]
	v_mfma_f32_16x16x32_bf16 v[24:27], v[124:127], v[96:99], v[12:15]
	v_mfma_f32_16x16x32_bf16 v[12:15], v[172:175], v[88:91], v[28:31]
	v_mfma_f32_16x16x32_bf16 v[208:211], v[176:179], v[96:99], v[12:15]
	v_mfma_f32_16x16x32_bf16 v[12:15], v[120:123], v[188:191], v[60:63]
	v_mfma_f32_16x16x32_bf16 v[224:227], v[124:127], v[192:195], v[12:15]
	v_mfma_f32_16x16x32_bf16 v[12:15], v[172:175], v[188:191], v[100:103]
	v_mfma_f32_16x16x32_bf16 v[8:11], v[120:123], v[48:51], v[8:11]
	v_mfma_f32_16x16x32_bf16 v[188:191], v[176:179], v[192:195], v[12:15]
	v_mfma_f32_16x16x32_bf16 v[12:15], v[120:123], v[196:199], v[16:19]
	v_mfma_f32_16x16x32_bf16 v[8:11], v[124:127], v[56:59], v[8:11]
	v_mfma_f32_16x16x32_bf16 v[192:195], v[124:127], v[200:203], v[12:15]
	v_mfma_f32_16x16x32_bf16 v[12:15], v[172:175], v[196:199], v[20:23]
	v_mfma_f32_16x16x32_bf16 v[172:175], v[176:179], v[200:203], v[12:15]
	s_barrier
	s_nop 4
	ds_read_b128 v[12:15], v228
	ds_read_b128 v[16:19], v228 offset:1024
	ds_read_b128 v[176:179], v228 offset:2048
	ds_read_b128 v[196:199], v228 offset:3072
	ds_read_b128 v[200:203], v236
	ds_read_b128 v[228:231], v236 offset:1024
	ds_read_b128 v[232:235], v236 offset:2048
	ds_read_b128 v[236:239], v236 offset:3072
	s_add_u32 s52, s58, 0x10000
	s_addc_u32 s53, s59, 0
	s_mov_b32 m0, s64
	v_lshl_add_u64 v[48:49], s[52:53], 0, v[128:129]
	ds_read_b128 v[20:23], v147 offset:32768
	ds_read_b128 v[28:31], v147 offset:33792
	ds_read_b128 v[60:63], v147 offset:34816
	ds_read_b128 v[100:103], v147 offset:35840
	ds_read_b128 v[240:243], v147 offset:36864
	ds_read_b128 v[244:247], v147 offset:37888
	ds_read_b128 v[248:251], v147 offset:38912
	ds_read_b128 v[216:219], v147 offset:39936
	global_load_lds_dwordx4 v[48:49], off
	v_lshl_add_u64 v[48:49], s[52:53], 0, v[132:133]
	s_mov_b32 m0, s65
	s_nop 0
	global_load_lds_dwordx4 v[48:49], off
	s_waitcnt vmcnt(8)
	s_waitcnt lgkmcnt(0)
	s_barrier
	v_mfma_f32_16x16x32_bf16 v[48:51], v[12:15], v[20:23], v[64:67]
	v_mfma_f32_16x16x32_bf16 v[120:123], v[16:19], v[28:31], v[48:51]
	v_mfma_f32_16x16x32_bf16 v[48:51], v[176:179], v[20:23], v[68:71]
	v_mfma_f32_16x16x32_bf16 v[112:115], v[196:199], v[28:31], v[48:51]
	v_mfma_f32_16x16x32_bf16 v[48:51], v[12:15], v[60:63], v[72:75]
	v_mfma_f32_16x16x32_bf16 v[104:107], v[16:19], v[100:103], v[48:51]
	v_mfma_f32_16x16x32_bf16 v[48:51], v[176:179], v[60:63], v[76:79]
	v_mfma_f32_16x16x32_bf16 v[96:99], v[196:199], v[100:103], v[48:51]
	v_mfma_f32_16x16x32_bf16 v[48:51], v[12:15], v[240:243], v[80:83]
	v_mfma_f32_16x16x32_bf16 v[88:91], v[16:19], v[244:247], v[48:51]
	v_mfma_f32_16x16x32_bf16 v[48:51], v[176:179], v[240:243], v[84:87]
	v_mfma_f32_16x16x32_bf16 v[80:83], v[196:199], v[244:247], v[48:51]
	v_mfma_f32_16x16x32_bf16 v[48:51], v[12:15], v[248:251], v[212:215]
	v_mfma_f32_16x16x32_bf16 v[56:59], v[16:19], v[216:219], v[48:51]
	v_mfma_f32_16x16x32_bf16 v[48:51], v[176:179], v[248:251], v[92:95]
	v_mfma_f32_16x16x32_bf16 v[48:51], v[196:199], v[216:219], v[48:51]
	v_mfma_f32_16x16x32_bf16 v[64:67], v[200:203], v[20:23], v[220:223]
	v_mfma_f32_16x16x32_bf16 v[20:23], v[232:235], v[20:23], v[32:35]
	v_mfma_f32_16x16x32_bf16 v[116:119], v[236:239], v[28:31], v[20:23]
	v_mfma_f32_16x16x32_bf16 v[20:23], v[200:203], v[60:63], v[36:39]
	v_mfma_f32_16x16x32_bf16 v[108:111], v[228:231], v[100:103], v[20:23]
	v_mfma_f32_16x16x32_bf16 v[20:23], v[232:235], v[60:63], v[40:43]
	v_mfma_f32_16x16x32_bf16 v[100:103], v[236:239], v[100:103], v[20:23]
	v_mfma_f32_16x16x32_bf16 v[20:23], v[200:203], v[240:243], v[44:47]
	v_mfma_f32_16x16x32_bf16 v[92:95], v[228:231], v[244:247], v[20:23]
	v_mfma_f32_16x16x32_bf16 v[20:23], v[232:235], v[240:243], v[180:183]
	v_mfma_f32_16x16x32_bf16 v[84:87], v[236:239], v[244:247], v[20:23]
	v_mfma_f32_16x16x32_bf16 v[20:23], v[200:203], v[248:251], v[52:55]
	v_mfma_f32_16x16x32_bf16 v[60:63], v[228:231], v[216:219], v[20:23]
	v_mfma_f32_16x16x32_bf16 v[20:23], v[232:235], v[248:251], v[184:187]
	v_mfma_f32_16x16x32_bf16 v[124:127], v[228:231], v[28:31], v[64:67]
	v_mfma_f32_16x16x32_bf16 v[52:55], v[236:239], v[216:219], v[20:23]
	s_barrier
	s_mov_b32 m0, s84
	s_nop 2
	v_lshl_add_u64 v[20:21], v[140:141], 0, s[12:13]
	s_add_u32 s52, s56, 0x10080
	ds_read_b128 v[32:35], v147 offset:49152
	ds_read_b128 v[40:43], v147 offset:50176
	ds_read_b128 v[180:183], v147 offset:51200
	ds_read_b128 v[184:187], v147 offset:52224
	ds_read_b128 v[212:215], v147 offset:53248
	ds_read_b128 v[216:219], v147 offset:54272
	ds_read_b128 v[220:223], v147 offset:55296
	ds_read_b128 v[240:243], v147 offset:56320
	global_load_lds_dwordx4 v[20:21], off
	v_lshl_add_u64 v[20:21], v[252:253], 0, s[12:13]
	s_mov_b32 m0, s82
	s_addc_u32 s53, s57, 0
	global_load_lds_dwordx4 v[20:21], off
	v_lshl_add_u64 v[20:21], s[52:53], 0, v[130:131]
	s_mov_b32 m0, s54
	s_nop 0
	global_load_lds_dwordx4 v[20:21], off
	v_lshl_add_u64 v[20:21], s[52:53], 0, v[134:135]
	s_mov_b32 m0, s55
	s_nop 0
	global_load_lds_dwordx4 v[20:21], off
	v_lshl_add_u64 v[20:21], v[136:137], 0, s[12:13]
	s_mov_b32 m0, s66
	s_nop 0
	global_load_lds_dwordx4 v[20:21], off
	v_lshl_add_u64 v[20:21], v[138:139], 0, s[12:13]
	s_mov_b32 m0, s67
	s_nop 0
	global_load_lds_dwordx4 v[20:21], off
	s_waitcnt vmcnt(8)
	s_waitcnt lgkmcnt(0)
	s_barrier
	v_mfma_f32_16x16x32_bf16 v[20:23], v[12:15], v[32:35], v[148:151]
	v_mfma_f32_16x16x32_bf16 v[76:79], v[16:19], v[40:43], v[20:23]
	v_mfma_f32_16x16x32_bf16 v[20:23], v[176:179], v[32:35], v[152:155]
	v_mfma_f32_16x16x32_bf16 v[68:71], v[196:199], v[40:43], v[20:23]
	v_mfma_f32_16x16x32_bf16 v[20:23], v[12:15], v[180:183], v[156:159]
	v_mfma_f32_16x16x32_bf16 v[44:47], v[16:19], v[184:187], v[20:23]
	v_mfma_f32_16x16x32_bf16 v[20:23], v[176:179], v[180:183], v[160:163]
	v_mfma_f32_16x16x32_bf16 v[36:39], v[196:199], v[184:187], v[20:23]
	v_mfma_f32_16x16x32_bf16 v[20:23], v[12:15], v[212:215], v[164:167]
	v_mfma_f32_16x16x32_bf16 v[0:3], v[12:15], v[220:223], v[0:3]
	v_mfma_f32_16x16x32_bf16 v[28:31], v[16:19], v[216:219], v[20:23]
	v_mfma_f32_16x16x32_bf16 v[20:23], v[176:179], v[212:215], v[168:171]
	v_mfma_f32_16x16x32_bf16 v[12:15], v[16:19], v[240:243], v[0:3]
	v_mfma_f32_16x16x32_bf16 v[0:3], v[176:179], v[220:223], v[4:7]
	v_mfma_f32_16x16x32_bf16 v[20:23], v[196:199], v[216:219], v[20:23]
	v_mfma_f32_16x16x32_bf16 v[4:7], v[196:199], v[240:243], v[0:3]
	v_mfma_f32_16x16x32_bf16 v[0:3], v[200:203], v[32:35], v[8:11]
	v_mfma_f32_16x16x32_bf16 v[72:75], v[228:231], v[40:43], v[0:3]
	v_mfma_f32_16x16x32_bf16 v[0:3], v[232:235], v[32:35], v[204:207]
	v_mfma_f32_16x16x32_bf16 v[64:67], v[236:239], v[40:43], v[0:3]
	v_mfma_f32_16x16x32_bf16 v[0:3], v[200:203], v[180:183], v[24:27]
	v_mfma_f32_16x16x32_bf16 v[40:43], v[228:231], v[184:187], v[0:3]
	v_mfma_f32_16x16x32_bf16 v[0:3], v[232:235], v[180:183], v[208:211]
	v_mfma_f32_16x16x32_bf16 v[32:35], v[236:239], v[184:187], v[0:3]
	v_mfma_f32_16x16x32_bf16 v[0:3], v[200:203], v[212:215], v[224:227]
	v_mfma_f32_16x16x32_bf16 v[24:27], v[228:231], v[216:219], v[0:3]
	v_mfma_f32_16x16x32_bf16 v[0:3], v[232:235], v[212:215], v[188:191]
	v_mfma_f32_16x16x32_bf16 v[16:19], v[236:239], v[216:219], v[0:3]
	v_mfma_f32_16x16x32_bf16 v[0:3], v[200:203], v[220:223], v[192:195]
	v_mfma_f32_16x16x32_bf16 v[8:11], v[228:231], v[240:243], v[0:3]
	v_mfma_f32_16x16x32_bf16 v[0:3], v[232:235], v[220:223], v[172:175]
	v_mfma_f32_16x16x32_bf16 v[0:3], v[236:239], v[240:243], v[0:3]
	s_barrier
	s_andn2_b64 vcc, exec, s[14:15]
	s_cbranch_vccnz .LBB0_155
	s_barrier

.LBB0_178:
	ds_read_b128 v[148:151], v157
	ds_read_b128 v[162:165], v157 offset:1024
	ds_read_b128 v[166:169], v157 offset:2048
	ds_read_b128 v[170:173], v157 offset:3072
	ds_read_b128 v[174:177], v158
	ds_read_b128 v[178:181], v158 offset:1024
	ds_read_b128 v[182:185], v158 offset:2048
	ds_read_b128 v[186:189], v158 offset:3072
	s_add_u32 s48, s46, 0xfff80080
	s_addc_u32 s49, s47, -1
	s_cmp_eq_u32 s72, 28
	s_cselect_b32 s51, s31, s49
	s_cselect_b32 s50, s66, s48
	s_cselect_b32 s49, s27, s71
	s_cselect_b32 s48, s67, s70
	v_lshl_add_u64 v[152:153], s[46:47], 0, v[142:143]
	s_add_i32 m0, s13, 0xc000
	ds_read_b128 v[190:193], v159
	ds_read_b128 v[194:197], v159 offset:1024
	ds_read_b128 v[198:201], v159 offset:2048
	ds_read_b128 v[202:205], v159 offset:3072
	ds_read_b128 v[206:209], v159 offset:4096
	ds_read_b128 v[210:213], v159 offset:5120
	ds_read_b128 v[214:217], v159 offset:6144
	ds_read_b128 v[218:221], v159 offset:7168
	global_load_lds_dwordx4 v[152:153], off
	v_lshl_add_u64 v[152:153], s[46:47], 0, v[140:141]
	s_add_i32 m0, s13, 0xe000
	s_nop 0
	global_load_lds_dwordx4 v[152:153], off
	s_waitcnt vmcnt(8)
	s_waitcnt lgkmcnt(0)
	s_barrier
	v_mfma_f32_16x16x32_bf16 v[124:127], v[148:151], v[190:193], v[124:127]
	v_mfma_f32_16x16x32_bf16 v[120:123], v[166:169], v[190:193], v[120:123]
	v_mfma_f32_16x16x32_bf16 v[108:111], v[148:151], v[198:201], v[108:111]
	v_mfma_f32_16x16x32_bf16 v[104:107], v[166:169], v[198:201], v[104:107]
	v_mfma_f32_16x16x32_bf16 v[92:95], v[148:151], v[206:209], v[92:95]
	v_mfma_f32_16x16x32_bf16 v[88:91], v[166:169], v[206:209], v[88:91]
	v_mfma_f32_16x16x32_bf16 v[76:79], v[148:151], v[214:217], v[76:79]
	v_mfma_f32_16x16x32_bf16 v[72:75], v[166:169], v[214:217], v[72:75]
	v_mfma_f32_16x16x32_bf16 v[124:127], v[162:165], v[194:197], v[124:127]
	v_mfma_f32_16x16x32_bf16 v[120:123], v[170:173], v[194:197], v[120:123]
	v_mfma_f32_16x16x32_bf16 v[108:111], v[162:165], v[202:205], v[108:111]
	v_mfma_f32_16x16x32_bf16 v[104:107], v[170:173], v[202:205], v[104:107]
	v_mfma_f32_16x16x32_bf16 v[92:95], v[162:165], v[210:213], v[92:95]
	v_mfma_f32_16x16x32_bf16 v[88:91], v[170:173], v[210:213], v[88:91]
	v_mfma_f32_16x16x32_bf16 v[76:79], v[162:165], v[218:221], v[76:79]
	v_mfma_f32_16x16x32_bf16 v[72:75], v[170:173], v[218:221], v[72:75]
	v_mfma_f32_16x16x32_bf16 v[116:119], v[174:177], v[190:193], v[116:119]
	v_mfma_f32_16x16x32_bf16 v[112:115], v[182:185], v[190:193], v[112:115]
	v_mfma_f32_16x16x32_bf16 v[100:103], v[174:177], v[198:201], v[100:103]
	v_mfma_f32_16x16x32_bf16 v[96:99], v[182:185], v[198:201], v[96:99]
	v_mfma_f32_16x16x32_bf16 v[84:87], v[174:177], v[206:209], v[84:87]
	v_mfma_f32_16x16x32_bf16 v[80:83], v[182:185], v[206:209], v[80:83]
	v_mfma_f32_16x16x32_bf16 v[68:71], v[174:177], v[214:217], v[68:71]
	v_mfma_f32_16x16x32_bf16 v[64:67], v[182:185], v[214:217], v[64:67]
	v_mfma_f32_16x16x32_bf16 v[116:119], v[178:181], v[194:197], v[116:119]
	v_mfma_f32_16x16x32_bf16 v[112:115], v[186:189], v[194:197], v[112:115]
	v_mfma_f32_16x16x32_bf16 v[100:103], v[178:181], v[202:205], v[100:103]
	v_mfma_f32_16x16x32_bf16 v[96:99], v[186:189], v[202:205], v[96:99]
	v_mfma_f32_16x16x32_bf16 v[84:87], v[178:181], v[210:213], v[84:87]
	v_mfma_f32_16x16x32_bf16 v[80:83], v[186:189], v[210:213], v[80:83]
	v_mfma_f32_16x16x32_bf16 v[68:71], v[178:181], v[218:221], v[68:71]
	v_mfma_f32_16x16x32_bf16 v[64:67], v[186:189], v[218:221], v[64:67]
	s_barrier
	s_add_i32 s73, s62, s52
	v_lshl_add_u64 v[152:153], s[48:49], 0, v[130:131]
	s_mov_b32 m0, s73
	ds_read_b128 v[190:193], v159 offset:16384
	ds_read_b128 v[194:197], v159 offset:17408
	ds_read_b128 v[198:201], v159 offset:18432
	ds_read_b128 v[202:205], v159 offset:19456
	ds_read_b128 v[206:209], v159 offset:20480
	ds_read_b128 v[210:213], v159 offset:21504
	ds_read_b128 v[214:217], v159 offset:22528
	ds_read_b128 v[218:221], v159 offset:23552
	global_load_lds_dwordx4 v[152:153], off
	s_add_i32 m0, s73, 0x2000
	s_add_u32 s74, s48, 0x80000
	v_lshl_add_u64 v[222:223], s[48:49], 0, v[134:135]
	s_addc_u32 s75, s49, 0
	s_add_i32 s73, s63, s52
	global_load_lds_dwordx4 v[222:223], off
	v_lshl_add_u64 v[224:225], s[74:75], 0, v[130:131]
	s_mov_b32 m0, s73
	v_lshl_add_u64 v[226:227], s[50:51], 0, v[132:133]
	global_load_lds_dwordx4 v[224:225], off
	v_lshl_add_u64 v[224:225], s[74:75], 0, v[134:135]
	s_add_i32 m0, s73, 0x2000
	s_nop 0
	global_load_lds_dwordx4 v[224:225], off
	v_lshl_add_u64 v[224:225], s[50:51], 0, v[128:129]
	s_mov_b32 m0, s13
	s_nop 0
	global_load_lds_dwordx4 v[224:225], off
	s_mov_b32 m0, s53
	s_nop 0
	global_load_lds_dwordx4 v[226:227], off
	s_waitcnt vmcnt(8)
	s_waitcnt lgkmcnt(0)
	s_barrier
	v_mfma_f32_16x16x32_bf16 v[60:63], v[148:151], v[190:193], v[60:63]
	v_mfma_f32_16x16x32_bf16 v[56:59], v[166:169], v[190:193], v[56:59]
	v_mfma_f32_16x16x32_bf16 v[44:47], v[148:151], v[198:201], v[44:47]
	v_mfma_f32_16x16x32_bf16 v[40:43], v[166:169], v[198:201], v[40:43]
	v_mfma_f32_16x16x32_bf16 v[28:31], v[148:151], v[206:209], v[28:31]
	v_mfma_f32_16x16x32_bf16 v[24:27], v[166:169], v[206:209], v[24:27]
	v_mfma_f32_16x16x32_bf16 v[12:15], v[148:151], v[214:217], v[12:15]
	v_mfma_f32_16x16x32_bf16 v[8:11], v[166:169], v[214:217], v[8:11]
	v_mfma_f32_16x16x32_bf16 v[60:63], v[162:165], v[194:197], v[60:63]
	v_mfma_f32_16x16x32_bf16 v[56:59], v[170:173], v[194:197], v[56:59]
	v_mfma_f32_16x16x32_bf16 v[44:47], v[162:165], v[202:205], v[44:47]
	v_mfma_f32_16x16x32_bf16 v[40:43], v[170:173], v[202:205], v[40:43]
	v_mfma_f32_16x16x32_bf16 v[28:31], v[162:165], v[210:213], v[28:31]
	v_mfma_f32_16x16x32_bf16 v[24:27], v[170:173], v[210:213], v[24:27]
	v_mfma_f32_16x16x32_bf16 v[12:15], v[162:165], v[218:221], v[12:15]
	v_mfma_f32_16x16x32_bf16 v[8:11], v[170:173], v[218:221], v[8:11]
	v_mfma_f32_16x16x32_bf16 v[52:55], v[174:177], v[190:193], v[52:55]
	v_mfma_f32_16x16x32_bf16 v[48:51], v[182:185], v[190:193], v[48:51]
	v_mfma_f32_16x16x32_bf16 v[36:39], v[174:177], v[198:201], v[36:39]
	v_mfma_f32_16x16x32_bf16 v[32:35], v[182:185], v[198:201], v[32:35]
	v_mfma_f32_16x16x32_bf16 v[20:23], v[174:177], v[206:209], v[20:23]
	v_mfma_f32_16x16x32_bf16 v[16:19], v[182:185], v[206:209], v[16:19]
	v_mfma_f32_16x16x32_bf16 v[4:7], v[174:177], v[214:217], v[4:7]
	v_mfma_f32_16x16x32_bf16 v[0:3], v[182:185], v[214:217], v[0:3]
	v_mfma_f32_16x16x32_bf16 v[52:55], v[178:181], v[194:197], v[52:55]
	v_mfma_f32_16x16x32_bf16 v[48:51], v[186:189], v[194:197], v[48:51]
	v_mfma_f32_16x16x32_bf16 v[36:39], v[178:181], v[202:205], v[36:39]
	v_mfma_f32_16x16x32_bf16 v[32:35], v[186:189], v[202:205], v[32:35]
	v_mfma_f32_16x16x32_bf16 v[20:23], v[178:181], v[210:213], v[20:23]
	v_mfma_f32_16x16x32_bf16 v[16:19], v[186:189], v[210:213], v[16:19]
	v_mfma_f32_16x16x32_bf16 v[4:7], v[178:181], v[218:221], v[4:7]
	v_mfma_f32_16x16x32_bf16 v[0:3], v[186:189], v[218:221], v[0:3]
	s_barrier
	s_add_i32 s73, 0, 0x18000
	v_add_u32_e32 v137, s73, v155
	s_add_i32 s74, 0, 0x1c000
	ds_read_b128 v[148:151], v137
	ds_read_b128 v[162:165], v137 offset:1024
	ds_read_b128 v[166:169], v137 offset:2048
	ds_read_b128 v[170:173], v137 offset:3072
	v_add_u32_e32 v137, s74, v155
	ds_read_b128 v[174:177], v137
	ds_read_b128 v[178:181], v137 offset:1024
	ds_read_b128 v[182:185], v137 offset:2048
	ds_read_b128 v[186:189], v137 offset:3072
	s_add_u32 s50, s50, 0x80000
	s_addc_u32 s51, s51, 0
	s_mov_b32 m0, s54
	v_lshl_add_u64 v[228:229], s[50:51], 0, v[128:129]
	ds_read_b128 v[190:193], v159 offset:32768
	ds_read_b128 v[194:197], v159 offset:33792
	ds_read_b128 v[198:201], v159 offset:34816
	ds_read_b128 v[202:205], v159 offset:35840
	ds_read_b128 v[206:209], v159 offset:36864
	ds_read_b128 v[210:213], v159 offset:37888
	ds_read_b128 v[214:217], v159 offset:38912
	ds_read_b128 v[218:221], v159 offset:39936
	global_load_lds_dwordx4 v[228:229], off
	v_lshl_add_u64 v[228:229], s[50:51], 0, v[132:133]
	s_mov_b32 m0, s55
	s_nop 0
	global_load_lds_dwordx4 v[228:229], off
	s_waitcnt vmcnt(8)
	s_waitcnt lgkmcnt(0)
	s_barrier
	v_mfma_f32_16x16x32_bf16 v[124:127], v[148:151], v[190:193], v[124:127]
	v_mfma_f32_16x16x32_bf16 v[120:123], v[166:169], v[190:193], v[120:123]
	v_mfma_f32_16x16x32_bf16 v[108:111], v[148:151], v[198:201], v[108:111]
	v_mfma_f32_16x16x32_bf16 v[104:107], v[166:169], v[198:201], v[104:107]
	v_mfma_f32_16x16x32_bf16 v[92:95], v[148:151], v[206:209], v[92:95]
	v_mfma_f32_16x16x32_bf16 v[88:91], v[166:169], v[206:209], v[88:91]
	v_mfma_f32_16x16x32_bf16 v[76:79], v[148:151], v[214:217], v[76:79]
	v_mfma_f32_16x16x32_bf16 v[72:75], v[166:169], v[214:217], v[72:75]
	v_mfma_f32_16x16x32_bf16 v[124:127], v[162:165], v[194:197], v[124:127]
	v_mfma_f32_16x16x32_bf16 v[120:123], v[170:173], v[194:197], v[120:123]
	v_mfma_f32_16x16x32_bf16 v[108:111], v[162:165], v[202:205], v[108:111]
	v_mfma_f32_16x16x32_bf16 v[104:107], v[170:173], v[202:205], v[104:107]
	v_mfma_f32_16x16x32_bf16 v[92:95], v[162:165], v[210:213], v[92:95]
	v_mfma_f32_16x16x32_bf16 v[88:91], v[170:173], v[210:213], v[88:91]
	v_mfma_f32_16x16x32_bf16 v[76:79], v[162:165], v[218:221], v[76:79]
	v_mfma_f32_16x16x32_bf16 v[72:75], v[170:173], v[218:221], v[72:75]
	v_mfma_f32_16x16x32_bf16 v[116:119], v[174:177], v[190:193], v[116:119]
	v_mfma_f32_16x16x32_bf16 v[112:115], v[182:185], v[190:193], v[112:115]
	v_mfma_f32_16x16x32_bf16 v[100:103], v[174:177], v[198:201], v[100:103]
	v_mfma_f32_16x16x32_bf16 v[96:99], v[182:185], v[198:201], v[96:99]
	v_mfma_f32_16x16x32_bf16 v[84:87], v[174:177], v[206:209], v[84:87]
	v_mfma_f32_16x16x32_bf16 v[80:83], v[182:185], v[206:209], v[80:83]
	v_mfma_f32_16x16x32_bf16 v[68:71], v[174:177], v[214:217], v[68:71]
	v_mfma_f32_16x16x32_bf16 v[64:67], v[182:185], v[214:217], v[64:67]
	v_mfma_f32_16x16x32_bf16 v[116:119], v[178:181], v[194:197], v[116:119]
	v_mfma_f32_16x16x32_bf16 v[112:115], v[186:189], v[194:197], v[112:115]
	v_mfma_f32_16x16x32_bf16 v[100:103], v[178:181], v[202:205], v[100:103]
	v_mfma_f32_16x16x32_bf16 v[96:99], v[186:189], v[202:205], v[96:99]
	v_mfma_f32_16x16x32_bf16 v[84:87], v[178:181], v[210:213], v[84:87]
	v_mfma_f32_16x16x32_bf16 v[80:83], v[186:189], v[210:213], v[80:83]
	v_mfma_f32_16x16x32_bf16 v[68:71], v[178:181], v[218:221], v[68:71]
	v_mfma_f32_16x16x32_bf16 v[64:67], v[186:189], v[218:221], v[64:67]
	s_barrier
	s_add_i32 s50, s73, s52
	v_lshl_add_u64 v[152:153], v[152:153], 0, s[22:23]
	s_mov_b32 m0, s50
	ds_read_b128 v[190:193], v159 offset:49152
	ds_read_b128 v[194:197], v159 offset:50176
	ds_read_b128 v[198:201], v159 offset:51200
	ds_read_b128 v[202:205], v159 offset:52224
	ds_read_b128 v[206:209], v159 offset:53248
	ds_read_b128 v[210:213], v159 offset:54272
	ds_read_b128 v[214:217], v159 offset:55296
	ds_read_b128 v[218:221], v159 offset:56320
	global_load_lds_dwordx4 v[152:153], off
	s_add_i32 m0, s50, 0x2000
	s_add_u32 s48, s48, 0x80080
	v_lshl_add_u64 v[152:153], v[222:223], 0, s[22:23]
	s_addc_u32 s49, s49, 0
	s_add_i32 s50, s74, s52
	global_load_lds_dwordx4 v[152:153], off
	v_lshl_add_u64 v[152:153], s[48:49], 0, v[130:131]
	s_mov_b32 m0, s50
	s_nop 0
	global_load_lds_dwordx4 v[152:153], off
	v_lshl_add_u64 v[152:153], s[48:49], 0, v[134:135]
	s_add_i32 m0, s50, 0x2000
	s_nop 0
	global_load_lds_dwordx4 v[152:153], off
	v_lshl_add_u64 v[152:153], v[224:225], 0, s[22:23]
	s_mov_b32 m0, s57
	s_nop 0
	global_load_lds_dwordx4 v[152:153], off
	v_lshl_add_u64 v[152:153], v[226:227], 0, s[22:23]
	s_mov_b32 m0, s58
	s_nop 0
	global_load_lds_dwordx4 v[152:153], off
	s_waitcnt vmcnt(8)
	s_waitcnt lgkmcnt(0)
	s_barrier
	v_mfma_f32_16x16x32_bf16 v[60:63], v[148:151], v[190:193], v[60:63]
	v_mfma_f32_16x16x32_bf16 v[56:59], v[166:169], v[190:193], v[56:59]
	v_mfma_f32_16x16x32_bf16 v[44:47], v[148:151], v[198:201], v[44:47]
	v_mfma_f32_16x16x32_bf16 v[40:43], v[166:169], v[198:201], v[40:43]
	v_mfma_f32_16x16x32_bf16 v[28:31], v[148:151], v[206:209], v[28:31]
	v_mfma_f32_16x16x32_bf16 v[24:27], v[166:169], v[206:209], v[24:27]
	v_mfma_f32_16x16x32_bf16 v[12:15], v[148:151], v[214:217], v[12:15]
	v_mfma_f32_16x16x32_bf16 v[8:11], v[166:169], v[214:217], v[8:11]
	v_mfma_f32_16x16x32_bf16 v[60:63], v[162:165], v[194:197], v[60:63]
	v_mfma_f32_16x16x32_bf16 v[56:59], v[170:173], v[194:197], v[56:59]
	v_mfma_f32_16x16x32_bf16 v[44:47], v[162:165], v[202:205], v[44:47]
	v_mfma_f32_16x16x32_bf16 v[40:43], v[170:173], v[202:205], v[40:43]
	v_mfma_f32_16x16x32_bf16 v[28:31], v[162:165], v[210:213], v[28:31]
	v_mfma_f32_16x16x32_bf16 v[24:27], v[170:173], v[210:213], v[24:27]
	v_mfma_f32_16x16x32_bf16 v[12:15], v[162:165], v[218:221], v[12:15]
	v_mfma_f32_16x16x32_bf16 v[8:11], v[170:173], v[218:221], v[8:11]
	v_mfma_f32_16x16x32_bf16 v[52:55], v[174:177], v[190:193], v[52:55]
	v_mfma_f32_16x16x32_bf16 v[48:51], v[182:185], v[190:193], v[48:51]
	v_mfma_f32_16x16x32_bf16 v[36:39], v[174:177], v[198:201], v[36:39]
	v_mfma_f32_16x16x32_bf16 v[32:35], v[182:185], v[198:201], v[32:35]
	v_mfma_f32_16x16x32_bf16 v[20:23], v[174:177], v[206:209], v[20:23]
	v_mfma_f32_16x16x32_bf16 v[16:19], v[182:185], v[206:209], v[16:19]
	v_mfma_f32_16x16x32_bf16 v[4:7], v[174:177], v[214:217], v[4:7]
	v_mfma_f32_16x16x32_bf16 v[0:3], v[182:185], v[214:217], v[0:3]
	v_mfma_f32_16x16x32_bf16 v[52:55], v[178:181], v[194:197], v[52:55]
	v_mfma_f32_16x16x32_bf16 v[48:51], v[186:189], v[194:197], v[48:51]
	v_mfma_f32_16x16x32_bf16 v[36:39], v[178:181], v[202:205], v[36:39]
	v_mfma_f32_16x16x32_bf16 v[32:35], v[186:189], v[202:205], v[32:35]
	v_mfma_f32_16x16x32_bf16 v[20:23], v[178:181], v[210:213], v[20:23]
	v_mfma_f32_16x16x32_bf16 v[16:19], v[186:189], v[210:213], v[16:19]
	v_mfma_f32_16x16x32_bf16 v[4:7], v[178:181], v[218:221], v[4:7]
	v_mfma_f32_16x16x32_bf16 v[0:3], v[186:189], v[218:221], v[0:3]
	s_barrier
	s_add_i32 s72, s72, 2
	s_add_u32 s70, s70, 0x100
	s_addc_u32 s71, s71, 0
	s_add_u32 s46, s46, 0x100
	s_addc_u32 s47, s47, 0
	s_cmp_gt_u32 s72, 29
	s_cbranch_scc0 .LBB0_178
	s_and_b64 vcc, exec, s[24:25]
	s_cbranch_vccz .LBB0_181
	s_barrier

.LBB0_337:
	ds_read_b128 v[144:147], v151
	ds_read_b128 v[156:159], v151 offset:1024
	ds_read_b128 v[160:163], v151 offset:2048
	ds_read_b128 v[164:167], v151 offset:3072
	ds_read_b128 v[168:171], v152
	ds_read_b128 v[172:175], v152 offset:1024
	ds_read_b128 v[176:179], v152 offset:2048
	ds_read_b128 v[180:183], v152 offset:3072
	s_add_u32 s50, s48, 0xfff80080
	s_addc_u32 s51, s49, -1
	s_cmp_eq_u32 s75, 28
	s_cselect_b32 s53, s31, s51
	s_cselect_b32 s52, s47, s50
	s_cselect_b32 s51, s27, s74
	s_cselect_b32 s50, s71, s72
	v_lshl_add_u64 v[216:217], s[48:49], 0, v[138:139]
	s_add_i32 m0, s57, 0xc000
	ds_read_b128 v[184:187], v153
	ds_read_b128 v[188:191], v153 offset:1024
	ds_read_b128 v[192:195], v153 offset:2048
	ds_read_b128 v[196:199], v153 offset:3072
	ds_read_b128 v[200:203], v153 offset:4096
	ds_read_b128 v[204:207], v153 offset:5120
	ds_read_b128 v[208:211], v153 offset:6144
	ds_read_b128 v[212:215], v153 offset:7168
	global_load_lds_dwordx4 v[216:217], off
	v_lshl_add_u64 v[216:217], s[48:49], 0, v[136:137]
	s_add_i32 m0, s57, 0xe000
	s_nop 0
	global_load_lds_dwordx4 v[216:217], off
	s_waitcnt vmcnt(8)
	s_waitcnt lgkmcnt(0)
	s_barrier
	v_mfma_f32_16x16x32_bf16 v[124:127], v[144:147], v[184:187], v[124:127]
	v_mfma_f32_16x16x32_bf16 v[120:123], v[160:163], v[184:187], v[120:123]
	v_mfma_f32_16x16x32_bf16 v[108:111], v[144:147], v[192:195], v[108:111]
	v_mfma_f32_16x16x32_bf16 v[104:107], v[160:163], v[192:195], v[104:107]
	v_mfma_f32_16x16x32_bf16 v[92:95], v[144:147], v[200:203], v[92:95]
	v_mfma_f32_16x16x32_bf16 v[88:91], v[160:163], v[200:203], v[88:91]
	v_mfma_f32_16x16x32_bf16 v[76:79], v[144:147], v[208:211], v[76:79]
	v_mfma_f32_16x16x32_bf16 v[72:75], v[160:163], v[208:211], v[72:75]
	v_mfma_f32_16x16x32_bf16 v[124:127], v[156:159], v[188:191], v[124:127]
	v_mfma_f32_16x16x32_bf16 v[120:123], v[164:167], v[188:191], v[120:123]
	v_mfma_f32_16x16x32_bf16 v[108:111], v[156:159], v[196:199], v[108:111]
	v_mfma_f32_16x16x32_bf16 v[104:107], v[164:167], v[196:199], v[104:107]
	v_mfma_f32_16x16x32_bf16 v[92:95], v[156:159], v[204:207], v[92:95]
	v_mfma_f32_16x16x32_bf16 v[88:91], v[164:167], v[204:207], v[88:91]
	v_mfma_f32_16x16x32_bf16 v[76:79], v[156:159], v[212:215], v[76:79]
	v_mfma_f32_16x16x32_bf16 v[72:75], v[164:167], v[212:215], v[72:75]
	v_mfma_f32_16x16x32_bf16 v[116:119], v[168:171], v[184:187], v[116:119]
	v_mfma_f32_16x16x32_bf16 v[112:115], v[176:179], v[184:187], v[112:115]
	v_mfma_f32_16x16x32_bf16 v[100:103], v[168:171], v[192:195], v[100:103]
	v_mfma_f32_16x16x32_bf16 v[96:99], v[176:179], v[192:195], v[96:99]
	v_mfma_f32_16x16x32_bf16 v[84:87], v[168:171], v[200:203], v[84:87]
	v_mfma_f32_16x16x32_bf16 v[80:83], v[176:179], v[200:203], v[80:83]
	v_mfma_f32_16x16x32_bf16 v[68:71], v[168:171], v[208:211], v[68:71]
	v_mfma_f32_16x16x32_bf16 v[64:67], v[176:179], v[208:211], v[64:67]
	v_mfma_f32_16x16x32_bf16 v[116:119], v[172:175], v[188:191], v[116:119]
	v_mfma_f32_16x16x32_bf16 v[112:115], v[180:183], v[188:191], v[112:115]
	v_mfma_f32_16x16x32_bf16 v[100:103], v[172:175], v[196:199], v[100:103]
	v_mfma_f32_16x16x32_bf16 v[96:99], v[180:183], v[196:199], v[96:99]
	v_mfma_f32_16x16x32_bf16 v[84:87], v[172:175], v[204:207], v[84:87]
	v_mfma_f32_16x16x32_bf16 v[80:83], v[180:183], v[204:207], v[80:83]
	v_mfma_f32_16x16x32_bf16 v[68:71], v[172:175], v[212:215], v[68:71]
	v_mfma_f32_16x16x32_bf16 v[64:67], v[180:183], v[212:215], v[64:67]
	s_barrier
	s_add_i32 s76, s66, s56
	v_lshl_add_u64 v[216:217], s[50:51], 0, v[130:131]
	s_mov_b32 m0, s76
	ds_read_b128 v[184:187], v153 offset:16384
	ds_read_b128 v[188:191], v153 offset:17408
	ds_read_b128 v[192:195], v153 offset:18432
	ds_read_b128 v[196:199], v153 offset:19456
	ds_read_b128 v[200:203], v153 offset:20480
	ds_read_b128 v[204:207], v153 offset:21504
	ds_read_b128 v[208:211], v153 offset:22528
	ds_read_b128 v[212:215], v153 offset:23552
	global_load_lds_dwordx4 v[216:217], off
	s_add_i32 m0, s76, 0x2000
	s_add_u32 s76, s50, 0x80000
	v_lshl_add_u64 v[218:219], s[50:51], 0, v[134:135]
	s_addc_u32 s77, s51, 0
	s_add_i32 s78, s67, s56
	global_load_lds_dwordx4 v[218:219], off
	v_lshl_add_u64 v[220:221], s[76:77], 0, v[130:131]
	s_mov_b32 m0, s78
	v_lshl_add_u64 v[222:223], s[52:53], 0, v[132:133]
	global_load_lds_dwordx4 v[220:221], off
	v_lshl_add_u64 v[220:221], s[76:77], 0, v[134:135]
	s_add_i32 m0, s78, 0x2000
	s_nop 0
	global_load_lds_dwordx4 v[220:221], off
	v_lshl_add_u64 v[220:221], s[52:53], 0, v[128:129]
	s_mov_b32 m0, s57
	s_nop 0
	global_load_lds_dwordx4 v[220:221], off
	s_mov_b32 m0, s58
	s_nop 0
	global_load_lds_dwordx4 v[222:223], off
	s_waitcnt vmcnt(8)
	s_waitcnt lgkmcnt(0)
	s_barrier
	v_mfma_f32_16x16x32_bf16 v[60:63], v[144:147], v[184:187], v[60:63]
	v_mfma_f32_16x16x32_bf16 v[56:59], v[160:163], v[184:187], v[56:59]
	v_mfma_f32_16x16x32_bf16 v[44:47], v[144:147], v[192:195], v[44:47]
	v_mfma_f32_16x16x32_bf16 v[40:43], v[160:163], v[192:195], v[40:43]
	v_mfma_f32_16x16x32_bf16 v[28:31], v[144:147], v[200:203], v[28:31]
	v_mfma_f32_16x16x32_bf16 v[24:27], v[160:163], v[200:203], v[24:27]
	v_mfma_f32_16x16x32_bf16 v[12:15], v[144:147], v[208:211], v[12:15]
	v_mfma_f32_16x16x32_bf16 v[8:11], v[160:163], v[208:211], v[8:11]
	v_mfma_f32_16x16x32_bf16 v[60:63], v[156:159], v[188:191], v[60:63]
	v_mfma_f32_16x16x32_bf16 v[56:59], v[164:167], v[188:191], v[56:59]
	v_mfma_f32_16x16x32_bf16 v[44:47], v[156:159], v[196:199], v[44:47]
	v_mfma_f32_16x16x32_bf16 v[40:43], v[164:167], v[196:199], v[40:43]
	v_mfma_f32_16x16x32_bf16 v[28:31], v[156:159], v[204:207], v[28:31]
	v_mfma_f32_16x16x32_bf16 v[24:27], v[164:167], v[204:207], v[24:27]
	v_mfma_f32_16x16x32_bf16 v[12:15], v[156:159], v[212:215], v[12:15]
	v_mfma_f32_16x16x32_bf16 v[8:11], v[164:167], v[212:215], v[8:11]
	v_mfma_f32_16x16x32_bf16 v[52:55], v[168:171], v[184:187], v[52:55]
	v_mfma_f32_16x16x32_bf16 v[48:51], v[176:179], v[184:187], v[48:51]
	v_mfma_f32_16x16x32_bf16 v[36:39], v[168:171], v[192:195], v[36:39]
	v_mfma_f32_16x16x32_bf16 v[32:35], v[176:179], v[192:195], v[32:35]
	v_mfma_f32_16x16x32_bf16 v[20:23], v[168:171], v[200:203], v[20:23]
	v_mfma_f32_16x16x32_bf16 v[16:19], v[176:179], v[200:203], v[16:19]
	v_mfma_f32_16x16x32_bf16 v[4:7], v[168:171], v[208:211], v[4:7]
	v_mfma_f32_16x16x32_bf16 v[0:3], v[176:179], v[208:211], v[0:3]
	v_mfma_f32_16x16x32_bf16 v[52:55], v[172:175], v[188:191], v[52:55]
	v_mfma_f32_16x16x32_bf16 v[48:51], v[180:183], v[188:191], v[48:51]
	v_mfma_f32_16x16x32_bf16 v[36:39], v[172:175], v[196:199], v[36:39]
	v_mfma_f32_16x16x32_bf16 v[32:35], v[180:183], v[196:199], v[32:35]
	v_mfma_f32_16x16x32_bf16 v[20:23], v[172:175], v[204:207], v[20:23]
	v_mfma_f32_16x16x32_bf16 v[16:19], v[180:183], v[204:207], v[16:19]
	v_mfma_f32_16x16x32_bf16 v[4:7], v[172:175], v[212:215], v[4:7]
	v_mfma_f32_16x16x32_bf16 v[0:3], v[180:183], v[212:215], v[0:3]
	s_barrier
	s_add_i32 s76, 0, 0x18000
	v_add_u32_e32 v155, s76, v149
	s_add_i32 s77, 0, 0x1c000
	ds_read_b128 v[144:147], v155
	ds_read_b128 v[156:159], v155 offset:1024
	ds_read_b128 v[160:163], v155 offset:2048
	ds_read_b128 v[164:167], v155 offset:3072
	v_add_u32_e32 v155, s77, v149
	ds_read_b128 v[168:171], v155
	ds_read_b128 v[172:175], v155 offset:1024
	ds_read_b128 v[176:179], v155 offset:2048
	ds_read_b128 v[180:183], v155 offset:3072
	s_add_u32 s52, s52, 0x80000
	s_addc_u32 s53, s53, 0
	s_mov_b32 m0, s59
	v_lshl_add_u64 v[224:225], s[52:53], 0, v[128:129]
	ds_read_b128 v[184:187], v153 offset:32768
	ds_read_b128 v[188:191], v153 offset:33792
	ds_read_b128 v[192:195], v153 offset:34816
	ds_read_b128 v[196:199], v153 offset:35840
	ds_read_b128 v[200:203], v153 offset:36864
	ds_read_b128 v[204:207], v153 offset:37888
	ds_read_b128 v[208:211], v153 offset:38912
	ds_read_b128 v[212:215], v153 offset:39936
	global_load_lds_dwordx4 v[224:225], off
	v_lshl_add_u64 v[224:225], s[52:53], 0, v[132:133]
	s_mov_b32 m0, s60
	s_nop 0
	global_load_lds_dwordx4 v[224:225], off
	s_waitcnt vmcnt(8)
	s_waitcnt lgkmcnt(0)
	s_barrier
	v_mfma_f32_16x16x32_bf16 v[124:127], v[144:147], v[184:187], v[124:127]
	v_mfma_f32_16x16x32_bf16 v[120:123], v[160:163], v[184:187], v[120:123]
	v_mfma_f32_16x16x32_bf16 v[108:111], v[144:147], v[192:195], v[108:111]
	v_mfma_f32_16x16x32_bf16 v[104:107], v[160:163], v[192:195], v[104:107]
	v_mfma_f32_16x16x32_bf16 v[92:95], v[144:147], v[200:203], v[92:95]
	v_mfma_f32_16x16x32_bf16 v[88:91], v[160:163], v[200:203], v[88:91]
	v_mfma_f32_16x16x32_bf16 v[76:79], v[144:147], v[208:211], v[76:79]
	v_mfma_f32_16x16x32_bf16 v[72:75], v[160:163], v[208:211], v[72:75]
	v_mfma_f32_16x16x32_bf16 v[124:127], v[156:159], v[188:191], v[124:127]
	v_mfma_f32_16x16x32_bf16 v[120:123], v[164:167], v[188:191], v[120:123]
	v_mfma_f32_16x16x32_bf16 v[108:111], v[156:159], v[196:199], v[108:111]
	v_mfma_f32_16x16x32_bf16 v[104:107], v[164:167], v[196:199], v[104:107]
	v_mfma_f32_16x16x32_bf16 v[92:95], v[156:159], v[204:207], v[92:95]
	v_mfma_f32_16x16x32_bf16 v[88:91], v[164:167], v[204:207], v[88:91]
	v_mfma_f32_16x16x32_bf16 v[76:79], v[156:159], v[212:215], v[76:79]
	v_mfma_f32_16x16x32_bf16 v[72:75], v[164:167], v[212:215], v[72:75]
	v_mfma_f32_16x16x32_bf16 v[116:119], v[168:171], v[184:187], v[116:119]
	v_mfma_f32_16x16x32_bf16 v[112:115], v[176:179], v[184:187], v[112:115]
	v_mfma_f32_16x16x32_bf16 v[100:103], v[168:171], v[192:195], v[100:103]
	v_mfma_f32_16x16x32_bf16 v[96:99], v[176:179], v[192:195], v[96:99]
	v_mfma_f32_16x16x32_bf16 v[84:87], v[168:171], v[200:203], v[84:87]
	v_mfma_f32_16x16x32_bf16 v[80:83], v[176:179], v[200:203], v[80:83]
	v_mfma_f32_16x16x32_bf16 v[68:71], v[168:171], v[208:211], v[68:71]
	v_mfma_f32_16x16x32_bf16 v[64:67], v[176:179], v[208:211], v[64:67]
	v_mfma_f32_16x16x32_bf16 v[116:119], v[172:175], v[188:191], v[116:119]
	v_mfma_f32_16x16x32_bf16 v[112:115], v[180:183], v[188:191], v[112:115]
	v_mfma_f32_16x16x32_bf16 v[100:103], v[172:175], v[196:199], v[100:103]
	v_mfma_f32_16x16x32_bf16 v[96:99], v[180:183], v[196:199], v[96:99]
	v_mfma_f32_16x16x32_bf16 v[84:87], v[172:175], v[204:207], v[84:87]
	v_mfma_f32_16x16x32_bf16 v[80:83], v[180:183], v[204:207], v[80:83]
	v_mfma_f32_16x16x32_bf16 v[68:71], v[172:175], v[212:215], v[68:71]
	v_mfma_f32_16x16x32_bf16 v[64:67], v[180:183], v[212:215], v[64:67]
	s_barrier
	s_add_i32 s52, s76, s56
	v_lshl_add_u64 v[216:217], v[216:217], 0, s[22:23]
	s_mov_b32 m0, s52
	ds_read_b128 v[184:187], v153 offset:49152
	ds_read_b128 v[188:191], v153 offset:50176
	ds_read_b128 v[192:195], v153 offset:51200
	ds_read_b128 v[196:199], v153 offset:52224
	ds_read_b128 v[200:203], v153 offset:53248
	ds_read_b128 v[204:207], v153 offset:54272
	ds_read_b128 v[208:211], v153 offset:55296
	ds_read_b128 v[212:215], v153 offset:56320
	global_load_lds_dwordx4 v[216:217], off
	s_add_i32 m0, s52, 0x2000
	s_add_u32 s50, s50, 0x80080
	v_lshl_add_u64 v[216:217], v[218:219], 0, s[22:23]
	s_addc_u32 s51, s51, 0
	s_add_i32 s52, s77, s56
	global_load_lds_dwordx4 v[216:217], off
	v_lshl_add_u64 v[216:217], s[50:51], 0, v[130:131]
	s_mov_b32 m0, s52
	s_nop 0
	global_load_lds_dwordx4 v[216:217], off
	v_lshl_add_u64 v[216:217], s[50:51], 0, v[134:135]
	s_add_i32 m0, s52, 0x2000
	s_nop 0
	global_load_lds_dwordx4 v[216:217], off
	v_lshl_add_u64 v[216:217], v[220:221], 0, s[22:23]
	s_mov_b32 m0, s62
	s_nop 0
	global_load_lds_dwordx4 v[216:217], off
	v_lshl_add_u64 v[216:217], v[222:223], 0, s[22:23]
	s_mov_b32 m0, s63
	s_nop 0
	global_load_lds_dwordx4 v[216:217], off
	s_waitcnt vmcnt(8)
	s_waitcnt lgkmcnt(0)
	s_barrier
	v_mfma_f32_16x16x32_bf16 v[60:63], v[144:147], v[184:187], v[60:63]
	v_mfma_f32_16x16x32_bf16 v[56:59], v[160:163], v[184:187], v[56:59]
	v_mfma_f32_16x16x32_bf16 v[44:47], v[144:147], v[192:195], v[44:47]
	v_mfma_f32_16x16x32_bf16 v[40:43], v[160:163], v[192:195], v[40:43]
	v_mfma_f32_16x16x32_bf16 v[28:31], v[144:147], v[200:203], v[28:31]
	v_mfma_f32_16x16x32_bf16 v[24:27], v[160:163], v[200:203], v[24:27]
	v_mfma_f32_16x16x32_bf16 v[12:15], v[144:147], v[208:211], v[12:15]
	v_mfma_f32_16x16x32_bf16 v[8:11], v[160:163], v[208:211], v[8:11]
	v_mfma_f32_16x16x32_bf16 v[60:63], v[156:159], v[188:191], v[60:63]
	v_mfma_f32_16x16x32_bf16 v[56:59], v[164:167], v[188:191], v[56:59]
	v_mfma_f32_16x16x32_bf16 v[44:47], v[156:159], v[196:199], v[44:47]
	v_mfma_f32_16x16x32_bf16 v[40:43], v[164:167], v[196:199], v[40:43]
	v_mfma_f32_16x16x32_bf16 v[28:31], v[156:159], v[204:207], v[28:31]
	v_mfma_f32_16x16x32_bf16 v[24:27], v[164:167], v[204:207], v[24:27]
	v_mfma_f32_16x16x32_bf16 v[12:15], v[156:159], v[212:215], v[12:15]
	v_mfma_f32_16x16x32_bf16 v[8:11], v[164:167], v[212:215], v[8:11]
	v_mfma_f32_16x16x32_bf16 v[52:55], v[168:171], v[184:187], v[52:55]
	v_mfma_f32_16x16x32_bf16 v[48:51], v[176:179], v[184:187], v[48:51]
	v_mfma_f32_16x16x32_bf16 v[36:39], v[168:171], v[192:195], v[36:39]
	v_mfma_f32_16x16x32_bf16 v[32:35], v[176:179], v[192:195], v[32:35]
	v_mfma_f32_16x16x32_bf16 v[20:23], v[168:171], v[200:203], v[20:23]
	v_mfma_f32_16x16x32_bf16 v[16:19], v[176:179], v[200:203], v[16:19]
	v_mfma_f32_16x16x32_bf16 v[4:7], v[168:171], v[208:211], v[4:7]
	v_mfma_f32_16x16x32_bf16 v[0:3], v[176:179], v[208:211], v[0:3]
	v_mfma_f32_16x16x32_bf16 v[52:55], v[172:175], v[188:191], v[52:55]
	v_mfma_f32_16x16x32_bf16 v[48:51], v[180:183], v[188:191], v[48:51]
	v_mfma_f32_16x16x32_bf16 v[36:39], v[172:175], v[196:199], v[36:39]
	v_mfma_f32_16x16x32_bf16 v[32:35], v[180:183], v[196:199], v[32:35]
	v_mfma_f32_16x16x32_bf16 v[20:23], v[172:175], v[204:207], v[20:23]
	v_mfma_f32_16x16x32_bf16 v[16:19], v[180:183], v[204:207], v[16:19]
	v_mfma_f32_16x16x32_bf16 v[4:7], v[172:175], v[212:215], v[4:7]
	v_mfma_f32_16x16x32_bf16 v[0:3], v[180:183], v[212:215], v[0:3]
	s_barrier
	s_add_i32 s75, s75, 2
	s_add_u32 s72, s72, 0x100
	s_addc_u32 s74, s74, 0
	s_add_u32 s48, s48, 0x100
	s_addc_u32 s49, s49, 0
	s_cmp_gt_u32 s75, 29
	s_cbranch_scc0 .LBB0_337
	s_and_b64 vcc, exec, s[24:25]
	s_cbranch_vccz .LBB0_340
	s_barrier

.LBB0_435:
	ds_read_b128 v[148:151], v222
	ds_read_b128 v[152:155], v222 offset:1024
	ds_read_b128 v[156:159], v222 offset:2048
	ds_read_b128 v[160:163], v222 offset:3072
	ds_read_b128 v[132:135], v223
	ds_read_b128 v[136:139], v223 offset:1024
	ds_read_b128 v[140:143], v223 offset:2048
	ds_read_b128 v[144:147], v223 offset:3072
	s_add_u32 s10, s54, 0xfff80080
	s_addc_u32 s11, s55, -1
	s_cmp_eq_u32 s84, 28
	s_cselect_b32 s59, s25, s11
	s_cselect_b32 s58, s46, s10
	s_cselect_b32 s57, s23, s83
	s_cselect_b32 s56, s47, s82
	v_lshl_add_u64 v[2:3], s[54:55], 0, v[208:209]
	s_add_i32 m0, s37, 0xc000
	s_waitcnt lgkmcnt(0)
	ds_read_b128 v[164:167], v224
	ds_read_b128 v[168:171], v224 offset:1024
	ds_read_b128 v[172:175], v224 offset:2048
	ds_read_b128 v[176:179], v224 offset:3072
	ds_read_b128 v[180:183], v224 offset:4096
	ds_read_b128 v[184:187], v224 offset:5120
	ds_read_b128 v[188:191], v224 offset:6144
	ds_read_b128 v[192:195], v224 offset:7168
	global_load_lds_dwordx4 v[2:3], off
	v_lshl_add_u64 v[2:3], s[54:55], 0, v[206:207]
	s_add_i32 m0, s37, 0xe000
	s_nop 0
	global_load_lds_dwordx4 v[2:3], off
	s_waitcnt vmcnt(8)
	s_waitcnt lgkmcnt(0)
	s_barrier
	v_mfma_f32_16x16x32_bf16 v[120:123], v[148:151], v[164:167], v[120:123]
	v_mfma_f32_16x16x32_bf16 v[116:119], v[156:159], v[164:167], v[116:119]
	v_mfma_f32_16x16x32_bf16 v[104:107], v[148:151], v[172:175], v[104:107]
	v_mfma_f32_16x16x32_bf16 v[100:103], v[156:159], v[172:175], v[100:103]
	v_mfma_f32_16x16x32_bf16 v[88:91], v[148:151], v[180:183], v[88:91]
	v_mfma_f32_16x16x32_bf16 v[84:87], v[156:159], v[180:183], v[84:87]
	v_mfma_f32_16x16x32_bf16 v[76:79], v[148:151], v[188:191], v[76:79]
	v_mfma_f32_16x16x32_bf16 v[72:75], v[156:159], v[188:191], v[72:75]
	v_mfma_f32_16x16x32_bf16 v[120:123], v[152:155], v[168:171], v[120:123]
	v_mfma_f32_16x16x32_bf16 v[116:119], v[160:163], v[168:171], v[116:119]
	v_mfma_f32_16x16x32_bf16 v[104:107], v[152:155], v[176:179], v[104:107]
	v_mfma_f32_16x16x32_bf16 v[100:103], v[160:163], v[176:179], v[100:103]
	v_mfma_f32_16x16x32_bf16 v[88:91], v[152:155], v[184:187], v[88:91]
	v_mfma_f32_16x16x32_bf16 v[84:87], v[160:163], v[184:187], v[84:87]
	v_mfma_f32_16x16x32_bf16 v[76:79], v[152:155], v[192:195], v[76:79]
	v_mfma_f32_16x16x32_bf16 v[72:75], v[160:163], v[192:195], v[72:75]
	v_mfma_f32_16x16x32_bf16 v[128:131], v[132:135], v[164:167], v[128:131]
	v_mfma_f32_16x16x32_bf16 v[124:127], v[140:143], v[164:167], v[124:127]
	v_mfma_f32_16x16x32_bf16 v[112:115], v[132:135], v[172:175], v[112:115]
	v_mfma_f32_16x16x32_bf16 v[108:111], v[140:143], v[172:175], v[108:111]
	v_mfma_f32_16x16x32_bf16 v[96:99], v[132:135], v[180:183], v[96:99]
	v_mfma_f32_16x16x32_bf16 v[92:95], v[140:143], v[180:183], v[92:95]
	v_mfma_f32_16x16x32_bf16 v[80:83], v[132:135], v[188:191], v[80:83]
	v_mfma_f32_16x16x32_bf16 v[68:71], v[140:143], v[188:191], v[68:71]
	v_mfma_f32_16x16x32_bf16 v[128:131], v[136:139], v[168:171], v[128:131]
	v_mfma_f32_16x16x32_bf16 v[124:127], v[144:147], v[168:171], v[124:127]
	v_mfma_f32_16x16x32_bf16 v[112:115], v[136:139], v[176:179], v[112:115]
	v_mfma_f32_16x16x32_bf16 v[108:111], v[144:147], v[176:179], v[108:111]
	v_mfma_f32_16x16x32_bf16 v[96:99], v[136:139], v[184:187], v[96:99]
	v_mfma_f32_16x16x32_bf16 v[92:95], v[144:147], v[184:187], v[92:95]
	v_mfma_f32_16x16x32_bf16 v[80:83], v[136:139], v[192:195], v[80:83]
	v_mfma_f32_16x16x32_bf16 v[68:71], v[144:147], v[192:195], v[68:71]
	s_barrier
	s_add_i32 s10, s67, s48
	v_lshl_add_u64 v[2:3], s[56:57], 0, v[198:199]
	s_mov_b32 m0, s10
	ds_read_b128 v[188:191], v224 offset:16384
	ds_read_b128 v[192:195], v224 offset:17408
	ds_read_b128 v[180:183], v224 offset:18432
	ds_read_b128 v[184:187], v224 offset:19456
	ds_read_b128 v[172:175], v224 offset:20480
	ds_read_b128 v[176:179], v224 offset:21504
	ds_read_b128 v[164:167], v224 offset:22528
	ds_read_b128 v[168:171], v224 offset:23552
	global_load_lds_dwordx4 v[2:3], off
	s_add_i32 m0, s10, 0x2000
	s_add_u32 s10, s56, 0x80000
	v_lshl_add_u64 v[212:213], s[56:57], 0, v[202:203]
	s_addc_u32 s11, s57, 0
	s_add_i32 s78, s70, s48
	global_load_lds_dwordx4 v[212:213], off
	v_lshl_add_u64 v[214:215], s[10:11], 0, v[198:199]
	s_mov_b32 m0, s78
	v_lshl_add_u64 v[216:217], s[58:59], 0, v[200:201]
	global_load_lds_dwordx4 v[214:215], off
	v_lshl_add_u64 v[214:215], s[10:11], 0, v[202:203]
	s_add_i32 m0, s78, 0x2000
	v_cmp_ne_u32_e64 s[10:11], 1, v227
	global_load_lds_dwordx4 v[214:215], off
	v_lshl_add_u64 v[214:215], s[58:59], 0, v[196:197]
	s_mov_b32 m0, s37
	s_andn2_b64 vcc, exec, s[52:53]
	global_load_lds_dwordx4 v[214:215], off
	s_mov_b32 m0, s60
	s_nop 0
	global_load_lds_dwordx4 v[216:217], off
	s_waitcnt vmcnt(8)
	s_waitcnt lgkmcnt(0)
	s_cbranch_vccnz .Lsegskip_0
	s_barrier
	v_mfma_f32_16x16x32_bf16 v[56:59], v[148:151], v[188:191], v[56:59]
	v_mfma_f32_16x16x32_bf16 v[52:55], v[156:159], v[188:191], v[52:55]
	v_mfma_f32_16x16x32_bf16 v[40:43], v[148:151], v[180:183], v[40:43]
	v_mfma_f32_16x16x32_bf16 v[36:39], v[156:159], v[180:183], v[36:39]
	v_mfma_f32_16x16x32_bf16 v[24:27], v[148:151], v[172:175], v[24:27]
	v_mfma_f32_16x16x32_bf16 v[20:23], v[156:159], v[172:175], v[20:23]
	v_mfma_f32_16x16x32_bf16 v[8:11], v[148:151], v[164:167], v[8:11]
	v_mfma_f32_16x16x32_bf16 v[4:7], v[156:159], v[164:167], v[4:7]
	v_mfma_f32_16x16x32_bf16 v[56:59], v[152:155], v[192:195], v[56:59]
	v_mfma_f32_16x16x32_bf16 v[52:55], v[160:163], v[192:195], v[52:55]
	v_mfma_f32_16x16x32_bf16 v[40:43], v[152:155], v[184:187], v[40:43]
	v_mfma_f32_16x16x32_bf16 v[36:39], v[160:163], v[184:187], v[36:39]
	v_mfma_f32_16x16x32_bf16 v[24:27], v[152:155], v[176:179], v[24:27]
	v_mfma_f32_16x16x32_bf16 v[20:23], v[160:163], v[176:179], v[20:23]
	v_mfma_f32_16x16x32_bf16 v[8:11], v[152:155], v[168:171], v[8:11]
	v_mfma_f32_16x16x32_bf16 v[4:7], v[160:163], v[168:171], v[4:7]
	v_mfma_f32_16x16x32_bf16 v[64:67], v[132:135], v[188:191], v[64:67]
	v_mfma_f32_16x16x32_bf16 v[60:63], v[140:143], v[188:191], v[60:63]
	v_mfma_f32_16x16x32_bf16 v[48:51], v[132:135], v[180:183], v[48:51]
	v_mfma_f32_16x16x32_bf16 v[44:47], v[140:143], v[180:183], v[44:47]
	v_mfma_f32_16x16x32_bf16 v[32:35], v[132:135], v[172:175], v[32:35]
	v_mfma_f32_16x16x32_bf16 v[28:31], v[140:143], v[172:175], v[28:31]
	v_mfma_f32_16x16x32_bf16 v[16:19], v[132:135], v[164:167], v[16:19]
	v_mfma_f32_16x16x32_bf16 v[12:15], v[140:143], v[164:167], v[12:15]
	v_mfma_f32_16x16x32_bf16 v[64:67], v[136:139], v[192:195], v[64:67]
	v_mfma_f32_16x16x32_bf16 v[60:63], v[144:147], v[192:195], v[60:63]
	v_mfma_f32_16x16x32_bf16 v[48:51], v[136:139], v[184:187], v[48:51]
	v_mfma_f32_16x16x32_bf16 v[44:47], v[144:147], v[184:187], v[44:47]
	v_mfma_f32_16x16x32_bf16 v[32:35], v[136:139], v[176:179], v[32:35]
	v_mfma_f32_16x16x32_bf16 v[28:31], v[144:147], v[176:179], v[28:31]
	v_mfma_f32_16x16x32_bf16 v[16:19], v[136:139], v[168:171], v[16:19]
	v_mfma_f32_16x16x32_bf16 v[12:15], v[144:147], v[168:171], v[12:15]
.LBB0_437:
	s_barrier
	s_add_i32 s78, 0, 0x18000
	v_add_u32_e32 v1, s78, v220
	s_add_i32 s79, 0, 0x1c000
	ds_read_b128 v[148:151], v1
	ds_read_b128 v[152:155], v1 offset:1024
	ds_read_b128 v[156:159], v1 offset:2048
	ds_read_b128 v[160:163], v1 offset:3072
	v_add_u32_e32 v1, s79, v220
	ds_read_b128 v[132:135], v1
	ds_read_b128 v[136:139], v1 offset:1024
	ds_read_b128 v[140:143], v1 offset:2048
	ds_read_b128 v[144:147], v1 offset:3072
	s_add_u32 s58, s58, 0x80000
	s_addc_u32 s59, s59, 0
	s_mov_b32 m0, s61
	v_lshl_add_u64 v[228:229], s[58:59], 0, v[196:197]
	s_waitcnt lgkmcnt(0)
	ds_read_b128 v[164:167], v224 offset:32768
	ds_read_b128 v[168:171], v224 offset:33792
	ds_read_b128 v[172:175], v224 offset:34816
	ds_read_b128 v[176:179], v224 offset:35840
	ds_read_b128 v[180:183], v224 offset:36864
	ds_read_b128 v[184:187], v224 offset:37888
	ds_read_b128 v[188:191], v224 offset:38912
	ds_read_b128 v[192:195], v224 offset:39936
	global_load_lds_dwordx4 v[228:229], off
	v_lshl_add_u64 v[228:229], s[58:59], 0, v[200:201]
	s_mov_b32 m0, s62
	s_nop 0
	global_load_lds_dwordx4 v[228:229], off
	s_waitcnt vmcnt(8)
	s_waitcnt lgkmcnt(0)
	s_barrier
	v_mfma_f32_16x16x32_bf16 v[120:123], v[148:151], v[164:167], v[120:123]
	v_mfma_f32_16x16x32_bf16 v[116:119], v[156:159], v[164:167], v[116:119]
	v_mfma_f32_16x16x32_bf16 v[104:107], v[148:151], v[172:175], v[104:107]
	v_mfma_f32_16x16x32_bf16 v[100:103], v[156:159], v[172:175], v[100:103]
	v_mfma_f32_16x16x32_bf16 v[88:91], v[148:151], v[180:183], v[88:91]
	v_mfma_f32_16x16x32_bf16 v[84:87], v[156:159], v[180:183], v[84:87]
	v_mfma_f32_16x16x32_bf16 v[76:79], v[148:151], v[188:191], v[76:79]
	v_mfma_f32_16x16x32_bf16 v[72:75], v[156:159], v[188:191], v[72:75]
	v_mfma_f32_16x16x32_bf16 v[120:123], v[152:155], v[168:171], v[120:123]
	v_mfma_f32_16x16x32_bf16 v[116:119], v[160:163], v[168:171], v[116:119]
	v_mfma_f32_16x16x32_bf16 v[104:107], v[152:155], v[176:179], v[104:107]
	v_mfma_f32_16x16x32_bf16 v[100:103], v[160:163], v[176:179], v[100:103]
	v_mfma_f32_16x16x32_bf16 v[88:91], v[152:155], v[184:187], v[88:91]
	v_mfma_f32_16x16x32_bf16 v[84:87], v[160:163], v[184:187], v[84:87]
	v_mfma_f32_16x16x32_bf16 v[76:79], v[152:155], v[192:195], v[76:79]
	v_mfma_f32_16x16x32_bf16 v[72:75], v[160:163], v[192:195], v[72:75]
	v_mfma_f32_16x16x32_bf16 v[128:131], v[132:135], v[164:167], v[128:131]
	v_mfma_f32_16x16x32_bf16 v[124:127], v[140:143], v[164:167], v[124:127]
	v_mfma_f32_16x16x32_bf16 v[112:115], v[132:135], v[172:175], v[112:115]
	v_mfma_f32_16x16x32_bf16 v[108:111], v[140:143], v[172:175], v[108:111]
	v_mfma_f32_16x16x32_bf16 v[96:99], v[132:135], v[180:183], v[96:99]
	v_mfma_f32_16x16x32_bf16 v[92:95], v[140:143], v[180:183], v[92:95]
	v_mfma_f32_16x16x32_bf16 v[80:83], v[132:135], v[188:191], v[80:83]
	v_mfma_f32_16x16x32_bf16 v[68:71], v[140:143], v[188:191], v[68:71]
	v_mfma_f32_16x16x32_bf16 v[128:131], v[136:139], v[168:171], v[128:131]
	v_mfma_f32_16x16x32_bf16 v[124:127], v[144:147], v[168:171], v[124:127]
	v_mfma_f32_16x16x32_bf16 v[112:115], v[136:139], v[176:179], v[112:115]
	v_mfma_f32_16x16x32_bf16 v[108:111], v[144:147], v[176:179], v[108:111]
	v_mfma_f32_16x16x32_bf16 v[96:99], v[136:139], v[184:187], v[96:99]
	v_mfma_f32_16x16x32_bf16 v[92:95], v[144:147], v[184:187], v[92:95]
	v_mfma_f32_16x16x32_bf16 v[80:83], v[136:139], v[192:195], v[80:83]
	v_mfma_f32_16x16x32_bf16 v[68:71], v[144:147], v[192:195], v[68:71]
	s_barrier
	s_add_i32 s58, s78, s48
	v_lshl_add_u64 v[2:3], v[2:3], 0, s[16:17]
	s_mov_b32 m0, s58
	ds_read_b128 v[188:191], v224 offset:49152
	ds_read_b128 v[192:195], v224 offset:50176
	ds_read_b128 v[180:183], v224 offset:51200
	ds_read_b128 v[184:187], v224 offset:52224
	ds_read_b128 v[172:175], v224 offset:53248
	ds_read_b128 v[176:179], v224 offset:54272
	ds_read_b128 v[164:167], v224 offset:55296
	ds_read_b128 v[168:171], v224 offset:56320
	global_load_lds_dwordx4 v[2:3], off
	s_add_i32 m0, s58, 0x2000
	s_add_u32 s56, s56, 0x80080
	v_lshl_add_u64 v[2:3], v[212:213], 0, s[16:17]
	s_addc_u32 s57, s57, 0
	s_add_i32 s58, s79, s48
	global_load_lds_dwordx4 v[2:3], off
	v_lshl_add_u64 v[2:3], s[56:57], 0, v[198:199]
	s_mov_b32 m0, s58
	s_and_b64 vcc, exec, s[10:11]
	global_load_lds_dwordx4 v[2:3], off
	v_lshl_add_u64 v[2:3], s[56:57], 0, v[202:203]
	s_add_i32 m0, s58, 0x2000
	s_nop 0
	global_load_lds_dwordx4 v[2:3], off
	v_lshl_add_u64 v[2:3], v[214:215], 0, s[16:17]
	s_mov_b32 m0, s63
	s_nop 0
	global_load_lds_dwordx4 v[2:3], off
	v_lshl_add_u64 v[2:3], v[216:217], 0, s[16:17]
	s_mov_b32 m0, s64
	s_nop 0
	global_load_lds_dwordx4 v[2:3], off
	s_waitcnt vmcnt(8)
	s_waitcnt lgkmcnt(0)
	s_cbranch_vccnz .Lsegskip_1
	s_barrier
	v_mfma_f32_16x16x32_bf16 v[56:59], v[148:151], v[188:191], v[56:59]
	v_mfma_f32_16x16x32_bf16 v[52:55], v[156:159], v[188:191], v[52:55]
	v_mfma_f32_16x16x32_bf16 v[40:43], v[148:151], v[180:183], v[40:43]
	v_mfma_f32_16x16x32_bf16 v[36:39], v[156:159], v[180:183], v[36:39]
	v_mfma_f32_16x16x32_bf16 v[24:27], v[148:151], v[172:175], v[24:27]
	v_mfma_f32_16x16x32_bf16 v[20:23], v[156:159], v[172:175], v[20:23]
	v_mfma_f32_16x16x32_bf16 v[8:11], v[148:151], v[164:167], v[8:11]
	v_mfma_f32_16x16x32_bf16 v[2:5], v[156:159], v[164:167], v[4:7]
	v_mfma_f32_16x16x32_bf16 v[56:59], v[152:155], v[192:195], v[56:59]
	v_mfma_f32_16x16x32_bf16 v[52:55], v[160:163], v[192:195], v[52:55]
	v_mfma_f32_16x16x32_bf16 v[40:43], v[152:155], v[184:187], v[40:43]
	v_mfma_f32_16x16x32_bf16 v[36:39], v[160:163], v[184:187], v[36:39]
	v_mfma_f32_16x16x32_bf16 v[24:27], v[152:155], v[176:179], v[24:27]
	v_mfma_f32_16x16x32_bf16 v[20:23], v[160:163], v[176:179], v[20:23]
	v_mfma_f32_16x16x32_bf16 v[8:11], v[152:155], v[168:171], v[8:11]
	v_mfma_f32_16x16x32_bf16 v[4:7], v[160:163], v[168:171], v[2:5]
	v_mfma_f32_16x16x32_bf16 v[64:67], v[132:135], v[188:191], v[64:67]
	v_mfma_f32_16x16x32_bf16 v[60:63], v[140:143], v[188:191], v[60:63]
	v_mfma_f32_16x16x32_bf16 v[48:51], v[132:135], v[180:183], v[48:51]
	v_mfma_f32_16x16x32_bf16 v[44:47], v[140:143], v[180:183], v[44:47]
	v_mfma_f32_16x16x32_bf16 v[32:35], v[132:135], v[172:175], v[32:35]
	v_mfma_f32_16x16x32_bf16 v[28:31], v[140:143], v[172:175], v[28:31]
	v_mfma_f32_16x16x32_bf16 v[16:19], v[132:135], v[164:167], v[16:19]
	v_mfma_f32_16x16x32_bf16 v[12:15], v[140:143], v[164:167], v[12:15]
	v_mfma_f32_16x16x32_bf16 v[64:67], v[136:139], v[192:195], v[64:67]
	v_mfma_f32_16x16x32_bf16 v[60:63], v[144:147], v[192:195], v[60:63]
	v_mfma_f32_16x16x32_bf16 v[48:51], v[136:139], v[184:187], v[48:51]
	v_mfma_f32_16x16x32_bf16 v[44:47], v[144:147], v[184:187], v[44:47]
	v_mfma_f32_16x16x32_bf16 v[32:35], v[136:139], v[176:179], v[32:35]
	v_mfma_f32_16x16x32_bf16 v[28:31], v[144:147], v[176:179], v[28:31]
	v_mfma_f32_16x16x32_bf16 v[16:19], v[136:139], v[168:171], v[16:19]
	v_mfma_f32_16x16x32_bf16 v[12:15], v[144:147], v[168:171], v[12:15]
	s_barrier
	s_branch .Lsegback_1

.LBB0_523:
	ds_read_b128 v[144:147], v151
	ds_read_b128 v[156:159], v151 offset:1024
	ds_read_b128 v[160:163], v151 offset:2048
	ds_read_b128 v[164:167], v151 offset:3072
	ds_read_b128 v[168:171], v152
	ds_read_b128 v[172:175], v152 offset:1024
	ds_read_b128 v[176:179], v152 offset:2048
	ds_read_b128 v[180:183], v152 offset:3072
	s_add_u32 s36, s34, 0x100
	s_addc_u32 s37, s35, 0
	s_cmpk_eq_i32 s66, 0x54
	s_cselect_b32 s55, s13, s37
	s_cselect_b32 s54, s12, s36
	s_cselect_b32 s53, s31, s47
	s_cselect_b32 s52, s30, s46
	v_lshl_add_u64 v[216:217], s[34:35], 0, v[138:139]
	s_add_i32 m0, s49, 0xc000
	ds_read_b128 v[184:187], v153
	ds_read_b128 v[188:191], v153 offset:1024
	ds_read_b128 v[192:195], v153 offset:2048
	ds_read_b128 v[196:199], v153 offset:3072
	ds_read_b128 v[200:203], v153 offset:4096
	ds_read_b128 v[204:207], v153 offset:5120
	ds_read_b128 v[208:211], v153 offset:6144
	ds_read_b128 v[212:215], v153 offset:7168
	global_load_lds_dwordx4 v[216:217], off
	v_lshl_add_u64 v[216:217], s[34:35], 0, v[136:137]
	s_add_i32 m0, s49, 0xe000
	s_nop 0
	global_load_lds_dwordx4 v[216:217], off
	s_waitcnt vmcnt(8)
	s_waitcnt lgkmcnt(0)
	s_barrier
	v_mfma_f32_16x16x32_bf16 v[124:127], v[144:147], v[184:187], v[124:127]
	v_mfma_f32_16x16x32_bf16 v[120:123], v[160:163], v[184:187], v[120:123]
	v_mfma_f32_16x16x32_bf16 v[108:111], v[144:147], v[192:195], v[108:111]
	v_mfma_f32_16x16x32_bf16 v[104:107], v[160:163], v[192:195], v[104:107]
	v_mfma_f32_16x16x32_bf16 v[92:95], v[144:147], v[200:203], v[92:95]
	v_mfma_f32_16x16x32_bf16 v[88:91], v[160:163], v[200:203], v[88:91]
	v_mfma_f32_16x16x32_bf16 v[76:79], v[144:147], v[208:211], v[76:79]
	v_mfma_f32_16x16x32_bf16 v[72:75], v[160:163], v[208:211], v[72:75]
	v_mfma_f32_16x16x32_bf16 v[124:127], v[156:159], v[188:191], v[124:127]
	v_mfma_f32_16x16x32_bf16 v[120:123], v[164:167], v[188:191], v[120:123]
	v_mfma_f32_16x16x32_bf16 v[108:111], v[156:159], v[196:199], v[108:111]
	v_mfma_f32_16x16x32_bf16 v[104:107], v[164:167], v[196:199], v[104:107]
	v_mfma_f32_16x16x32_bf16 v[92:95], v[156:159], v[204:207], v[92:95]
	v_mfma_f32_16x16x32_bf16 v[88:91], v[164:167], v[204:207], v[88:91]
	v_mfma_f32_16x16x32_bf16 v[76:79], v[156:159], v[212:215], v[76:79]
	v_mfma_f32_16x16x32_bf16 v[72:75], v[164:167], v[212:215], v[72:75]
	v_mfma_f32_16x16x32_bf16 v[116:119], v[168:171], v[184:187], v[116:119]
	v_mfma_f32_16x16x32_bf16 v[112:115], v[176:179], v[184:187], v[112:115]
	v_mfma_f32_16x16x32_bf16 v[100:103], v[168:171], v[192:195], v[100:103]
	v_mfma_f32_16x16x32_bf16 v[96:99], v[176:179], v[192:195], v[96:99]
	v_mfma_f32_16x16x32_bf16 v[84:87], v[168:171], v[200:203], v[84:87]
	v_mfma_f32_16x16x32_bf16 v[80:83], v[176:179], v[200:203], v[80:83]
	v_mfma_f32_16x16x32_bf16 v[68:71], v[168:171], v[208:211], v[68:71]
	v_mfma_f32_16x16x32_bf16 v[64:67], v[176:179], v[208:211], v[64:67]
	v_mfma_f32_16x16x32_bf16 v[116:119], v[172:175], v[188:191], v[116:119]
	v_mfma_f32_16x16x32_bf16 v[112:115], v[180:183], v[188:191], v[112:115]
	v_mfma_f32_16x16x32_bf16 v[100:103], v[172:175], v[196:199], v[100:103]
	v_mfma_f32_16x16x32_bf16 v[96:99], v[180:183], v[196:199], v[96:99]
	v_mfma_f32_16x16x32_bf16 v[84:87], v[172:175], v[204:207], v[84:87]
	v_mfma_f32_16x16x32_bf16 v[80:83], v[180:183], v[204:207], v[80:83]
	v_mfma_f32_16x16x32_bf16 v[68:71], v[172:175], v[212:215], v[68:71]
	v_mfma_f32_16x16x32_bf16 v[64:67], v[180:183], v[212:215], v[64:67]
	s_barrier
	s_add_i32 s34, s62, s48
	v_lshl_add_u64 v[216:217], s[52:53], 0, v[130:131]
	s_mov_b32 m0, s34
	ds_read_b128 v[184:187], v153 offset:16384
	ds_read_b128 v[188:191], v153 offset:17408
	ds_read_b128 v[192:195], v153 offset:18432
	ds_read_b128 v[196:199], v153 offset:19456
	ds_read_b128 v[200:203], v153 offset:20480
	ds_read_b128 v[204:207], v153 offset:21504
	ds_read_b128 v[208:211], v153 offset:22528
	ds_read_b128 v[212:215], v153 offset:23552
	global_load_lds_dwordx4 v[216:217], off
	s_add_i32 m0, s34, 0x2000
	s_add_u32 s34, s52, 0x160000
	v_lshl_add_u64 v[218:219], s[52:53], 0, v[134:135]
	s_addc_u32 s35, s53, 0
	s_add_i32 s67, s63, s48
	global_load_lds_dwordx4 v[218:219], off
	v_lshl_add_u64 v[220:221], s[34:35], 0, v[130:131]
	s_mov_b32 m0, s67
	v_lshl_add_u64 v[222:223], s[54:55], 0, v[132:133]
	global_load_lds_dwordx4 v[220:221], off
	v_lshl_add_u64 v[220:221], s[34:35], 0, v[134:135]
	s_add_i32 m0, s67, 0x2000
	s_nop 0
	global_load_lds_dwordx4 v[220:221], off
	v_lshl_add_u64 v[220:221], s[54:55], 0, v[128:129]
	s_mov_b32 m0, s49
	s_nop 0
	global_load_lds_dwordx4 v[220:221], off
	s_mov_b32 m0, s56
	s_nop 0
	global_load_lds_dwordx4 v[222:223], off
	s_waitcnt vmcnt(8)
	s_waitcnt lgkmcnt(0)
	s_barrier
	v_mfma_f32_16x16x32_bf16 v[60:63], v[144:147], v[184:187], v[60:63]
	v_mfma_f32_16x16x32_bf16 v[56:59], v[160:163], v[184:187], v[56:59]
	v_mfma_f32_16x16x32_bf16 v[44:47], v[144:147], v[192:195], v[44:47]
	v_mfma_f32_16x16x32_bf16 v[40:43], v[160:163], v[192:195], v[40:43]
	v_mfma_f32_16x16x32_bf16 v[28:31], v[144:147], v[200:203], v[28:31]
	v_mfma_f32_16x16x32_bf16 v[24:27], v[160:163], v[200:203], v[24:27]
	v_mfma_f32_16x16x32_bf16 v[12:15], v[144:147], v[208:211], v[12:15]
	v_mfma_f32_16x16x32_bf16 v[8:11], v[160:163], v[208:211], v[8:11]
	v_mfma_f32_16x16x32_bf16 v[60:63], v[156:159], v[188:191], v[60:63]
	v_mfma_f32_16x16x32_bf16 v[56:59], v[164:167], v[188:191], v[56:59]
	v_mfma_f32_16x16x32_bf16 v[44:47], v[156:159], v[196:199], v[44:47]
	v_mfma_f32_16x16x32_bf16 v[40:43], v[164:167], v[196:199], v[40:43]
	v_mfma_f32_16x16x32_bf16 v[28:31], v[156:159], v[204:207], v[28:31]
	v_mfma_f32_16x16x32_bf16 v[24:27], v[164:167], v[204:207], v[24:27]
	v_mfma_f32_16x16x32_bf16 v[12:15], v[156:159], v[212:215], v[12:15]
	v_mfma_f32_16x16x32_bf16 v[8:11], v[164:167], v[212:215], v[8:11]
	v_mfma_f32_16x16x32_bf16 v[52:55], v[168:171], v[184:187], v[52:55]
	v_mfma_f32_16x16x32_bf16 v[48:51], v[176:179], v[184:187], v[48:51]
	v_mfma_f32_16x16x32_bf16 v[36:39], v[168:171], v[192:195], v[36:39]
	v_mfma_f32_16x16x32_bf16 v[32:35], v[176:179], v[192:195], v[32:35]
	v_mfma_f32_16x16x32_bf16 v[20:23], v[168:171], v[200:203], v[20:23]
	v_mfma_f32_16x16x32_bf16 v[16:19], v[176:179], v[200:203], v[16:19]
	v_mfma_f32_16x16x32_bf16 v[4:7], v[168:171], v[208:211], v[4:7]
	v_mfma_f32_16x16x32_bf16 v[0:3], v[176:179], v[208:211], v[0:3]
	v_mfma_f32_16x16x32_bf16 v[52:55], v[172:175], v[188:191], v[52:55]
	v_mfma_f32_16x16x32_bf16 v[48:51], v[180:183], v[188:191], v[48:51]
	v_mfma_f32_16x16x32_bf16 v[36:39], v[172:175], v[196:199], v[36:39]
	v_mfma_f32_16x16x32_bf16 v[32:35], v[180:183], v[196:199], v[32:35]
	v_mfma_f32_16x16x32_bf16 v[20:23], v[172:175], v[204:207], v[20:23]
	v_mfma_f32_16x16x32_bf16 v[16:19], v[180:183], v[204:207], v[16:19]
	v_mfma_f32_16x16x32_bf16 v[4:7], v[172:175], v[212:215], v[4:7]
	v_mfma_f32_16x16x32_bf16 v[0:3], v[180:183], v[212:215], v[0:3]
	s_barrier
	s_add_i32 s67, 0, 0x18000
	v_add_u32_e32 v155, s67, v149
	s_add_i32 s70, 0, 0x1c000
	ds_read_b128 v[144:147], v155
	ds_read_b128 v[156:159], v155 offset:1024
	ds_read_b128 v[160:163], v155 offset:2048
	ds_read_b128 v[164:167], v155 offset:3072
	v_add_u32_e32 v155, s70, v149
	ds_read_b128 v[168:171], v155
	ds_read_b128 v[172:175], v155 offset:1024
	ds_read_b128 v[176:179], v155 offset:2048
	ds_read_b128 v[180:183], v155 offset:3072
	s_add_u32 s34, s54, 0x160000
	s_addc_u32 s35, s55, 0
	s_mov_b32 m0, s57
	v_lshl_add_u64 v[224:225], s[34:35], 0, v[128:129]
	ds_read_b128 v[184:187], v153 offset:32768
	ds_read_b128 v[188:191], v153 offset:33792
	ds_read_b128 v[192:195], v153 offset:34816
	ds_read_b128 v[196:199], v153 offset:35840
	ds_read_b128 v[200:203], v153 offset:36864
	ds_read_b128 v[204:207], v153 offset:37888
	ds_read_b128 v[208:211], v153 offset:38912
	ds_read_b128 v[212:215], v153 offset:39936
	global_load_lds_dwordx4 v[224:225], off
	v_lshl_add_u64 v[224:225], s[34:35], 0, v[132:133]
	s_mov_b32 m0, s58
	s_nop 0
	global_load_lds_dwordx4 v[224:225], off
	s_waitcnt vmcnt(8)
	s_waitcnt lgkmcnt(0)
	s_barrier
	v_mfma_f32_16x16x32_bf16 v[124:127], v[144:147], v[184:187], v[124:127]
	v_mfma_f32_16x16x32_bf16 v[120:123], v[160:163], v[184:187], v[120:123]
	v_mfma_f32_16x16x32_bf16 v[108:111], v[144:147], v[192:195], v[108:111]
	v_mfma_f32_16x16x32_bf16 v[104:107], v[160:163], v[192:195], v[104:107]
	v_mfma_f32_16x16x32_bf16 v[92:95], v[144:147], v[200:203], v[92:95]
	v_mfma_f32_16x16x32_bf16 v[88:91], v[160:163], v[200:203], v[88:91]
	v_mfma_f32_16x16x32_bf16 v[76:79], v[144:147], v[208:211], v[76:79]
	v_mfma_f32_16x16x32_bf16 v[72:75], v[160:163], v[208:211], v[72:75]
	v_mfma_f32_16x16x32_bf16 v[124:127], v[156:159], v[188:191], v[124:127]
	v_mfma_f32_16x16x32_bf16 v[120:123], v[164:167], v[188:191], v[120:123]
	v_mfma_f32_16x16x32_bf16 v[108:111], v[156:159], v[196:199], v[108:111]
	v_mfma_f32_16x16x32_bf16 v[104:107], v[164:167], v[196:199], v[104:107]
	v_mfma_f32_16x16x32_bf16 v[92:95], v[156:159], v[204:207], v[92:95]
	v_mfma_f32_16x16x32_bf16 v[88:91], v[164:167], v[204:207], v[88:91]
	v_mfma_f32_16x16x32_bf16 v[76:79], v[156:159], v[212:215], v[76:79]
	v_mfma_f32_16x16x32_bf16 v[72:75], v[164:167], v[212:215], v[72:75]
	v_mfma_f32_16x16x32_bf16 v[116:119], v[168:171], v[184:187], v[116:119]
	v_mfma_f32_16x16x32_bf16 v[112:115], v[176:179], v[184:187], v[112:115]
	v_mfma_f32_16x16x32_bf16 v[100:103], v[168:171], v[192:195], v[100:103]
	v_mfma_f32_16x16x32_bf16 v[96:99], v[176:179], v[192:195], v[96:99]
	v_mfma_f32_16x16x32_bf16 v[84:87], v[168:171], v[200:203], v[84:87]
	v_mfma_f32_16x16x32_bf16 v[80:83], v[176:179], v[200:203], v[80:83]
	v_mfma_f32_16x16x32_bf16 v[68:71], v[168:171], v[208:211], v[68:71]
	v_mfma_f32_16x16x32_bf16 v[64:67], v[176:179], v[208:211], v[64:67]
	v_mfma_f32_16x16x32_bf16 v[116:119], v[172:175], v[188:191], v[116:119]
	v_mfma_f32_16x16x32_bf16 v[112:115], v[180:183], v[188:191], v[112:115]
	v_mfma_f32_16x16x32_bf16 v[100:103], v[172:175], v[196:199], v[100:103]
	v_mfma_f32_16x16x32_bf16 v[96:99], v[180:183], v[196:199], v[96:99]
	v_mfma_f32_16x16x32_bf16 v[84:87], v[172:175], v[204:207], v[84:87]
	v_mfma_f32_16x16x32_bf16 v[80:83], v[180:183], v[204:207], v[80:83]
	v_mfma_f32_16x16x32_bf16 v[68:71], v[172:175], v[212:215], v[68:71]
	v_mfma_f32_16x16x32_bf16 v[64:67], v[180:183], v[212:215], v[64:67]
	s_barrier
	s_add_i32 s34, s67, s48
	v_lshl_add_u64 v[216:217], v[216:217], 0, s[24:25]
	s_mov_b32 m0, s34
	ds_read_b128 v[184:187], v153 offset:49152
	ds_read_b128 v[188:191], v153 offset:50176
	ds_read_b128 v[192:195], v153 offset:51200
	ds_read_b128 v[196:199], v153 offset:52224
	ds_read_b128 v[200:203], v153 offset:53248
	ds_read_b128 v[204:207], v153 offset:54272
	ds_read_b128 v[208:211], v153 offset:55296
	ds_read_b128 v[212:215], v153 offset:56320
	global_load_lds_dwordx4 v[216:217], off
	s_add_i32 m0, s34, 0x2000
	s_add_u32 s34, s52, 0x160080
	v_lshl_add_u64 v[216:217], v[218:219], 0, s[24:25]
	s_addc_u32 s35, s53, 0
	s_add_i32 s52, s70, s48
	global_load_lds_dwordx4 v[216:217], off
	v_lshl_add_u64 v[216:217], s[34:35], 0, v[130:131]
	s_mov_b32 m0, s52
	s_nop 0
	global_load_lds_dwordx4 v[216:217], off
	v_lshl_add_u64 v[216:217], s[34:35], 0, v[134:135]
	s_add_i32 m0, s52, 0x2000
	s_nop 0
	global_load_lds_dwordx4 v[216:217], off
	v_lshl_add_u64 v[216:217], v[220:221], 0, s[24:25]
	s_mov_b32 m0, s60
	s_nop 0
	global_load_lds_dwordx4 v[216:217], off
	v_lshl_add_u64 v[216:217], v[222:223], 0, s[24:25]
	s_mov_b32 m0, s61
	s_nop 0
	global_load_lds_dwordx4 v[216:217], off
	s_waitcnt vmcnt(8)
	s_waitcnt lgkmcnt(0)
	s_barrier
	v_mfma_f32_16x16x32_bf16 v[60:63], v[144:147], v[184:187], v[60:63]
	v_mfma_f32_16x16x32_bf16 v[56:59], v[160:163], v[184:187], v[56:59]
	v_mfma_f32_16x16x32_bf16 v[44:47], v[144:147], v[192:195], v[44:47]
	v_mfma_f32_16x16x32_bf16 v[40:43], v[160:163], v[192:195], v[40:43]
	v_mfma_f32_16x16x32_bf16 v[28:31], v[144:147], v[200:203], v[28:31]
	v_mfma_f32_16x16x32_bf16 v[24:27], v[160:163], v[200:203], v[24:27]
	v_mfma_f32_16x16x32_bf16 v[12:15], v[144:147], v[208:211], v[12:15]
	v_mfma_f32_16x16x32_bf16 v[8:11], v[160:163], v[208:211], v[8:11]
	v_mfma_f32_16x16x32_bf16 v[60:63], v[156:159], v[188:191], v[60:63]
	v_mfma_f32_16x16x32_bf16 v[56:59], v[164:167], v[188:191], v[56:59]
	v_mfma_f32_16x16x32_bf16 v[44:47], v[156:159], v[196:199], v[44:47]
	v_mfma_f32_16x16x32_bf16 v[40:43], v[164:167], v[196:199], v[40:43]
	v_mfma_f32_16x16x32_bf16 v[28:31], v[156:159], v[204:207], v[28:31]
	v_mfma_f32_16x16x32_bf16 v[24:27], v[164:167], v[204:207], v[24:27]
	v_mfma_f32_16x16x32_bf16 v[12:15], v[156:159], v[212:215], v[12:15]
	v_mfma_f32_16x16x32_bf16 v[8:11], v[164:167], v[212:215], v[8:11]
	v_mfma_f32_16x16x32_bf16 v[52:55], v[168:171], v[184:187], v[52:55]
	v_mfma_f32_16x16x32_bf16 v[48:51], v[176:179], v[184:187], v[48:51]
	v_mfma_f32_16x16x32_bf16 v[36:39], v[168:171], v[192:195], v[36:39]
	v_mfma_f32_16x16x32_bf16 v[32:35], v[176:179], v[192:195], v[32:35]
	v_mfma_f32_16x16x32_bf16 v[20:23], v[168:171], v[200:203], v[20:23]
	v_mfma_f32_16x16x32_bf16 v[16:19], v[176:179], v[200:203], v[16:19]
	v_mfma_f32_16x16x32_bf16 v[4:7], v[168:171], v[208:211], v[4:7]
	v_mfma_f32_16x16x32_bf16 v[0:3], v[176:179], v[208:211], v[0:3]
	v_mfma_f32_16x16x32_bf16 v[52:55], v[172:175], v[188:191], v[52:55]
	v_mfma_f32_16x16x32_bf16 v[48:51], v[180:183], v[188:191], v[48:51]
	v_mfma_f32_16x16x32_bf16 v[36:39], v[172:175], v[196:199], v[36:39]
	v_mfma_f32_16x16x32_bf16 v[32:35], v[180:183], v[196:199], v[32:35]
	v_mfma_f32_16x16x32_bf16 v[20:23], v[172:175], v[204:207], v[20:23]
	v_mfma_f32_16x16x32_bf16 v[16:19], v[180:183], v[204:207], v[16:19]
	v_mfma_f32_16x16x32_bf16 v[4:7], v[172:175], v[212:215], v[4:7]
	v_mfma_f32_16x16x32_bf16 v[0:3], v[180:183], v[212:215], v[0:3]
	s_barrier
	s_add_i32 s66, s66, 2
	s_add_u32 s46, s46, 0x100
	s_addc_u32 s47, s47, 0
	s_cmpk_gt_u32 s66, 0x55
	s_mov_b64 s[34:35], s[36:37]
	s_cbranch_scc0 .LBB0_523
	s_and_b64 vcc, exec, s[26:27]
	s_cbranch_vccz .LBB0_526
	s_barrier

.LBB0_617:
	ds_read_b128 v[146:149], v159
	ds_read_b128 v[150:153], v159 offset:1024
	ds_read_b128 v[164:167], v159 offset:2048
	ds_read_b128 v[168:171], v159 offset:3072
	ds_read_b128 v[172:175], v160
	ds_read_b128 v[176:179], v160 offset:1024
	ds_read_b128 v[180:183], v160 offset:2048
	ds_read_b128 v[184:187], v160 offset:3072
	s_add_u32 s58, s56, 0xfff80080
	s_addc_u32 s59, s57, -1
	s_cmp_eq_u32 s55, 28
	s_cselect_b32 s61, s35, s59
	s_cselect_b32 s60, s46, s58
	s_cselect_b32 s59, s31, s51
	s_cselect_b32 s58, s47, s50
	v_lshl_add_u64 v[154:155], s[56:57], 0, v[140:141]
	s_add_i32 m0, s45, 0xc000
	ds_read_b128 v[188:191], v161
	ds_read_b128 v[192:195], v161 offset:1024
	ds_read_b128 v[196:199], v161 offset:2048
	ds_read_b128 v[200:203], v161 offset:3072
	ds_read_b128 v[204:207], v161 offset:4096
	ds_read_b128 v[208:211], v161 offset:5120
	ds_read_b128 v[212:215], v161 offset:6144
	ds_read_b128 v[216:219], v161 offset:7168
	global_load_lds_dwordx4 v[154:155], off
	v_lshl_add_u64 v[154:155], s[56:57], 0, v[138:139]
	s_add_i32 m0, s45, 0xe000
	s_nop 0
	global_load_lds_dwordx4 v[154:155], off
	s_waitcnt vmcnt(8)
	s_waitcnt lgkmcnt(0)
	s_barrier
	v_mfma_f32_16x16x32_bf16 v[124:127], v[146:149], v[188:191], v[124:127]
	v_mfma_f32_16x16x32_bf16 v[120:123], v[164:167], v[188:191], v[120:123]
	v_mfma_f32_16x16x32_bf16 v[108:111], v[146:149], v[196:199], v[108:111]
	v_mfma_f32_16x16x32_bf16 v[104:107], v[164:167], v[196:199], v[104:107]
	v_mfma_f32_16x16x32_bf16 v[92:95], v[146:149], v[204:207], v[92:95]
	v_mfma_f32_16x16x32_bf16 v[88:91], v[164:167], v[204:207], v[88:91]
	v_mfma_f32_16x16x32_bf16 v[76:79], v[146:149], v[212:215], v[76:79]
	v_mfma_f32_16x16x32_bf16 v[72:75], v[164:167], v[212:215], v[72:75]
	v_mfma_f32_16x16x32_bf16 v[124:127], v[150:153], v[192:195], v[124:127]
	v_mfma_f32_16x16x32_bf16 v[120:123], v[168:171], v[192:195], v[120:123]
	v_mfma_f32_16x16x32_bf16 v[108:111], v[150:153], v[200:203], v[108:111]
	v_mfma_f32_16x16x32_bf16 v[104:107], v[168:171], v[200:203], v[104:107]
	v_mfma_f32_16x16x32_bf16 v[92:95], v[150:153], v[208:211], v[92:95]
	v_mfma_f32_16x16x32_bf16 v[88:91], v[168:171], v[208:211], v[88:91]
	v_mfma_f32_16x16x32_bf16 v[76:79], v[150:153], v[216:219], v[76:79]
	v_mfma_f32_16x16x32_bf16 v[72:75], v[168:171], v[216:219], v[72:75]
	v_mfma_f32_16x16x32_bf16 v[116:119], v[172:175], v[188:191], v[116:119]
	v_mfma_f32_16x16x32_bf16 v[112:115], v[180:183], v[188:191], v[112:115]
	v_mfma_f32_16x16x32_bf16 v[100:103], v[172:175], v[196:199], v[100:103]
	v_mfma_f32_16x16x32_bf16 v[96:99], v[180:183], v[196:199], v[96:99]
	v_mfma_f32_16x16x32_bf16 v[84:87], v[172:175], v[204:207], v[84:87]
	v_mfma_f32_16x16x32_bf16 v[80:83], v[180:183], v[204:207], v[80:83]
	v_mfma_f32_16x16x32_bf16 v[68:71], v[172:175], v[212:215], v[68:71]
	v_mfma_f32_16x16x32_bf16 v[64:67], v[180:183], v[212:215], v[64:67]
	v_mfma_f32_16x16x32_bf16 v[116:119], v[176:179], v[192:195], v[116:119]
	v_mfma_f32_16x16x32_bf16 v[112:115], v[184:187], v[192:195], v[112:115]
	v_mfma_f32_16x16x32_bf16 v[100:103], v[176:179], v[200:203], v[100:103]
	v_mfma_f32_16x16x32_bf16 v[96:99], v[184:187], v[200:203], v[96:99]
	v_mfma_f32_16x16x32_bf16 v[84:87], v[176:179], v[208:211], v[84:87]
	v_mfma_f32_16x16x32_bf16 v[80:83], v[184:187], v[208:211], v[80:83]
	v_mfma_f32_16x16x32_bf16 v[68:71], v[176:179], v[216:219], v[68:71]
	v_mfma_f32_16x16x32_bf16 v[64:67], v[184:187], v[216:219], v[64:67]
	s_barrier
	s_add_i32 s72, s66, s44
	v_lshl_add_u64 v[154:155], s[58:59], 0, v[130:131]
	s_mov_b32 m0, s72
	ds_read_b128 v[188:191], v161 offset:16384
	ds_read_b128 v[192:195], v161 offset:17408
	ds_read_b128 v[196:199], v161 offset:18432
	ds_read_b128 v[200:203], v161 offset:19456
	ds_read_b128 v[204:207], v161 offset:20480
	ds_read_b128 v[208:211], v161 offset:21504
	ds_read_b128 v[212:215], v161 offset:22528
	ds_read_b128 v[216:219], v161 offset:23552
	global_load_lds_dwordx4 v[154:155], off
	s_add_i32 m0, s72, 0x2000
	s_add_u32 s80, s58, 0x80000
	v_lshl_add_u64 v[220:221], s[58:59], 0, v[134:135]
	s_addc_u32 s81, s59, 0
	s_add_i32 s72, s67, s44
	global_load_lds_dwordx4 v[220:221], off
	v_lshl_add_u64 v[222:223], s[80:81], 0, v[130:131]
	s_mov_b32 m0, s72
	v_lshl_add_u64 v[224:225], s[60:61], 0, v[132:133]
	global_load_lds_dwordx4 v[222:223], off
	v_lshl_add_u64 v[222:223], s[80:81], 0, v[134:135]
	s_add_i32 m0, s72, 0x2000
	s_nop 0
	global_load_lds_dwordx4 v[222:223], off
	v_lshl_add_u64 v[222:223], s[60:61], 0, v[128:129]
	s_mov_b32 m0, s45
	s_nop 0
	global_load_lds_dwordx4 v[222:223], off
	s_mov_b32 m0, s48
	s_nop 0
	global_load_lds_dwordx4 v[224:225], off
	s_waitcnt vmcnt(8)
	s_waitcnt lgkmcnt(0)
	s_barrier
	v_mfma_f32_16x16x32_bf16 v[60:63], v[146:149], v[188:191], v[60:63]
	v_mfma_f32_16x16x32_bf16 v[56:59], v[164:167], v[188:191], v[56:59]
	v_mfma_f32_16x16x32_bf16 v[44:47], v[146:149], v[196:199], v[44:47]
	v_mfma_f32_16x16x32_bf16 v[40:43], v[164:167], v[196:199], v[40:43]
	v_mfma_f32_16x16x32_bf16 v[28:31], v[146:149], v[204:207], v[28:31]
	v_mfma_f32_16x16x32_bf16 v[24:27], v[164:167], v[204:207], v[24:27]
	v_mfma_f32_16x16x32_bf16 v[12:15], v[146:149], v[212:215], v[12:15]
	v_mfma_f32_16x16x32_bf16 v[8:11], v[164:167], v[212:215], v[8:11]
	v_mfma_f32_16x16x32_bf16 v[60:63], v[150:153], v[192:195], v[60:63]
	v_mfma_f32_16x16x32_bf16 v[56:59], v[168:171], v[192:195], v[56:59]
	v_mfma_f32_16x16x32_bf16 v[44:47], v[150:153], v[200:203], v[44:47]
	v_mfma_f32_16x16x32_bf16 v[40:43], v[168:171], v[200:203], v[40:43]
	v_mfma_f32_16x16x32_bf16 v[28:31], v[150:153], v[208:211], v[28:31]
	v_mfma_f32_16x16x32_bf16 v[24:27], v[168:171], v[208:211], v[24:27]
	v_mfma_f32_16x16x32_bf16 v[12:15], v[150:153], v[216:219], v[12:15]
	v_mfma_f32_16x16x32_bf16 v[8:11], v[168:171], v[216:219], v[8:11]
	v_mfma_f32_16x16x32_bf16 v[52:55], v[172:175], v[188:191], v[52:55]
	v_mfma_f32_16x16x32_bf16 v[48:51], v[180:183], v[188:191], v[48:51]
	v_mfma_f32_16x16x32_bf16 v[36:39], v[172:175], v[196:199], v[36:39]
	v_mfma_f32_16x16x32_bf16 v[32:35], v[180:183], v[196:199], v[32:35]
	v_mfma_f32_16x16x32_bf16 v[20:23], v[172:175], v[204:207], v[20:23]
	v_mfma_f32_16x16x32_bf16 v[16:19], v[180:183], v[204:207], v[16:19]
	v_mfma_f32_16x16x32_bf16 v[4:7], v[172:175], v[212:215], v[4:7]
	v_mfma_f32_16x16x32_bf16 v[0:3], v[180:183], v[212:215], v[0:3]
	v_mfma_f32_16x16x32_bf16 v[52:55], v[176:179], v[192:195], v[52:55]
	v_mfma_f32_16x16x32_bf16 v[48:51], v[184:187], v[192:195], v[48:51]
	v_mfma_f32_16x16x32_bf16 v[36:39], v[176:179], v[200:203], v[36:39]
	v_mfma_f32_16x16x32_bf16 v[32:35], v[184:187], v[200:203], v[32:35]
	v_mfma_f32_16x16x32_bf16 v[20:23], v[176:179], v[208:211], v[20:23]
	v_mfma_f32_16x16x32_bf16 v[16:19], v[184:187], v[208:211], v[16:19]
	v_mfma_f32_16x16x32_bf16 v[4:7], v[176:179], v[216:219], v[4:7]
	v_mfma_f32_16x16x32_bf16 v[0:3], v[184:187], v[216:219], v[0:3]
	s_barrier
	s_add_i32 s72, 0, 0x18000
	s_add_i32 s78, 0, 0x1c000
	v_add_u32_e32 v168, s72, v157
	v_add_u32_e32 v184, s78, v157
	ds_read_b128 v[146:149], v168
	ds_read_b128 v[150:153], v168 offset:1024
	ds_read_b128 v[164:167], v168 offset:2048
	ds_read_b128 v[168:171], v168 offset:3072
	ds_read_b128 v[172:175], v184
	ds_read_b128 v[176:179], v184 offset:1024
	ds_read_b128 v[180:183], v184 offset:2048
	ds_read_b128 v[184:187], v184 offset:3072
	s_add_u32 s60, s60, 0x80000
	s_addc_u32 s61, s61, 0
	s_mov_b32 m0, s49
	v_lshl_add_u64 v[226:227], s[60:61], 0, v[128:129]
	ds_read_b128 v[188:191], v161 offset:32768
	ds_read_b128 v[192:195], v161 offset:33792
	ds_read_b128 v[196:199], v161 offset:34816
	ds_read_b128 v[200:203], v161 offset:35840
	ds_read_b128 v[204:207], v161 offset:36864
	ds_read_b128 v[208:211], v161 offset:37888
	ds_read_b128 v[212:215], v161 offset:38912
	ds_read_b128 v[216:219], v161 offset:39936
	global_load_lds_dwordx4 v[226:227], off
	v_lshl_add_u64 v[226:227], s[60:61], 0, v[132:133]
	s_mov_b32 m0, s62
	s_nop 0
	global_load_lds_dwordx4 v[226:227], off
	s_waitcnt vmcnt(8)
	s_waitcnt lgkmcnt(0)
	s_barrier
	v_mfma_f32_16x16x32_bf16 v[124:127], v[146:149], v[188:191], v[124:127]
	v_mfma_f32_16x16x32_bf16 v[120:123], v[164:167], v[188:191], v[120:123]
	v_mfma_f32_16x16x32_bf16 v[108:111], v[146:149], v[196:199], v[108:111]
	v_mfma_f32_16x16x32_bf16 v[104:107], v[164:167], v[196:199], v[104:107]
	v_mfma_f32_16x16x32_bf16 v[92:95], v[146:149], v[204:207], v[92:95]
	v_mfma_f32_16x16x32_bf16 v[88:91], v[164:167], v[204:207], v[88:91]
	v_mfma_f32_16x16x32_bf16 v[76:79], v[146:149], v[212:215], v[76:79]
	v_mfma_f32_16x16x32_bf16 v[72:75], v[164:167], v[212:215], v[72:75]
	v_mfma_f32_16x16x32_bf16 v[124:127], v[150:153], v[192:195], v[124:127]
	v_mfma_f32_16x16x32_bf16 v[120:123], v[168:171], v[192:195], v[120:123]
	v_mfma_f32_16x16x32_bf16 v[108:111], v[150:153], v[200:203], v[108:111]
	v_mfma_f32_16x16x32_bf16 v[104:107], v[168:171], v[200:203], v[104:107]
	v_mfma_f32_16x16x32_bf16 v[92:95], v[150:153], v[208:211], v[92:95]
	v_mfma_f32_16x16x32_bf16 v[88:91], v[168:171], v[208:211], v[88:91]
	v_mfma_f32_16x16x32_bf16 v[76:79], v[150:153], v[216:219], v[76:79]
	v_mfma_f32_16x16x32_bf16 v[72:75], v[168:171], v[216:219], v[72:75]
	v_mfma_f32_16x16x32_bf16 v[116:119], v[172:175], v[188:191], v[116:119]
	v_mfma_f32_16x16x32_bf16 v[112:115], v[180:183], v[188:191], v[112:115]
	v_mfma_f32_16x16x32_bf16 v[100:103], v[172:175], v[196:199], v[100:103]
	v_mfma_f32_16x16x32_bf16 v[96:99], v[180:183], v[196:199], v[96:99]
	v_mfma_f32_16x16x32_bf16 v[84:87], v[172:175], v[204:207], v[84:87]
	v_mfma_f32_16x16x32_bf16 v[80:83], v[180:183], v[204:207], v[80:83]
	v_mfma_f32_16x16x32_bf16 v[68:71], v[172:175], v[212:215], v[68:71]
	v_mfma_f32_16x16x32_bf16 v[64:67], v[180:183], v[212:215], v[64:67]
	v_mfma_f32_16x16x32_bf16 v[116:119], v[176:179], v[192:195], v[116:119]
	v_mfma_f32_16x16x32_bf16 v[112:115], v[184:187], v[192:195], v[112:115]
	v_mfma_f32_16x16x32_bf16 v[100:103], v[176:179], v[200:203], v[100:103]
	v_mfma_f32_16x16x32_bf16 v[96:99], v[184:187], v[200:203], v[96:99]
	v_mfma_f32_16x16x32_bf16 v[84:87], v[176:179], v[208:211], v[84:87]
	v_mfma_f32_16x16x32_bf16 v[80:83], v[184:187], v[208:211], v[80:83]
	v_mfma_f32_16x16x32_bf16 v[68:71], v[176:179], v[216:219], v[68:71]
	v_mfma_f32_16x16x32_bf16 v[64:67], v[184:187], v[216:219], v[64:67]
	s_barrier
	s_add_i32 s60, s72, s44
	v_lshl_add_u64 v[154:155], v[154:155], 0, s[24:25]
	s_mov_b32 m0, s60
	ds_read_b128 v[188:191], v161 offset:49152
	ds_read_b128 v[192:195], v161 offset:50176
	ds_read_b128 v[196:199], v161 offset:51200
	ds_read_b128 v[200:203], v161 offset:52224
	ds_read_b128 v[204:207], v161 offset:53248
	ds_read_b128 v[208:211], v161 offset:54272
	ds_read_b128 v[212:215], v161 offset:55296
	ds_read_b128 v[216:219], v161 offset:56320
	global_load_lds_dwordx4 v[154:155], off
	s_add_i32 m0, s60, 0x2000
	s_add_u32 s58, s58, 0x80080
	v_lshl_add_u64 v[154:155], v[220:221], 0, s[24:25]
	s_addc_u32 s59, s59, 0
	s_add_i32 s60, s78, s44
	global_load_lds_dwordx4 v[154:155], off
	v_lshl_add_u64 v[154:155], s[58:59], 0, v[130:131]
	s_mov_b32 m0, s60
	s_nop 0
	global_load_lds_dwordx4 v[154:155], off
	v_lshl_add_u64 v[154:155], s[58:59], 0, v[134:135]
	s_add_i32 m0, s60, 0x2000
	s_nop 0
	global_load_lds_dwordx4 v[154:155], off
	v_lshl_add_u64 v[154:155], v[222:223], 0, s[24:25]
	s_mov_b32 m0, s64
	s_nop 0
	global_load_lds_dwordx4 v[154:155], off
	v_lshl_add_u64 v[154:155], v[224:225], 0, s[24:25]
	s_mov_b32 m0, s65
	s_nop 0
	global_load_lds_dwordx4 v[154:155], off
	s_waitcnt vmcnt(8)
	s_waitcnt lgkmcnt(0)
	s_barrier
	v_mfma_f32_16x16x32_bf16 v[60:63], v[146:149], v[188:191], v[60:63]
	v_mfma_f32_16x16x32_bf16 v[56:59], v[164:167], v[188:191], v[56:59]
	v_mfma_f32_16x16x32_bf16 v[44:47], v[146:149], v[196:199], v[44:47]
	v_mfma_f32_16x16x32_bf16 v[40:43], v[164:167], v[196:199], v[40:43]
	v_mfma_f32_16x16x32_bf16 v[28:31], v[146:149], v[204:207], v[28:31]
	v_mfma_f32_16x16x32_bf16 v[24:27], v[164:167], v[204:207], v[24:27]
	v_mfma_f32_16x16x32_bf16 v[12:15], v[146:149], v[212:215], v[12:15]
	v_mfma_f32_16x16x32_bf16 v[8:11], v[164:167], v[212:215], v[8:11]
	v_mfma_f32_16x16x32_bf16 v[60:63], v[150:153], v[192:195], v[60:63]
	v_mfma_f32_16x16x32_bf16 v[56:59], v[168:171], v[192:195], v[56:59]
	v_mfma_f32_16x16x32_bf16 v[44:47], v[150:153], v[200:203], v[44:47]
	v_mfma_f32_16x16x32_bf16 v[40:43], v[168:171], v[200:203], v[40:43]
	v_mfma_f32_16x16x32_bf16 v[28:31], v[150:153], v[208:211], v[28:31]
	v_mfma_f32_16x16x32_bf16 v[24:27], v[168:171], v[208:211], v[24:27]
	v_mfma_f32_16x16x32_bf16 v[12:15], v[150:153], v[216:219], v[12:15]
	v_mfma_f32_16x16x32_bf16 v[8:11], v[168:171], v[216:219], v[8:11]
	v_mfma_f32_16x16x32_bf16 v[52:55], v[172:175], v[188:191], v[52:55]
	v_mfma_f32_16x16x32_bf16 v[48:51], v[180:183], v[188:191], v[48:51]
	v_mfma_f32_16x16x32_bf16 v[36:39], v[172:175], v[196:199], v[36:39]
	v_mfma_f32_16x16x32_bf16 v[32:35], v[180:183], v[196:199], v[32:35]
	v_mfma_f32_16x16x32_bf16 v[20:23], v[172:175], v[204:207], v[20:23]
	v_mfma_f32_16x16x32_bf16 v[16:19], v[180:183], v[204:207], v[16:19]
	v_mfma_f32_16x16x32_bf16 v[4:7], v[172:175], v[212:215], v[4:7]
	v_mfma_f32_16x16x32_bf16 v[0:3], v[180:183], v[212:215], v[0:3]
	v_mfma_f32_16x16x32_bf16 v[52:55], v[176:179], v[192:195], v[52:55]
	v_mfma_f32_16x16x32_bf16 v[48:51], v[184:187], v[192:195], v[48:51]
	v_mfma_f32_16x16x32_bf16 v[36:39], v[176:179], v[200:203], v[36:39]
	v_mfma_f32_16x16x32_bf16 v[32:35], v[184:187], v[200:203], v[32:35]
	v_mfma_f32_16x16x32_bf16 v[20:23], v[176:179], v[208:211], v[20:23]
	v_mfma_f32_16x16x32_bf16 v[16:19], v[184:187], v[208:211], v[16:19]
	v_mfma_f32_16x16x32_bf16 v[4:7], v[176:179], v[216:219], v[4:7]
	v_mfma_f32_16x16x32_bf16 v[0:3], v[184:187], v[216:219], v[0:3]
	s_barrier
	s_add_i32 s55, s55, 2
	s_add_u32 s50, s50, 0x100
	s_addc_u32 s51, s51, 0
	s_add_u32 s56, s56, 0x100
	s_addc_u32 s57, s57, 0
	s_cmp_gt_u32 s55, 29
	s_cbranch_scc0 .LBB0_617
	s_and_b64 vcc, exec, s[26:27]
	s_cbranch_vccz .LBB0_620
	s_barrier

.LBB0_708:
	ds_read_b128 v[0:3], v145
	ds_read_b128 v[4:7], v145 offset:1024
	ds_read_b128 v[8:11], v145 offset:2048
	ds_read_b128 v[12:15], v145 offset:3072
	ds_read_b128 v[16:19], v146
	ds_read_b128 v[20:23], v146 offset:1024
	ds_read_b128 v[24:27], v146 offset:2048
	ds_read_b128 v[28:31], v146 offset:3072
	s_ashr_i32 s37, s36, 31
	s_lshl_b64 s[52:53], s[36:37], 17
	s_add_u32 s52, s6, s52
	s_addc_u32 s53, s7, s53
	s_and_b64 s[54:55], s[8:9], exec
	s_cselect_b32 s65, s53, s59
	s_cselect_b32 s64, s52, s58
	s_ashr_i32 s35, s34, 31
	s_lshl_b64 s[54:55], s[34:35], 17
	s_add_u32 s54, s44, s54
	s_addc_u32 s55, s45, s55
	s_and_b64 s[62:63], s[8:9], exec
	s_cselect_b32 s63, s55, s61
	s_cselect_b32 s62, s54, s60
	s_add_u32 s86, s58, 0x10080
	s_addc_u32 s87, s59, 0
	s_mov_b32 m0, s72
	v_lshl_add_u64 v[64:65], s[86:87], 0, v[128:129]
	ds_read_b128 v[32:35], v147
	ds_read_b128 v[36:39], v147 offset:1024
	ds_read_b128 v[40:43], v147 offset:2048
	ds_read_b128 v[44:47], v147 offset:3072
	ds_read_b128 v[48:51], v147 offset:4096
	ds_read_b128 v[52:55], v147 offset:5120
	ds_read_b128 v[56:59], v147 offset:6144
	ds_read_b128 v[60:63], v147 offset:7168
	global_load_lds_dwordx4 v[64:65], off
	v_lshl_add_u64 v[64:65], s[86:87], 0, v[132:133]
	s_mov_b32 m0, s80
	s_nop 0
	global_load_lds_dwordx4 v[64:65], off
	s_waitcnt vmcnt(8)
	s_waitcnt lgkmcnt(0)
	s_barrier
	v_mfma_f32_16x16x32_bf16 v[64:67], v[0:3], v[32:35], 0
	v_mfma_f32_16x16x32_bf16 v[68:71], v[8:11], v[32:35], 0
	v_mfma_f32_16x16x32_bf16 v[72:75], v[0:3], v[40:43], 0
	v_mfma_f32_16x16x32_bf16 v[76:79], v[8:11], v[40:43], 0
	v_mfma_f32_16x16x32_bf16 v[80:83], v[0:3], v[48:51], 0
	v_mfma_f32_16x16x32_bf16 v[84:87], v[8:11], v[48:51], 0
	v_mfma_f32_16x16x32_bf16 v[88:91], v[0:3], v[56:59], 0
	v_mfma_f32_16x16x32_bf16 v[92:95], v[8:11], v[56:59], 0
	v_mfma_f32_16x16x32_bf16 v[64:67], v[4:7], v[36:39], v[64:67]
	v_mfma_f32_16x16x32_bf16 v[68:71], v[12:15], v[36:39], v[68:71]
	v_mfma_f32_16x16x32_bf16 v[72:75], v[4:7], v[44:47], v[72:75]
	v_mfma_f32_16x16x32_bf16 v[76:79], v[12:15], v[44:47], v[76:79]
	v_mfma_f32_16x16x32_bf16 v[80:83], v[4:7], v[52:55], v[80:83]
	v_mfma_f32_16x16x32_bf16 v[84:87], v[12:15], v[52:55], v[84:87]
	v_mfma_f32_16x16x32_bf16 v[88:91], v[4:7], v[60:63], v[88:91]
	v_mfma_f32_16x16x32_bf16 v[92:95], v[12:15], v[60:63], v[92:95]
	v_mfma_f32_16x16x32_bf16 v[96:99], v[16:19], v[32:35], 0
	v_mfma_f32_16x16x32_bf16 v[32:35], v[24:27], v[32:35], 0
	v_mfma_f32_16x16x32_bf16 v[96:99], v[20:23], v[36:39], v[96:99]
	v_mfma_f32_16x16x32_bf16 v[32:35], v[28:31], v[36:39], v[32:35]
	v_mfma_f32_16x16x32_bf16 v[36:39], v[16:19], v[40:43], 0
	v_mfma_f32_16x16x32_bf16 v[40:43], v[24:27], v[40:43], 0
	v_mfma_f32_16x16x32_bf16 v[36:39], v[20:23], v[44:47], v[36:39]
	v_mfma_f32_16x16x32_bf16 v[40:43], v[28:31], v[44:47], v[40:43]
	v_mfma_f32_16x16x32_bf16 v[44:47], v[16:19], v[48:51], 0
	v_mfma_f32_16x16x32_bf16 v[48:51], v[24:27], v[48:51], 0
	v_mfma_f32_16x16x32_bf16 v[44:47], v[20:23], v[52:55], v[44:47]
	v_mfma_f32_16x16x32_bf16 v[48:51], v[28:31], v[52:55], v[48:51]
	v_mfma_f32_16x16x32_bf16 v[52:55], v[16:19], v[56:59], 0
	v_mfma_f32_16x16x32_bf16 v[56:59], v[24:27], v[56:59], 0
	v_mfma_f32_16x16x32_bf16 v[52:55], v[20:23], v[60:63], v[52:55]
	v_mfma_f32_16x16x32_bf16 v[56:59], v[28:31], v[60:63], v[56:59]
	s_barrier
	s_add_i32 s85, s70, s48
	v_lshl_add_u64 v[140:141], s[60:61], 0, v[130:131]
	s_add_i32 s35, s85, 0x2000
	v_lshl_add_u64 v[148:149], v[140:141], 0, s[20:21]
	s_mov_b32 m0, s85
	v_lshl_add_u64 v[212:213], s[60:61], 0, v[134:135]
	s_add_u32 s86, s60, 0x10100
	ds_read_b128 v[60:63], v147 offset:16384
	ds_read_b128 v[100:103], v147 offset:17408
	ds_read_b128 v[104:107], v147 offset:18432
	ds_read_b128 v[108:111], v147 offset:19456
	ds_read_b128 v[112:115], v147 offset:20480
	ds_read_b128 v[116:119], v147 offset:21504
	ds_read_b128 v[120:123], v147 offset:22528
	ds_read_b128 v[124:127], v147 offset:23552
	global_load_lds_dwordx4 v[148:149], off
	v_lshl_add_u64 v[148:149], v[212:213], 0, s[20:21]
	s_mov_b32 m0, s35
	s_addc_u32 s87, s61, 0
	s_add_i32 s37, s71, s48
	global_load_lds_dwordx4 v[148:149], off
	v_lshl_add_u64 v[148:149], s[86:87], 0, v[130:131]
	s_mov_b32 m0, s37
	s_add_i32 s47, s37, 0x2000
	global_load_lds_dwordx4 v[148:149], off
	v_lshl_add_u64 v[148:149], s[86:87], 0, v[134:135]
	s_mov_b32 m0, s47
	v_lshl_add_u64 v[214:215], s[58:59], 0, v[128:129]
	global_load_lds_dwordx4 v[148:149], off
	v_lshl_add_u64 v[148:149], v[214:215], 0, s[20:21]
	s_mov_b32 m0, s49
	v_lshl_add_u64 v[216:217], s[58:59], 0, v[132:133]
	global_load_lds_dwordx4 v[148:149], off
	v_lshl_add_u64 v[148:149], v[216:217], 0, s[20:21]
	s_mov_b32 m0, s50
	s_nop 0
	global_load_lds_dwordx4 v[148:149], off
	s_waitcnt vmcnt(8)
	s_waitcnt lgkmcnt(0)
	s_barrier
	v_mfma_f32_16x16x32_bf16 v[148:151], v[0:3], v[60:63], 0
	v_mfma_f32_16x16x32_bf16 v[156:159], v[0:3], v[104:107], 0
	v_mfma_f32_16x16x32_bf16 v[164:167], v[0:3], v[112:115], 0
	v_mfma_f32_16x16x32_bf16 v[0:3], v[0:3], v[120:123], 0
	v_mfma_f32_16x16x32_bf16 v[148:151], v[4:7], v[100:103], v[148:151]
	v_mfma_f32_16x16x32_bf16 v[156:159], v[4:7], v[108:111], v[156:159]
	v_mfma_f32_16x16x32_bf16 v[164:167], v[4:7], v[116:119], v[164:167]
	v_mfma_f32_16x16x32_bf16 v[0:3], v[4:7], v[124:127], v[0:3]
	v_mfma_f32_16x16x32_bf16 v[4:7], v[8:11], v[120:123], 0
	v_mfma_f32_16x16x32_bf16 v[152:155], v[8:11], v[60:63], 0
	v_mfma_f32_16x16x32_bf16 v[160:163], v[8:11], v[104:107], 0
	v_mfma_f32_16x16x32_bf16 v[168:171], v[8:11], v[112:115], 0
	v_mfma_f32_16x16x32_bf16 v[4:7], v[12:15], v[124:127], v[4:7]
	v_mfma_f32_16x16x32_bf16 v[152:155], v[12:15], v[100:103], v[152:155]
	v_mfma_f32_16x16x32_bf16 v[160:163], v[12:15], v[108:111], v[160:163]
	v_mfma_f32_16x16x32_bf16 v[168:171], v[12:15], v[116:119], v[168:171]
	v_mfma_f32_16x16x32_bf16 v[8:11], v[16:19], v[60:63], 0
	v_mfma_f32_16x16x32_bf16 v[12:15], v[24:27], v[60:63], 0
	v_mfma_f32_16x16x32_bf16 v[8:11], v[20:23], v[100:103], v[8:11]
	v_mfma_f32_16x16x32_bf16 v[12:15], v[28:31], v[100:103], v[12:15]
	v_mfma_f32_16x16x32_bf16 v[60:63], v[16:19], v[104:107], 0
	v_mfma_f32_16x16x32_bf16 v[100:103], v[24:27], v[104:107], 0
	v_mfma_f32_16x16x32_bf16 v[104:107], v[16:19], v[112:115], 0
	v_mfma_f32_16x16x32_bf16 v[16:19], v[16:19], v[120:123], 0
	v_mfma_f32_16x16x32_bf16 v[60:63], v[20:23], v[108:111], v[60:63]
	v_mfma_f32_16x16x32_bf16 v[100:103], v[28:31], v[108:111], v[100:103]
	v_mfma_f32_16x16x32_bf16 v[104:107], v[20:23], v[116:119], v[104:107]
	v_mfma_f32_16x16x32_bf16 v[108:111], v[24:27], v[112:115], 0
	v_mfma_f32_16x16x32_bf16 v[16:19], v[20:23], v[124:127], v[16:19]
	v_mfma_f32_16x16x32_bf16 v[20:23], v[24:27], v[120:123], 0
	v_mfma_f32_16x16x32_bf16 v[108:111], v[28:31], v[116:119], v[108:111]
	v_mfma_f32_16x16x32_bf16 v[20:23], v[28:31], v[124:127], v[20:23]
	s_barrier
	s_add_i32 s78, 0, 0x18000
	s_add_i32 s79, 0, 0x1c000
	v_add_u32_e32 v224, s78, v143
	v_add_u32_e32 v232, s79, v143
	ds_read_b128 v[24:27], v224
	ds_read_b128 v[28:31], v224 offset:1024
	ds_read_b128 v[112:115], v224 offset:2048
	ds_read_b128 v[116:119], v224 offset:3072
	ds_read_b128 v[120:123], v232
	ds_read_b128 v[124:127], v232 offset:1024
	ds_read_b128 v[172:175], v232 offset:2048
	ds_read_b128 v[176:179], v232 offset:3072
	s_add_u32 s86, s58, 0x10100
	s_addc_u32 s87, s59, 0
	s_mov_b32 m0, s51
	v_lshl_add_u64 v[218:219], s[86:87], 0, v[128:129]
	ds_read_b128 v[180:183], v147 offset:32768
	ds_read_b128 v[184:187], v147 offset:33792
	ds_read_b128 v[188:191], v147 offset:34816
	ds_read_b128 v[192:195], v147 offset:35840
	ds_read_b128 v[196:199], v147 offset:36864
	ds_read_b128 v[200:203], v147 offset:37888
	ds_read_b128 v[204:207], v147 offset:38912
	ds_read_b128 v[208:211], v147 offset:39936
	global_load_lds_dwordx4 v[218:219], off
	v_lshl_add_u64 v[218:219], s[86:87], 0, v[132:133]
	s_mov_b32 m0, s57
	s_nop 0
	global_load_lds_dwordx4 v[218:219], off
	s_waitcnt vmcnt(8)
	s_waitcnt lgkmcnt(0)
	s_barrier
	v_mfma_f32_16x16x32_bf16 v[64:67], v[24:27], v[180:183], v[64:67]
	v_mfma_f32_16x16x32_bf16 v[68:71], v[112:115], v[180:183], v[68:71]
	v_mfma_f32_16x16x32_bf16 v[72:75], v[24:27], v[188:191], v[72:75]
	v_mfma_f32_16x16x32_bf16 v[76:79], v[112:115], v[188:191], v[76:79]
	v_mfma_f32_16x16x32_bf16 v[80:83], v[24:27], v[196:199], v[80:83]
	v_mfma_f32_16x16x32_bf16 v[84:87], v[112:115], v[196:199], v[84:87]
	v_mfma_f32_16x16x32_bf16 v[88:91], v[24:27], v[204:207], v[88:91]
	v_mfma_f32_16x16x32_bf16 v[92:95], v[112:115], v[204:207], v[92:95]
	v_mfma_f32_16x16x32_bf16 v[64:67], v[28:31], v[184:187], v[64:67]
	v_mfma_f32_16x16x32_bf16 v[68:71], v[116:119], v[184:187], v[68:71]
	v_mfma_f32_16x16x32_bf16 v[72:75], v[28:31], v[192:195], v[72:75]
	v_mfma_f32_16x16x32_bf16 v[76:79], v[116:119], v[192:195], v[76:79]
	v_mfma_f32_16x16x32_bf16 v[80:83], v[28:31], v[200:203], v[80:83]
	v_mfma_f32_16x16x32_bf16 v[84:87], v[116:119], v[200:203], v[84:87]
	v_mfma_f32_16x16x32_bf16 v[88:91], v[28:31], v[208:211], v[88:91]
	v_mfma_f32_16x16x32_bf16 v[92:95], v[116:119], v[208:211], v[92:95]
	v_mfma_f32_16x16x32_bf16 v[96:99], v[120:123], v[180:183], v[96:99]
	v_mfma_f32_16x16x32_bf16 v[32:35], v[172:175], v[180:183], v[32:35]
	v_mfma_f32_16x16x32_bf16 v[36:39], v[120:123], v[188:191], v[36:39]
	v_mfma_f32_16x16x32_bf16 v[40:43], v[172:175], v[188:191], v[40:43]
	v_mfma_f32_16x16x32_bf16 v[44:47], v[120:123], v[196:199], v[44:47]
	v_mfma_f32_16x16x32_bf16 v[48:51], v[172:175], v[196:199], v[48:51]
	v_mfma_f32_16x16x32_bf16 v[52:55], v[120:123], v[204:207], v[52:55]
	v_mfma_f32_16x16x32_bf16 v[56:59], v[172:175], v[204:207], v[56:59]
	v_mfma_f32_16x16x32_bf16 v[96:99], v[124:127], v[184:187], v[96:99]
	v_mfma_f32_16x16x32_bf16 v[32:35], v[176:179], v[184:187], v[32:35]
	v_mfma_f32_16x16x32_bf16 v[36:39], v[124:127], v[192:195], v[36:39]
	v_mfma_f32_16x16x32_bf16 v[40:43], v[176:179], v[192:195], v[40:43]
	v_mfma_f32_16x16x32_bf16 v[44:47], v[124:127], v[200:203], v[44:47]
	v_mfma_f32_16x16x32_bf16 v[48:51], v[176:179], v[200:203], v[48:51]
	v_mfma_f32_16x16x32_bf16 v[52:55], v[124:127], v[208:211], v[52:55]
	v_mfma_f32_16x16x32_bf16 v[56:59], v[176:179], v[208:211], v[56:59]
	s_barrier
	s_add_i32 s87, s78, s48
	s_add_i32 s86, s87, 0x2000
	v_lshl_add_u64 v[140:141], v[140:141], 0, s[22:23]
	s_mov_b32 m0, s87
	s_add_u32 s88, s60, 0x10180
	ds_read_b128 v[180:183], v147 offset:49152
	ds_read_b128 v[184:187], v147 offset:50176
	ds_read_b128 v[188:191], v147 offset:51200
	ds_read_b128 v[192:195], v147 offset:52224
	ds_read_b128 v[196:199], v147 offset:53248
	ds_read_b128 v[200:203], v147 offset:54272
	ds_read_b128 v[204:207], v147 offset:55296
	ds_read_b128 v[208:211], v147 offset:56320
	global_load_lds_dwordx4 v[140:141], off
	v_lshl_add_u64 v[140:141], v[212:213], 0, s[22:23]
	s_mov_b32 m0, s86
	s_addc_u32 s89, s61, 0
	s_add_i32 s60, s79, s48
	global_load_lds_dwordx4 v[140:141], off
	v_lshl_add_u64 v[140:141], s[88:89], 0, v[130:131]
	s_mov_b32 m0, s60
	s_add_i32 s61, s60, 0x2000
	global_load_lds_dwordx4 v[140:141], off
	v_lshl_add_u64 v[140:141], s[88:89], 0, v[134:135]
	s_mov_b32 m0, s61
	s_nop 0
	global_load_lds_dwordx4 v[140:141], off
	v_lshl_add_u64 v[140:141], v[214:215], 0, s[22:23]
	s_mov_b32 m0, s66
	s_nop 0
	global_load_lds_dwordx4 v[140:141], off
	v_lshl_add_u64 v[140:141], v[216:217], 0, s[22:23]
	s_mov_b32 m0, s67
	s_nop 0
	global_load_lds_dwordx4 v[140:141], off
	s_waitcnt vmcnt(8)
	s_waitcnt lgkmcnt(0)
	s_barrier
	v_mfma_f32_16x16x32_bf16 v[0:3], v[24:27], v[204:207], v[0:3]
	v_mfma_f32_16x16x32_bf16 v[4:7], v[112:115], v[204:207], v[4:7]
	v_mfma_f32_16x16x32_bf16 v[148:151], v[24:27], v[180:183], v[148:151]
	v_mfma_f32_16x16x32_bf16 v[152:155], v[112:115], v[180:183], v[152:155]
	v_mfma_f32_16x16x32_bf16 v[156:159], v[24:27], v[188:191], v[156:159]
	v_mfma_f32_16x16x32_bf16 v[160:163], v[112:115], v[188:191], v[160:163]
	v_mfma_f32_16x16x32_bf16 v[164:167], v[24:27], v[196:199], v[164:167]
	v_mfma_f32_16x16x32_bf16 v[168:171], v[112:115], v[196:199], v[168:171]
	v_mfma_f32_16x16x32_bf16 v[0:3], v[28:31], v[208:211], v[0:3]
	v_mfma_f32_16x16x32_bf16 v[4:7], v[116:119], v[208:211], v[4:7]
	v_mfma_f32_16x16x32_bf16 v[148:151], v[28:31], v[184:187], v[148:151]
	v_mfma_f32_16x16x32_bf16 v[152:155], v[116:119], v[184:187], v[152:155]
	v_mfma_f32_16x16x32_bf16 v[156:159], v[28:31], v[192:195], v[156:159]
	v_mfma_f32_16x16x32_bf16 v[160:163], v[116:119], v[192:195], v[160:163]
	v_mfma_f32_16x16x32_bf16 v[164:167], v[28:31], v[200:203], v[164:167]
	v_mfma_f32_16x16x32_bf16 v[168:171], v[116:119], v[200:203], v[168:171]
	v_mfma_f32_16x16x32_bf16 v[8:11], v[120:123], v[180:183], v[8:11]
	v_mfma_f32_16x16x32_bf16 v[12:15], v[172:175], v[180:183], v[12:15]
	v_mfma_f32_16x16x32_bf16 v[24:27], v[120:123], v[188:191], v[60:63]
	v_mfma_f32_16x16x32_bf16 v[28:31], v[172:175], v[188:191], v[100:103]
	v_mfma_f32_16x16x32_bf16 v[60:63], v[120:123], v[196:199], v[104:107]
	v_mfma_f32_16x16x32_bf16 v[100:103], v[172:175], v[196:199], v[108:111]
	v_mfma_f32_16x16x32_bf16 v[16:19], v[120:123], v[204:207], v[16:19]
	v_mfma_f32_16x16x32_bf16 v[20:23], v[172:175], v[204:207], v[20:23]
	v_mfma_f32_16x16x32_bf16 v[8:11], v[124:127], v[184:187], v[8:11]
	v_mfma_f32_16x16x32_bf16 v[12:15], v[176:179], v[184:187], v[12:15]
	v_mfma_f32_16x16x32_bf16 v[24:27], v[124:127], v[192:195], v[24:27]
	v_mfma_f32_16x16x32_bf16 v[28:31], v[176:179], v[192:195], v[28:31]
	v_mfma_f32_16x16x32_bf16 v[60:63], v[124:127], v[200:203], v[60:63]
	v_mfma_f32_16x16x32_bf16 v[100:103], v[176:179], v[200:203], v[100:103]
	v_mfma_f32_16x16x32_bf16 v[16:19], v[124:127], v[208:211], v[16:19]
	v_mfma_f32_16x16x32_bf16 v[20:23], v[176:179], v[208:211], v[20:23]
	s_barrier
	ds_read_b128 v[104:107], v145
	ds_read_b128 v[108:111], v145 offset:1024
	ds_read_b128 v[112:115], v145 offset:2048
	ds_read_b128 v[116:119], v145 offset:3072
	ds_read_b128 v[120:123], v146
	ds_read_b128 v[124:127], v146 offset:1024
	ds_read_b128 v[172:175], v146 offset:2048
	ds_read_b128 v[176:179], v146 offset:3072
	s_add_u32 s58, s58, 0x10180
	s_addc_u32 s59, s59, 0
	s_mov_b32 m0, s72
	v_lshl_add_u64 v[140:141], s[58:59], 0, v[128:129]
	ds_read_b128 v[180:183], v147
	ds_read_b128 v[184:187], v147 offset:1024
	ds_read_b128 v[188:191], v147 offset:2048
	ds_read_b128 v[192:195], v147 offset:3072
	ds_read_b128 v[196:199], v147 offset:4096
	ds_read_b128 v[200:203], v147 offset:5120
	ds_read_b128 v[204:207], v147 offset:6144
	ds_read_b128 v[208:211], v147 offset:7168
	global_load_lds_dwordx4 v[140:141], off
	v_lshl_add_u64 v[140:141], s[58:59], 0, v[132:133]
	s_mov_b32 m0, s80
	s_nop 0
	global_load_lds_dwordx4 v[140:141], off
	s_waitcnt vmcnt(8)
	s_waitcnt lgkmcnt(0)
	s_barrier
	v_mfma_f32_16x16x32_bf16 v[88:91], v[104:107], v[204:207], v[88:91]
	v_mfma_f32_16x16x32_bf16 v[64:67], v[104:107], v[180:183], v[64:67]
	v_mfma_f32_16x16x32_bf16 v[68:71], v[112:115], v[180:183], v[68:71]
	v_mfma_f32_16x16x32_bf16 v[72:75], v[104:107], v[188:191], v[72:75]
	v_mfma_f32_16x16x32_bf16 v[76:79], v[112:115], v[188:191], v[76:79]
	v_mfma_f32_16x16x32_bf16 v[80:83], v[104:107], v[196:199], v[80:83]
	v_mfma_f32_16x16x32_bf16 v[84:87], v[112:115], v[196:199], v[84:87]
	v_mfma_f32_16x16x32_bf16 v[212:215], v[108:111], v[208:211], v[88:91]
	v_mfma_f32_16x16x32_bf16 v[88:91], v[112:115], v[204:207], v[92:95]
	v_mfma_f32_16x16x32_bf16 v[64:67], v[108:111], v[184:187], v[64:67]
	v_mfma_f32_16x16x32_bf16 v[68:71], v[116:119], v[184:187], v[68:71]
	v_mfma_f32_16x16x32_bf16 v[72:75], v[108:111], v[192:195], v[72:75]
	v_mfma_f32_16x16x32_bf16 v[76:79], v[116:119], v[192:195], v[76:79]
	v_mfma_f32_16x16x32_bf16 v[80:83], v[108:111], v[200:203], v[80:83]
	v_mfma_f32_16x16x32_bf16 v[84:87], v[116:119], v[200:203], v[84:87]
	v_mfma_f32_16x16x32_bf16 v[92:95], v[116:119], v[208:211], v[88:91]
	v_mfma_f32_16x16x32_bf16 v[48:51], v[172:175], v[196:199], v[48:51]
	v_mfma_f32_16x16x32_bf16 v[88:91], v[120:123], v[180:183], v[96:99]
	v_mfma_f32_16x16x32_bf16 v[32:35], v[172:175], v[180:183], v[32:35]
	v_mfma_f32_16x16x32_bf16 v[36:39], v[120:123], v[188:191], v[36:39]
	v_mfma_f32_16x16x32_bf16 v[40:43], v[172:175], v[188:191], v[40:43]
	v_mfma_f32_16x16x32_bf16 v[44:47], v[120:123], v[196:199], v[44:47]
	v_mfma_f32_16x16x32_bf16 v[180:183], v[176:179], v[200:203], v[48:51]
	v_mfma_f32_16x16x32_bf16 v[48:51], v[120:123], v[204:207], v[52:55]
	v_mfma_f32_16x16x32_bf16 v[32:35], v[176:179], v[184:187], v[32:35]
	v_mfma_f32_16x16x32_bf16 v[36:39], v[124:127], v[192:195], v[36:39]
	v_mfma_f32_16x16x32_bf16 v[40:43], v[176:179], v[192:195], v[40:43]
	v_mfma_f32_16x16x32_bf16 v[44:47], v[124:127], v[200:203], v[44:47]
	v_mfma_f32_16x16x32_bf16 v[52:55], v[124:127], v[208:211], v[48:51]
	v_mfma_f32_16x16x32_bf16 v[48:51], v[172:175], v[204:207], v[56:59]
	v_mfma_f32_16x16x32_bf16 v[216:219], v[124:127], v[184:187], v[88:91]
	v_mfma_f32_16x16x32_bf16 v[184:187], v[176:179], v[208:211], v[48:51]
	s_barrier
	s_mov_b32 m0, s85
	v_lshl_add_u64 v[140:141], s[62:63], 0, v[130:131]
	s_add_u32 s58, s62, 0x10000
	s_nop 0
	ds_read_b128 v[48:51], v147 offset:16384
	ds_read_b128 v[56:59], v147 offset:17408
	ds_read_b128 v[88:91], v147 offset:18432
	ds_read_b128 v[96:99], v147 offset:19456
	ds_read_b128 v[188:191], v147 offset:20480
	ds_read_b128 v[192:195], v147 offset:21504
	ds_read_b128 v[196:199], v147 offset:22528
	ds_read_b128 v[200:203], v147 offset:23552
	global_load_lds_dwordx4 v[140:141], off
	v_lshl_add_u64 v[252:253], s[62:63], 0, v[134:135]
	s_mov_b32 m0, s35
	s_addc_u32 s59, s63, 0
	global_load_lds_dwordx4 v[252:253], off
	v_lshl_add_u64 v[204:205], s[58:59], 0, v[130:131]
	s_mov_b32 m0, s37
	v_lshl_add_u64 v[136:137], s[64:65], 0, v[128:129]
	global_load_lds_dwordx4 v[204:205], off
	v_lshl_add_u64 v[204:205], s[58:59], 0, v[134:135]
	s_mov_b32 m0, s47
	v_lshl_add_u64 v[138:139], s[64:65], 0, v[132:133]
	global_load_lds_dwordx4 v[204:205], off
	s_mov_b32 m0, s49
	s_nop 0
	global_load_lds_dwordx4 v[136:137], off
	s_mov_b32 m0, s50
	s_nop 0
	global_load_lds_dwordx4 v[138:139], off
	s_waitcnt vmcnt(8)
	s_waitcnt lgkmcnt(0)
	s_barrier
	v_mfma_f32_16x16x32_bf16 v[0:3], v[104:107], v[196:199], v[0:3]
	v_mfma_f32_16x16x32_bf16 v[4:7], v[112:115], v[196:199], v[4:7]
	v_mfma_f32_16x16x32_bf16 v[148:151], v[104:107], v[48:51], v[148:151]
	v_mfma_f32_16x16x32_bf16 v[152:155], v[112:115], v[48:51], v[152:155]
	v_mfma_f32_16x16x32_bf16 v[156:159], v[104:107], v[88:91], v[156:159]
	v_mfma_f32_16x16x32_bf16 v[160:163], v[112:115], v[88:91], v[160:163]
	v_mfma_f32_16x16x32_bf16 v[164:167], v[104:107], v[188:191], v[164:167]
	v_mfma_f32_16x16x32_bf16 v[168:171], v[112:115], v[188:191], v[168:171]
	v_mfma_f32_16x16x32_bf16 v[0:3], v[108:111], v[200:203], v[0:3]
	v_mfma_f32_16x16x32_bf16 v[4:7], v[116:119], v[200:203], v[4:7]
	v_mfma_f32_16x16x32_bf16 v[148:151], v[108:111], v[56:59], v[148:151]
	v_mfma_f32_16x16x32_bf16 v[152:155], v[116:119], v[56:59], v[152:155]
	v_mfma_f32_16x16x32_bf16 v[156:159], v[108:111], v[96:99], v[156:159]
	v_mfma_f32_16x16x32_bf16 v[160:163], v[116:119], v[96:99], v[160:163]
	v_mfma_f32_16x16x32_bf16 v[164:167], v[108:111], v[192:195], v[164:167]
	v_mfma_f32_16x16x32_bf16 v[168:171], v[116:119], v[192:195], v[168:171]
	v_mfma_f32_16x16x32_bf16 v[12:15], v[172:175], v[48:51], v[12:15]
	v_mfma_f32_16x16x32_bf16 v[204:207], v[176:179], v[56:59], v[12:15]
	v_mfma_f32_16x16x32_bf16 v[12:15], v[120:123], v[88:91], v[24:27]
	v_mfma_f32_16x16x32_bf16 v[24:27], v[124:127], v[96:99], v[12:15]
	v_mfma_f32_16x16x32_bf16 v[12:15], v[172:175], v[88:91], v[28:31]
	v_mfma_f32_16x16x32_bf16 v[208:211], v[176:179], v[96:99], v[12:15]
	v_mfma_f32_16x16x32_bf16 v[12:15], v[120:123], v[188:191], v[60:63]
	v_mfma_f32_16x16x32_bf16 v[220:223], v[124:127], v[192:195], v[12:15]
	v_mfma_f32_16x16x32_bf16 v[12:15], v[172:175], v[188:191], v[100:103]
	v_mfma_f32_16x16x32_bf16 v[8:11], v[120:123], v[48:51], v[8:11]
	v_mfma_f32_16x16x32_bf16 v[188:191], v[176:179], v[192:195], v[12:15]
	v_mfma_f32_16x16x32_bf16 v[12:15], v[120:123], v[196:199], v[16:19]
	v_mfma_f32_16x16x32_bf16 v[8:11], v[124:127], v[56:59], v[8:11]
	v_mfma_f32_16x16x32_bf16 v[192:195], v[124:127], v[200:203], v[12:15]
	v_mfma_f32_16x16x32_bf16 v[12:15], v[172:175], v[196:199], v[20:23]
	v_mfma_f32_16x16x32_bf16 v[172:175], v[176:179], v[200:203], v[12:15]
	s_barrier
	s_nop 4
	ds_read_b128 v[12:15], v224
	ds_read_b128 v[16:19], v224 offset:1024
	ds_read_b128 v[176:179], v224 offset:2048
	ds_read_b128 v[196:199], v224 offset:3072
	ds_read_b128 v[200:203], v232
	ds_read_b128 v[224:227], v232 offset:1024
	ds_read_b128 v[228:231], v232 offset:2048
	ds_read_b128 v[232:235], v232 offset:3072
	s_add_u32 s58, s64, 0x10000
	s_addc_u32 s59, s65, 0
	s_mov_b32 m0, s51
	v_lshl_add_u64 v[48:49], s[58:59], 0, v[128:129]
	ds_read_b128 v[20:23], v147 offset:32768
	ds_read_b128 v[28:31], v147 offset:33792
	ds_read_b128 v[60:63], v147 offset:34816
	ds_read_b128 v[100:103], v147 offset:35840
	ds_read_b128 v[236:239], v147 offset:36864
	ds_read_b128 v[240:243], v147 offset:37888
	ds_read_b128 v[244:247], v147 offset:38912
	ds_read_b128 v[248:251], v147 offset:39936
	global_load_lds_dwordx4 v[48:49], off
	v_lshl_add_u64 v[48:49], s[58:59], 0, v[132:133]
	s_mov_b32 m0, s57
	s_nop 0
	global_load_lds_dwordx4 v[48:49], off
	s_waitcnt vmcnt(8)
	s_waitcnt lgkmcnt(0)
	s_barrier
	v_mfma_f32_16x16x32_bf16 v[48:51], v[12:15], v[20:23], v[64:67]
	v_mfma_f32_16x16x32_bf16 v[120:123], v[16:19], v[28:31], v[48:51]
	v_mfma_f32_16x16x32_bf16 v[48:51], v[176:179], v[20:23], v[68:71]
	v_mfma_f32_16x16x32_bf16 v[112:115], v[196:199], v[28:31], v[48:51]
	v_mfma_f32_16x16x32_bf16 v[48:51], v[12:15], v[60:63], v[72:75]
	v_mfma_f32_16x16x32_bf16 v[104:107], v[16:19], v[100:103], v[48:51]
	v_mfma_f32_16x16x32_bf16 v[48:51], v[176:179], v[60:63], v[76:79]
	v_mfma_f32_16x16x32_bf16 v[96:99], v[196:199], v[100:103], v[48:51]
	v_mfma_f32_16x16x32_bf16 v[48:51], v[12:15], v[236:239], v[80:83]
	v_mfma_f32_16x16x32_bf16 v[88:91], v[16:19], v[240:243], v[48:51]
	v_mfma_f32_16x16x32_bf16 v[48:51], v[176:179], v[236:239], v[84:87]
	v_mfma_f32_16x16x32_bf16 v[80:83], v[196:199], v[240:243], v[48:51]
	v_mfma_f32_16x16x32_bf16 v[48:51], v[12:15], v[244:247], v[212:215]
	v_mfma_f32_16x16x32_bf16 v[56:59], v[16:19], v[248:251], v[48:51]
	v_mfma_f32_16x16x32_bf16 v[48:51], v[176:179], v[244:247], v[92:95]
	v_mfma_f32_16x16x32_bf16 v[48:51], v[196:199], v[248:251], v[48:51]
	v_mfma_f32_16x16x32_bf16 v[64:67], v[200:203], v[20:23], v[216:219]
	v_mfma_f32_16x16x32_bf16 v[20:23], v[228:231], v[20:23], v[32:35]
	v_mfma_f32_16x16x32_bf16 v[116:119], v[232:235], v[28:31], v[20:23]
	v_mfma_f32_16x16x32_bf16 v[20:23], v[200:203], v[60:63], v[36:39]
	v_mfma_f32_16x16x32_bf16 v[108:111], v[224:227], v[100:103], v[20:23]
	v_mfma_f32_16x16x32_bf16 v[20:23], v[228:231], v[60:63], v[40:43]
	v_mfma_f32_16x16x32_bf16 v[100:103], v[232:235], v[100:103], v[20:23]
	v_mfma_f32_16x16x32_bf16 v[20:23], v[200:203], v[236:239], v[44:47]
	v_mfma_f32_16x16x32_bf16 v[92:95], v[224:227], v[240:243], v[20:23]
	v_mfma_f32_16x16x32_bf16 v[20:23], v[228:231], v[236:239], v[180:183]
	v_mfma_f32_16x16x32_bf16 v[84:87], v[232:235], v[240:243], v[20:23]
	v_mfma_f32_16x16x32_bf16 v[20:23], v[200:203], v[244:247], v[52:55]
	v_mfma_f32_16x16x32_bf16 v[60:63], v[224:227], v[248:251], v[20:23]
	v_mfma_f32_16x16x32_bf16 v[20:23], v[228:231], v[244:247], v[184:187]
	v_mfma_f32_16x16x32_bf16 v[124:127], v[224:227], v[28:31], v[64:67]
	v_mfma_f32_16x16x32_bf16 v[52:55], v[232:235], v[248:251], v[20:23]
	s_barrier
	s_mov_b32 m0, s87
	s_nop 2
	v_lshl_add_u64 v[20:21], v[140:141], 0, s[14:15]
	s_add_u32 s58, s62, 0x10080
	ds_read_b128 v[32:35], v147 offset:49152
	ds_read_b128 v[40:43], v147 offset:50176
	ds_read_b128 v[180:183], v147 offset:51200
	ds_read_b128 v[184:187], v147 offset:52224
	ds_read_b128 v[212:215], v147 offset:53248
	ds_read_b128 v[216:219], v147 offset:54272
	ds_read_b128 v[236:239], v147 offset:55296
	ds_read_b128 v[240:243], v147 offset:56320
	global_load_lds_dwordx4 v[20:21], off
	v_lshl_add_u64 v[20:21], v[252:253], 0, s[14:15]
	s_mov_b32 m0, s86
	s_addc_u32 s59, s63, 0
	global_load_lds_dwordx4 v[20:21], off
	v_lshl_add_u64 v[20:21], s[58:59], 0, v[130:131]
	s_mov_b32 m0, s60
	s_nop 0
	global_load_lds_dwordx4 v[20:21], off
	v_lshl_add_u64 v[20:21], s[58:59], 0, v[134:135]
	s_mov_b32 m0, s61
	s_nop 0
	global_load_lds_dwordx4 v[20:21], off
	v_lshl_add_u64 v[20:21], v[136:137], 0, s[14:15]
	s_mov_b32 m0, s66
	s_nop 0
	global_load_lds_dwordx4 v[20:21], off
	v_lshl_add_u64 v[20:21], v[138:139], 0, s[14:15]
	s_mov_b32 m0, s67
	s_nop 0
	global_load_lds_dwordx4 v[20:21], off
	s_waitcnt vmcnt(8)
	s_waitcnt lgkmcnt(0)
	s_barrier
	v_mfma_f32_16x16x32_bf16 v[20:23], v[12:15], v[32:35], v[148:151]
	v_mfma_f32_16x16x32_bf16 v[76:79], v[16:19], v[40:43], v[20:23]
	v_mfma_f32_16x16x32_bf16 v[20:23], v[176:179], v[32:35], v[152:155]
	v_mfma_f32_16x16x32_bf16 v[68:71], v[196:199], v[40:43], v[20:23]
	v_mfma_f32_16x16x32_bf16 v[20:23], v[12:15], v[180:183], v[156:159]
	v_mfma_f32_16x16x32_bf16 v[44:47], v[16:19], v[184:187], v[20:23]
	v_mfma_f32_16x16x32_bf16 v[20:23], v[176:179], v[180:183], v[160:163]
	v_mfma_f32_16x16x32_bf16 v[36:39], v[196:199], v[184:187], v[20:23]
	v_mfma_f32_16x16x32_bf16 v[20:23], v[12:15], v[212:215], v[164:167]
	v_mfma_f32_16x16x32_bf16 v[0:3], v[12:15], v[236:239], v[0:3]
	v_mfma_f32_16x16x32_bf16 v[28:31], v[16:19], v[216:219], v[20:23]
	v_mfma_f32_16x16x32_bf16 v[20:23], v[176:179], v[212:215], v[168:171]
	v_mfma_f32_16x16x32_bf16 v[12:15], v[16:19], v[240:243], v[0:3]
	v_mfma_f32_16x16x32_bf16 v[0:3], v[176:179], v[236:239], v[4:7]
	v_mfma_f32_16x16x32_bf16 v[20:23], v[196:199], v[216:219], v[20:23]
	v_mfma_f32_16x16x32_bf16 v[4:7], v[196:199], v[240:243], v[0:3]
	v_mfma_f32_16x16x32_bf16 v[0:3], v[200:203], v[32:35], v[8:11]
	v_mfma_f32_16x16x32_bf16 v[72:75], v[224:227], v[40:43], v[0:3]
	v_mfma_f32_16x16x32_bf16 v[0:3], v[228:231], v[32:35], v[204:207]
	v_mfma_f32_16x16x32_bf16 v[64:67], v[232:235], v[40:43], v[0:3]
	v_mfma_f32_16x16x32_bf16 v[0:3], v[200:203], v[180:183], v[24:27]
	v_mfma_f32_16x16x32_bf16 v[40:43], v[224:227], v[184:187], v[0:3]
	v_mfma_f32_16x16x32_bf16 v[0:3], v[228:231], v[180:183], v[208:211]
	v_mfma_f32_16x16x32_bf16 v[32:35], v[232:235], v[184:187], v[0:3]
	v_mfma_f32_16x16x32_bf16 v[0:3], v[200:203], v[212:215], v[220:223]
	v_mfma_f32_16x16x32_bf16 v[24:27], v[224:227], v[216:219], v[0:3]
	v_mfma_f32_16x16x32_bf16 v[0:3], v[228:231], v[212:215], v[188:191]
	v_mfma_f32_16x16x32_bf16 v[16:19], v[232:235], v[216:219], v[0:3]
	v_mfma_f32_16x16x32_bf16 v[0:3], v[200:203], v[236:239], v[192:195]
	v_mfma_f32_16x16x32_bf16 v[8:11], v[224:227], v[240:243], v[0:3]
	v_mfma_f32_16x16x32_bf16 v[0:3], v[228:231], v[236:239], v[172:175]
	v_mfma_f32_16x16x32_bf16 v[0:3], v[232:235], v[240:243], v[0:3]
	s_barrier
	s_andn2_b64 vcc, exec, s[16:17]
	s_cbranch_vccnz .LBB0_710
	s_barrier

.LBB0_731:
	ds_read_b128 v[146:149], v153
	ds_read_b128 v[158:161], v153 offset:1024
	ds_read_b128 v[162:165], v153 offset:2048
	ds_read_b128 v[166:169], v153 offset:3072
	ds_read_b128 v[170:173], v154
	ds_read_b128 v[174:177], v154 offset:1024
	ds_read_b128 v[178:181], v154 offset:2048
	ds_read_b128 v[182:185], v154 offset:3072
	s_add_u32 s34, s30, 0xfff80080
	s_addc_u32 s35, s31, -1
	s_cmp_eq_u32 s61, 28
	s_cselect_b32 s37, s21, s35
	s_cselect_b32 s36, s46, s34
	s_cselect_b32 s35, s19, s60
	s_cselect_b32 s34, s47, s59
	v_lshl_add_u64 v[218:219], s[30:31], 0, v[140:141]
	s_add_i32 m0, s27, 0xc000
	ds_read_b128 v[186:189], v155
	ds_read_b128 v[190:193], v155 offset:1024
	ds_read_b128 v[194:197], v155 offset:2048
	ds_read_b128 v[198:201], v155 offset:3072
	ds_read_b128 v[202:205], v155 offset:4096
	ds_read_b128 v[206:209], v155 offset:5120
	ds_read_b128 v[210:213], v155 offset:6144
	ds_read_b128 v[214:217], v155 offset:7168
	global_load_lds_dwordx4 v[218:219], off
	v_lshl_add_u64 v[218:219], s[30:31], 0, v[138:139]
	s_add_i32 m0, s27, 0xe000
	s_nop 0
	global_load_lds_dwordx4 v[218:219], off
	s_waitcnt vmcnt(8)
	s_waitcnt lgkmcnt(0)
	s_barrier
	v_mfma_f32_16x16x32_bf16 v[124:127], v[146:149], v[186:189], v[124:127]
	v_mfma_f32_16x16x32_bf16 v[120:123], v[162:165], v[186:189], v[120:123]
	v_mfma_f32_16x16x32_bf16 v[108:111], v[146:149], v[194:197], v[108:111]
	v_mfma_f32_16x16x32_bf16 v[104:107], v[162:165], v[194:197], v[104:107]
	v_mfma_f32_16x16x32_bf16 v[92:95], v[146:149], v[202:205], v[92:95]
	v_mfma_f32_16x16x32_bf16 v[88:91], v[162:165], v[202:205], v[88:91]
	v_mfma_f32_16x16x32_bf16 v[76:79], v[146:149], v[210:213], v[76:79]
	v_mfma_f32_16x16x32_bf16 v[72:75], v[162:165], v[210:213], v[72:75]
	v_mfma_f32_16x16x32_bf16 v[124:127], v[158:161], v[190:193], v[124:127]
	v_mfma_f32_16x16x32_bf16 v[120:123], v[166:169], v[190:193], v[120:123]
	v_mfma_f32_16x16x32_bf16 v[108:111], v[158:161], v[198:201], v[108:111]
	v_mfma_f32_16x16x32_bf16 v[104:107], v[166:169], v[198:201], v[104:107]
	v_mfma_f32_16x16x32_bf16 v[92:95], v[158:161], v[206:209], v[92:95]
	v_mfma_f32_16x16x32_bf16 v[88:91], v[166:169], v[206:209], v[88:91]
	v_mfma_f32_16x16x32_bf16 v[76:79], v[158:161], v[214:217], v[76:79]
	v_mfma_f32_16x16x32_bf16 v[72:75], v[166:169], v[214:217], v[72:75]
	v_mfma_f32_16x16x32_bf16 v[116:119], v[170:173], v[186:189], v[116:119]
	v_mfma_f32_16x16x32_bf16 v[112:115], v[178:181], v[186:189], v[112:115]
	v_mfma_f32_16x16x32_bf16 v[100:103], v[170:173], v[194:197], v[100:103]
	v_mfma_f32_16x16x32_bf16 v[96:99], v[178:181], v[194:197], v[96:99]
	v_mfma_f32_16x16x32_bf16 v[84:87], v[170:173], v[202:205], v[84:87]
	v_mfma_f32_16x16x32_bf16 v[80:83], v[178:181], v[202:205], v[80:83]
	v_mfma_f32_16x16x32_bf16 v[68:71], v[170:173], v[210:213], v[68:71]
	v_mfma_f32_16x16x32_bf16 v[64:67], v[178:181], v[210:213], v[64:67]
	v_mfma_f32_16x16x32_bf16 v[116:119], v[174:177], v[190:193], v[116:119]
	v_mfma_f32_16x16x32_bf16 v[112:115], v[182:185], v[190:193], v[112:115]
	v_mfma_f32_16x16x32_bf16 v[100:103], v[174:177], v[198:201], v[100:103]
	v_mfma_f32_16x16x32_bf16 v[96:99], v[182:185], v[198:201], v[96:99]
	v_mfma_f32_16x16x32_bf16 v[84:87], v[174:177], v[206:209], v[84:87]
	v_mfma_f32_16x16x32_bf16 v[80:83], v[182:185], v[206:209], v[80:83]
	v_mfma_f32_16x16x32_bf16 v[68:71], v[174:177], v[214:217], v[68:71]
	v_mfma_f32_16x16x32_bf16 v[64:67], v[182:185], v[214:217], v[64:67]
	s_barrier
	s_add_i32 s62, s55, s48
	v_lshl_add_u64 v[218:219], s[34:35], 0, v[130:131]
	s_mov_b32 m0, s62
	ds_read_b128 v[186:189], v155 offset:16384
	ds_read_b128 v[190:193], v155 offset:17408
	ds_read_b128 v[194:197], v155 offset:18432
	ds_read_b128 v[198:201], v155 offset:19456
	ds_read_b128 v[202:205], v155 offset:20480
	ds_read_b128 v[206:209], v155 offset:21504
	ds_read_b128 v[210:213], v155 offset:22528
	ds_read_b128 v[214:217], v155 offset:23552
	global_load_lds_dwordx4 v[218:219], off
	s_add_i32 m0, s62, 0x2000
	s_add_u32 s62, s34, 0x80000
	v_lshl_add_u64 v[220:221], s[34:35], 0, v[134:135]
	s_addc_u32 s63, s35, 0
	s_add_i32 s64, s56, s48
	global_load_lds_dwordx4 v[220:221], off
	v_lshl_add_u64 v[222:223], s[62:63], 0, v[130:131]
	s_mov_b32 m0, s64
	v_lshl_add_u64 v[224:225], s[36:37], 0, v[132:133]
	global_load_lds_dwordx4 v[222:223], off
	v_lshl_add_u64 v[222:223], s[62:63], 0, v[134:135]
	s_add_i32 m0, s64, 0x2000
	s_nop 0
	global_load_lds_dwordx4 v[222:223], off
	v_lshl_add_u64 v[222:223], s[36:37], 0, v[128:129]
	s_mov_b32 m0, s27
	s_nop 0
	global_load_lds_dwordx4 v[222:223], off
	s_mov_b32 m0, s49
	s_nop 0
	global_load_lds_dwordx4 v[224:225], off
	s_waitcnt vmcnt(8)
	s_waitcnt lgkmcnt(0)
	s_barrier
	v_mfma_f32_16x16x32_bf16 v[60:63], v[146:149], v[186:189], v[60:63]
	v_mfma_f32_16x16x32_bf16 v[56:59], v[162:165], v[186:189], v[56:59]
	v_mfma_f32_16x16x32_bf16 v[44:47], v[146:149], v[194:197], v[44:47]
	v_mfma_f32_16x16x32_bf16 v[40:43], v[162:165], v[194:197], v[40:43]
	v_mfma_f32_16x16x32_bf16 v[28:31], v[146:149], v[202:205], v[28:31]
	v_mfma_f32_16x16x32_bf16 v[24:27], v[162:165], v[202:205], v[24:27]
	v_mfma_f32_16x16x32_bf16 v[12:15], v[146:149], v[210:213], v[12:15]
	v_mfma_f32_16x16x32_bf16 v[8:11], v[162:165], v[210:213], v[8:11]
	v_mfma_f32_16x16x32_bf16 v[60:63], v[158:161], v[190:193], v[60:63]
	v_mfma_f32_16x16x32_bf16 v[56:59], v[166:169], v[190:193], v[56:59]
	v_mfma_f32_16x16x32_bf16 v[44:47], v[158:161], v[198:201], v[44:47]
	v_mfma_f32_16x16x32_bf16 v[40:43], v[166:169], v[198:201], v[40:43]
	v_mfma_f32_16x16x32_bf16 v[28:31], v[158:161], v[206:209], v[28:31]
	v_mfma_f32_16x16x32_bf16 v[24:27], v[166:169], v[206:209], v[24:27]
	v_mfma_f32_16x16x32_bf16 v[12:15], v[158:161], v[214:217], v[12:15]
	v_mfma_f32_16x16x32_bf16 v[8:11], v[166:169], v[214:217], v[8:11]
	v_mfma_f32_16x16x32_bf16 v[52:55], v[170:173], v[186:189], v[52:55]
	v_mfma_f32_16x16x32_bf16 v[48:51], v[178:181], v[186:189], v[48:51]
	v_mfma_f32_16x16x32_bf16 v[36:39], v[170:173], v[194:197], v[36:39]
	v_mfma_f32_16x16x32_bf16 v[32:35], v[178:181], v[194:197], v[32:35]
	v_mfma_f32_16x16x32_bf16 v[20:23], v[170:173], v[202:205], v[20:23]
	v_mfma_f32_16x16x32_bf16 v[16:19], v[178:181], v[202:205], v[16:19]
	v_mfma_f32_16x16x32_bf16 v[4:7], v[170:173], v[210:213], v[4:7]
	v_mfma_f32_16x16x32_bf16 v[0:3], v[178:181], v[210:213], v[0:3]
	v_mfma_f32_16x16x32_bf16 v[52:55], v[174:177], v[190:193], v[52:55]
	v_mfma_f32_16x16x32_bf16 v[48:51], v[182:185], v[190:193], v[48:51]
	v_mfma_f32_16x16x32_bf16 v[36:39], v[174:177], v[198:201], v[36:39]
	v_mfma_f32_16x16x32_bf16 v[32:35], v[182:185], v[198:201], v[32:35]
	v_mfma_f32_16x16x32_bf16 v[20:23], v[174:177], v[206:209], v[20:23]
	v_mfma_f32_16x16x32_bf16 v[16:19], v[182:185], v[206:209], v[16:19]
	v_mfma_f32_16x16x32_bf16 v[4:7], v[174:177], v[214:217], v[4:7]
	v_mfma_f32_16x16x32_bf16 v[0:3], v[182:185], v[214:217], v[0:3]
	s_barrier
	s_add_i32 s62, 0, 0x18000
	s_add_i32 s63, 0, 0x1c000
	v_add_u32_e32 v166, s62, v151
	v_add_u32_e32 v182, s63, v151
	ds_read_b128 v[146:149], v166
	ds_read_b128 v[158:161], v166 offset:1024
	ds_read_b128 v[162:165], v166 offset:2048
	ds_read_b128 v[166:169], v166 offset:3072
	ds_read_b128 v[170:173], v182
	ds_read_b128 v[174:177], v182 offset:1024
	ds_read_b128 v[178:181], v182 offset:2048
	ds_read_b128 v[182:185], v182 offset:3072
	s_add_u32 s36, s36, 0x80000
	s_addc_u32 s37, s37, 0
	s_mov_b32 m0, s50
	v_lshl_add_u64 v[226:227], s[36:37], 0, v[128:129]
	ds_read_b128 v[186:189], v155 offset:32768
	ds_read_b128 v[190:193], v155 offset:33792
	ds_read_b128 v[194:197], v155 offset:34816
	ds_read_b128 v[198:201], v155 offset:35840
	ds_read_b128 v[202:205], v155 offset:36864
	ds_read_b128 v[206:209], v155 offset:37888
	ds_read_b128 v[210:213], v155 offset:38912
	ds_read_b128 v[214:217], v155 offset:39936
	global_load_lds_dwordx4 v[226:227], off
	v_lshl_add_u64 v[226:227], s[36:37], 0, v[132:133]
	s_mov_b32 m0, s51
	s_nop 0
	global_load_lds_dwordx4 v[226:227], off
	s_waitcnt vmcnt(8)
	s_waitcnt lgkmcnt(0)
	s_barrier
	v_mfma_f32_16x16x32_bf16 v[124:127], v[146:149], v[186:189], v[124:127]
	v_mfma_f32_16x16x32_bf16 v[120:123], v[162:165], v[186:189], v[120:123]
	v_mfma_f32_16x16x32_bf16 v[108:111], v[146:149], v[194:197], v[108:111]
	v_mfma_f32_16x16x32_bf16 v[104:107], v[162:165], v[194:197], v[104:107]
	v_mfma_f32_16x16x32_bf16 v[92:95], v[146:149], v[202:205], v[92:95]
	v_mfma_f32_16x16x32_bf16 v[88:91], v[162:165], v[202:205], v[88:91]
	v_mfma_f32_16x16x32_bf16 v[76:79], v[146:149], v[210:213], v[76:79]
	v_mfma_f32_16x16x32_bf16 v[72:75], v[162:165], v[210:213], v[72:75]
	v_mfma_f32_16x16x32_bf16 v[124:127], v[158:161], v[190:193], v[124:127]
	v_mfma_f32_16x16x32_bf16 v[120:123], v[166:169], v[190:193], v[120:123]
	v_mfma_f32_16x16x32_bf16 v[108:111], v[158:161], v[198:201], v[108:111]
	v_mfma_f32_16x16x32_bf16 v[104:107], v[166:169], v[198:201], v[104:107]
	v_mfma_f32_16x16x32_bf16 v[92:95], v[158:161], v[206:209], v[92:95]
	v_mfma_f32_16x16x32_bf16 v[88:91], v[166:169], v[206:209], v[88:91]
	v_mfma_f32_16x16x32_bf16 v[76:79], v[158:161], v[214:217], v[76:79]
	v_mfma_f32_16x16x32_bf16 v[72:75], v[166:169], v[214:217], v[72:75]
	v_mfma_f32_16x16x32_bf16 v[116:119], v[170:173], v[186:189], v[116:119]
	v_mfma_f32_16x16x32_bf16 v[112:115], v[178:181], v[186:189], v[112:115]
	v_mfma_f32_16x16x32_bf16 v[100:103], v[170:173], v[194:197], v[100:103]
	v_mfma_f32_16x16x32_bf16 v[96:99], v[178:181], v[194:197], v[96:99]
	v_mfma_f32_16x16x32_bf16 v[84:87], v[170:173], v[202:205], v[84:87]
	v_mfma_f32_16x16x32_bf16 v[80:83], v[178:181], v[202:205], v[80:83]
	v_mfma_f32_16x16x32_bf16 v[68:71], v[170:173], v[210:213], v[68:71]
	v_mfma_f32_16x16x32_bf16 v[64:67], v[178:181], v[210:213], v[64:67]
	v_mfma_f32_16x16x32_bf16 v[116:119], v[174:177], v[190:193], v[116:119]
	v_mfma_f32_16x16x32_bf16 v[112:115], v[182:185], v[190:193], v[112:115]
	v_mfma_f32_16x16x32_bf16 v[100:103], v[174:177], v[198:201], v[100:103]
	v_mfma_f32_16x16x32_bf16 v[96:99], v[182:185], v[198:201], v[96:99]
	v_mfma_f32_16x16x32_bf16 v[84:87], v[174:177], v[206:209], v[84:87]
	v_mfma_f32_16x16x32_bf16 v[80:83], v[182:185], v[206:209], v[80:83]
	v_mfma_f32_16x16x32_bf16 v[68:71], v[174:177], v[214:217], v[68:71]
	v_mfma_f32_16x16x32_bf16 v[64:67], v[182:185], v[214:217], v[64:67]
	s_barrier
	s_add_i32 s36, s62, s48
	v_lshl_add_u64 v[218:219], v[218:219], 0, s[14:15]
	s_mov_b32 m0, s36
	ds_read_b128 v[186:189], v155 offset:49152
	ds_read_b128 v[190:193], v155 offset:50176
	ds_read_b128 v[194:197], v155 offset:51200
	ds_read_b128 v[198:201], v155 offset:52224
	ds_read_b128 v[202:205], v155 offset:53248
	ds_read_b128 v[206:209], v155 offset:54272
	ds_read_b128 v[210:213], v155 offset:55296
	ds_read_b128 v[214:217], v155 offset:56320
	global_load_lds_dwordx4 v[218:219], off
	s_add_i32 m0, s36, 0x2000
	s_add_u32 s34, s34, 0x80080
	v_lshl_add_u64 v[218:219], v[220:221], 0, s[14:15]
	s_addc_u32 s35, s35, 0
	s_add_i32 s36, s63, s48
	global_load_lds_dwordx4 v[218:219], off
	v_lshl_add_u64 v[218:219], s[34:35], 0, v[130:131]
	s_mov_b32 m0, s36
	s_nop 0
	global_load_lds_dwordx4 v[218:219], off
	v_lshl_add_u64 v[218:219], s[34:35], 0, v[134:135]
	s_add_i32 m0, s36, 0x2000
	s_nop 0
	global_load_lds_dwordx4 v[218:219], off
	v_lshl_add_u64 v[218:219], v[222:223], 0, s[14:15]
	s_mov_b32 m0, s53
	s_nop 0
	global_load_lds_dwordx4 v[218:219], off
	v_lshl_add_u64 v[218:219], v[224:225], 0, s[14:15]
	s_mov_b32 m0, s54
	s_nop 0
	global_load_lds_dwordx4 v[218:219], off
	s_waitcnt vmcnt(8)
	s_waitcnt lgkmcnt(0)
	s_barrier
	v_mfma_f32_16x16x32_bf16 v[60:63], v[146:149], v[186:189], v[60:63]
	v_mfma_f32_16x16x32_bf16 v[56:59], v[162:165], v[186:189], v[56:59]
	v_mfma_f32_16x16x32_bf16 v[44:47], v[146:149], v[194:197], v[44:47]
	v_mfma_f32_16x16x32_bf16 v[40:43], v[162:165], v[194:197], v[40:43]
	v_mfma_f32_16x16x32_bf16 v[28:31], v[146:149], v[202:205], v[28:31]
	v_mfma_f32_16x16x32_bf16 v[24:27], v[162:165], v[202:205], v[24:27]
	v_mfma_f32_16x16x32_bf16 v[12:15], v[146:149], v[210:213], v[12:15]
	v_mfma_f32_16x16x32_bf16 v[8:11], v[162:165], v[210:213], v[8:11]
	v_mfma_f32_16x16x32_bf16 v[60:63], v[158:161], v[190:193], v[60:63]
	v_mfma_f32_16x16x32_bf16 v[56:59], v[166:169], v[190:193], v[56:59]
	v_mfma_f32_16x16x32_bf16 v[44:47], v[158:161], v[198:201], v[44:47]
	v_mfma_f32_16x16x32_bf16 v[40:43], v[166:169], v[198:201], v[40:43]
	v_mfma_f32_16x16x32_bf16 v[28:31], v[158:161], v[206:209], v[28:31]
	v_mfma_f32_16x16x32_bf16 v[24:27], v[166:169], v[206:209], v[24:27]
	v_mfma_f32_16x16x32_bf16 v[12:15], v[158:161], v[214:217], v[12:15]
	v_mfma_f32_16x16x32_bf16 v[8:11], v[166:169], v[214:217], v[8:11]
	v_mfma_f32_16x16x32_bf16 v[52:55], v[170:173], v[186:189], v[52:55]
	v_mfma_f32_16x16x32_bf16 v[48:51], v[178:181], v[186:189], v[48:51]
	v_mfma_f32_16x16x32_bf16 v[36:39], v[170:173], v[194:197], v[36:39]
	v_mfma_f32_16x16x32_bf16 v[32:35], v[178:181], v[194:197], v[32:35]
	v_mfma_f32_16x16x32_bf16 v[20:23], v[170:173], v[202:205], v[20:23]
	v_mfma_f32_16x16x32_bf16 v[16:19], v[178:181], v[202:205], v[16:19]
	v_mfma_f32_16x16x32_bf16 v[4:7], v[170:173], v[210:213], v[4:7]
	v_mfma_f32_16x16x32_bf16 v[0:3], v[178:181], v[210:213], v[0:3]
	v_mfma_f32_16x16x32_bf16 v[52:55], v[174:177], v[190:193], v[52:55]
	v_mfma_f32_16x16x32_bf16 v[48:51], v[182:185], v[190:193], v[48:51]
	v_mfma_f32_16x16x32_bf16 v[36:39], v[174:177], v[198:201], v[36:39]
	v_mfma_f32_16x16x32_bf16 v[32:35], v[182:185], v[198:201], v[32:35]
	v_mfma_f32_16x16x32_bf16 v[20:23], v[174:177], v[206:209], v[20:23]
	v_mfma_f32_16x16x32_bf16 v[16:19], v[182:185], v[206:209], v[16:19]
	v_mfma_f32_16x16x32_bf16 v[4:7], v[174:177], v[214:217], v[4:7]
	v_mfma_f32_16x16x32_bf16 v[0:3], v[182:185], v[214:217], v[0:3]
	s_barrier
	s_add_i32 s61, s61, 2
	s_add_u32 s59, s59, 0x100
	s_addc_u32 s60, s60, 0
	s_add_u32 s30, s30, 0x100
	s_addc_u32 s31, s31, 0
	s_cmp_gt_u32 s61, 29
	s_cbranch_scc0 .LBB0_731
	s_and_b64 vcc, exec, s[16:17]
	s_cbranch_vccz .LBB0_734
	s_barrier

.LBB0_952:
	ds_read_b128 v[144:147], v151
	ds_read_b128 v[156:159], v151 offset:1024
	ds_read_b128 v[160:163], v151 offset:2048
	ds_read_b128 v[164:167], v151 offset:3072
	ds_read_b128 v[168:171], v152
	ds_read_b128 v[172:175], v152 offset:1024
	ds_read_b128 v[176:179], v152 offset:2048
	ds_read_b128 v[180:183], v152 offset:3072
	s_add_u32 s54, s52, 0xfff80080
	s_addc_u32 s55, s53, -1
	s_cmp_eq_u32 s68, 28
	s_cselect_b32 s57, s27, s55
	s_cselect_b32 s56, s37, s54
	s_cselect_b32 s55, s25, s67
	s_cselect_b32 s54, s46, s47
	v_lshl_add_u64 v[216:217], s[52:53], 0, v[138:139]
	s_add_i32 m0, s59, 0xc000
	ds_read_b128 v[184:187], v153
	ds_read_b128 v[188:191], v153 offset:1024
	ds_read_b128 v[192:195], v153 offset:2048
	ds_read_b128 v[196:199], v153 offset:3072
	ds_read_b128 v[200:203], v153 offset:4096
	ds_read_b128 v[204:207], v153 offset:5120
	ds_read_b128 v[208:211], v153 offset:6144
	ds_read_b128 v[212:215], v153 offset:7168
	global_load_lds_dwordx4 v[216:217], off
	v_lshl_add_u64 v[216:217], s[52:53], 0, v[136:137]
	s_add_i32 m0, s59, 0xe000
	s_nop 0
	global_load_lds_dwordx4 v[216:217], off
	s_waitcnt vmcnt(8)
	s_waitcnt lgkmcnt(0)
	s_barrier
	v_mfma_f32_16x16x32_bf16 v[116:119], v[144:147], v[184:187], v[116:119]
	v_mfma_f32_16x16x32_bf16 v[112:115], v[160:163], v[184:187], v[112:115]
	v_mfma_f32_16x16x32_bf16 v[104:107], v[144:147], v[192:195], v[104:107]
	v_mfma_f32_16x16x32_bf16 v[96:99], v[160:163], v[192:195], v[96:99]
	v_mfma_f32_16x16x32_bf16 v[88:91], v[144:147], v[200:203], v[88:91]
	v_mfma_f32_16x16x32_bf16 v[80:83], v[160:163], v[200:203], v[80:83]
	v_mfma_f32_16x16x32_bf16 v[72:75], v[144:147], v[208:211], v[72:75]
	v_mfma_f32_16x16x32_bf16 v[64:67], v[160:163], v[208:211], v[64:67]
	v_mfma_f32_16x16x32_bf16 v[116:119], v[156:159], v[188:191], v[116:119]
	v_mfma_f32_16x16x32_bf16 v[112:115], v[164:167], v[188:191], v[112:115]
	v_mfma_f32_16x16x32_bf16 v[104:107], v[156:159], v[196:199], v[104:107]
	v_mfma_f32_16x16x32_bf16 v[96:99], v[164:167], v[196:199], v[96:99]
	v_mfma_f32_16x16x32_bf16 v[88:91], v[156:159], v[204:207], v[88:91]
	v_mfma_f32_16x16x32_bf16 v[80:83], v[164:167], v[204:207], v[80:83]
	v_mfma_f32_16x16x32_bf16 v[72:75], v[156:159], v[212:215], v[72:75]
	v_mfma_f32_16x16x32_bf16 v[64:67], v[164:167], v[212:215], v[64:67]
	v_mfma_f32_16x16x32_bf16 v[124:127], v[168:171], v[184:187], v[124:127]
	v_mfma_f32_16x16x32_bf16 v[120:123], v[176:179], v[184:187], v[120:123]
	v_mfma_f32_16x16x32_bf16 v[108:111], v[168:171], v[192:195], v[108:111]
	v_mfma_f32_16x16x32_bf16 v[100:103], v[176:179], v[192:195], v[100:103]
	v_mfma_f32_16x16x32_bf16 v[92:95], v[168:171], v[200:203], v[92:95]
	v_mfma_f32_16x16x32_bf16 v[84:87], v[176:179], v[200:203], v[84:87]
	v_mfma_f32_16x16x32_bf16 v[76:79], v[168:171], v[208:211], v[76:79]
	v_mfma_f32_16x16x32_bf16 v[68:71], v[176:179], v[208:211], v[68:71]
	v_mfma_f32_16x16x32_bf16 v[124:127], v[172:175], v[188:191], v[124:127]
	v_mfma_f32_16x16x32_bf16 v[120:123], v[180:183], v[188:191], v[120:123]
	v_mfma_f32_16x16x32_bf16 v[108:111], v[172:175], v[196:199], v[108:111]
	v_mfma_f32_16x16x32_bf16 v[100:103], v[180:183], v[196:199], v[100:103]
	v_mfma_f32_16x16x32_bf16 v[92:95], v[172:175], v[204:207], v[92:95]
	v_mfma_f32_16x16x32_bf16 v[84:87], v[180:183], v[204:207], v[84:87]
	v_mfma_f32_16x16x32_bf16 v[76:79], v[172:175], v[212:215], v[76:79]
	v_mfma_f32_16x16x32_bf16 v[68:71], v[180:183], v[212:215], v[68:71]
	s_barrier
	s_add_i32 s69, s64, s58
	v_lshl_add_u64 v[216:217], s[54:55], 0, v[130:131]
	s_mov_b32 m0, s69
	ds_read_b128 v[184:187], v153 offset:16384
	ds_read_b128 v[188:191], v153 offset:17408
	ds_read_b128 v[192:195], v153 offset:18432
	ds_read_b128 v[196:199], v153 offset:19456
	ds_read_b128 v[200:203], v153 offset:20480
	ds_read_b128 v[204:207], v153 offset:21504
	ds_read_b128 v[208:211], v153 offset:22528
	ds_read_b128 v[212:215], v153 offset:23552
	global_load_lds_dwordx4 v[216:217], off
	s_add_i32 m0, s69, 0x2000
	s_add_u32 s70, s54, 0x80000
	v_lshl_add_u64 v[218:219], s[54:55], 0, v[134:135]
	s_addc_u32 s71, s55, 0
	s_add_i32 s69, s65, s58
	global_load_lds_dwordx4 v[218:219], off
	v_lshl_add_u64 v[220:221], s[70:71], 0, v[130:131]
	s_mov_b32 m0, s69
	v_lshl_add_u64 v[222:223], s[56:57], 0, v[132:133]
	global_load_lds_dwordx4 v[220:221], off
	v_lshl_add_u64 v[220:221], s[70:71], 0, v[134:135]
	s_add_i32 m0, s69, 0x2000
	s_nop 0
	global_load_lds_dwordx4 v[220:221], off
	v_lshl_add_u64 v[220:221], s[56:57], 0, v[128:129]
	s_mov_b32 m0, s59
	s_nop 0
	global_load_lds_dwordx4 v[220:221], off
	s_mov_b32 m0, s50
	s_nop 0
	global_load_lds_dwordx4 v[222:223], off
	s_waitcnt vmcnt(8)
	s_waitcnt lgkmcnt(0)
	s_barrier
	v_mfma_f32_16x16x32_bf16 v[56:59], v[144:147], v[184:187], v[56:59]
	v_mfma_f32_16x16x32_bf16 v[48:51], v[160:163], v[184:187], v[48:51]
	v_mfma_f32_16x16x32_bf16 v[40:43], v[144:147], v[192:195], v[40:43]
	v_mfma_f32_16x16x32_bf16 v[32:35], v[160:163], v[192:195], v[32:35]
	v_mfma_f32_16x16x32_bf16 v[24:27], v[144:147], v[200:203], v[24:27]
	v_mfma_f32_16x16x32_bf16 v[16:19], v[160:163], v[200:203], v[16:19]
	v_mfma_f32_16x16x32_bf16 v[8:11], v[144:147], v[208:211], v[8:11]
	v_mfma_f32_16x16x32_bf16 v[0:3], v[160:163], v[208:211], v[0:3]
	v_mfma_f32_16x16x32_bf16 v[56:59], v[156:159], v[188:191], v[56:59]
	v_mfma_f32_16x16x32_bf16 v[48:51], v[164:167], v[188:191], v[48:51]
	v_mfma_f32_16x16x32_bf16 v[40:43], v[156:159], v[196:199], v[40:43]
	v_mfma_f32_16x16x32_bf16 v[32:35], v[164:167], v[196:199], v[32:35]
	v_mfma_f32_16x16x32_bf16 v[24:27], v[156:159], v[204:207], v[24:27]
	v_mfma_f32_16x16x32_bf16 v[16:19], v[164:167], v[204:207], v[16:19]
	v_mfma_f32_16x16x32_bf16 v[8:11], v[156:159], v[212:215], v[8:11]
	v_mfma_f32_16x16x32_bf16 v[0:3], v[164:167], v[212:215], v[0:3]
	v_mfma_f32_16x16x32_bf16 v[60:63], v[168:171], v[184:187], v[60:63]
	v_mfma_f32_16x16x32_bf16 v[52:55], v[176:179], v[184:187], v[52:55]
	v_mfma_f32_16x16x32_bf16 v[44:47], v[168:171], v[192:195], v[44:47]
	v_mfma_f32_16x16x32_bf16 v[36:39], v[176:179], v[192:195], v[36:39]
	v_mfma_f32_16x16x32_bf16 v[28:31], v[168:171], v[200:203], v[28:31]
	v_mfma_f32_16x16x32_bf16 v[20:23], v[176:179], v[200:203], v[20:23]
	v_mfma_f32_16x16x32_bf16 v[12:15], v[168:171], v[208:211], v[12:15]
	v_mfma_f32_16x16x32_bf16 v[4:7], v[176:179], v[208:211], v[4:7]
	v_mfma_f32_16x16x32_bf16 v[60:63], v[172:175], v[188:191], v[60:63]
	v_mfma_f32_16x16x32_bf16 v[52:55], v[180:183], v[188:191], v[52:55]
	v_mfma_f32_16x16x32_bf16 v[44:47], v[172:175], v[196:199], v[44:47]
	v_mfma_f32_16x16x32_bf16 v[36:39], v[180:183], v[196:199], v[36:39]
	v_mfma_f32_16x16x32_bf16 v[28:31], v[172:175], v[204:207], v[28:31]
	v_mfma_f32_16x16x32_bf16 v[20:23], v[180:183], v[204:207], v[20:23]
	v_mfma_f32_16x16x32_bf16 v[12:15], v[172:175], v[212:215], v[12:15]
	v_mfma_f32_16x16x32_bf16 v[4:7], v[180:183], v[212:215], v[4:7]
	s_barrier
	s_add_i32 s69, 0, 0x18000
	v_add_u32_e32 v155, s69, v149
	s_add_i32 s70, 0, 0x1c000
	ds_read_b128 v[144:147], v155
	ds_read_b128 v[156:159], v155 offset:1024
	ds_read_b128 v[160:163], v155 offset:2048
	ds_read_b128 v[164:167], v155 offset:3072
	v_add_u32_e32 v155, s70, v149
	ds_read_b128 v[168:171], v155
	ds_read_b128 v[172:175], v155 offset:1024
	ds_read_b128 v[176:179], v155 offset:2048
	ds_read_b128 v[180:183], v155 offset:3072
	s_add_u32 s56, s56, 0x80000
	s_addc_u32 s57, s57, 0
	s_mov_b32 m0, s51
	v_lshl_add_u64 v[224:225], s[56:57], 0, v[128:129]
	ds_read_b128 v[184:187], v153 offset:32768
	ds_read_b128 v[188:191], v153 offset:33792
	ds_read_b128 v[192:195], v153 offset:34816
	ds_read_b128 v[196:199], v153 offset:35840
	ds_read_b128 v[200:203], v153 offset:36864
	ds_read_b128 v[204:207], v153 offset:37888
	ds_read_b128 v[208:211], v153 offset:38912
	ds_read_b128 v[212:215], v153 offset:39936
	global_load_lds_dwordx4 v[224:225], off
	v_lshl_add_u64 v[224:225], s[56:57], 0, v[132:133]
	s_mov_b32 m0, s60
	s_nop 0
	global_load_lds_dwordx4 v[224:225], off
	s_waitcnt vmcnt(8)
	s_waitcnt lgkmcnt(0)
	s_barrier
	v_mfma_f32_16x16x32_bf16 v[116:119], v[144:147], v[184:187], v[116:119]
	v_mfma_f32_16x16x32_bf16 v[112:115], v[160:163], v[184:187], v[112:115]
	v_mfma_f32_16x16x32_bf16 v[104:107], v[144:147], v[192:195], v[104:107]
	v_mfma_f32_16x16x32_bf16 v[96:99], v[160:163], v[192:195], v[96:99]
	v_mfma_f32_16x16x32_bf16 v[88:91], v[144:147], v[200:203], v[88:91]
	v_mfma_f32_16x16x32_bf16 v[80:83], v[160:163], v[200:203], v[80:83]
	v_mfma_f32_16x16x32_bf16 v[72:75], v[144:147], v[208:211], v[72:75]
	v_mfma_f32_16x16x32_bf16 v[64:67], v[160:163], v[208:211], v[64:67]
	v_mfma_f32_16x16x32_bf16 v[116:119], v[156:159], v[188:191], v[116:119]
	v_mfma_f32_16x16x32_bf16 v[112:115], v[164:167], v[188:191], v[112:115]
	v_mfma_f32_16x16x32_bf16 v[104:107], v[156:159], v[196:199], v[104:107]
	v_mfma_f32_16x16x32_bf16 v[96:99], v[164:167], v[196:199], v[96:99]
	v_mfma_f32_16x16x32_bf16 v[88:91], v[156:159], v[204:207], v[88:91]
	v_mfma_f32_16x16x32_bf16 v[80:83], v[164:167], v[204:207], v[80:83]
	v_mfma_f32_16x16x32_bf16 v[72:75], v[156:159], v[212:215], v[72:75]
	v_mfma_f32_16x16x32_bf16 v[64:67], v[164:167], v[212:215], v[64:67]
	v_mfma_f32_16x16x32_bf16 v[124:127], v[168:171], v[184:187], v[124:127]
	v_mfma_f32_16x16x32_bf16 v[120:123], v[176:179], v[184:187], v[120:123]
	v_mfma_f32_16x16x32_bf16 v[108:111], v[168:171], v[192:195], v[108:111]
	v_mfma_f32_16x16x32_bf16 v[100:103], v[176:179], v[192:195], v[100:103]
	v_mfma_f32_16x16x32_bf16 v[92:95], v[168:171], v[200:203], v[92:95]
	v_mfma_f32_16x16x32_bf16 v[84:87], v[176:179], v[200:203], v[84:87]
	v_mfma_f32_16x16x32_bf16 v[76:79], v[168:171], v[208:211], v[76:79]
	v_mfma_f32_16x16x32_bf16 v[68:71], v[176:179], v[208:211], v[68:71]
	v_mfma_f32_16x16x32_bf16 v[124:127], v[172:175], v[188:191], v[124:127]
	v_mfma_f32_16x16x32_bf16 v[120:123], v[180:183], v[188:191], v[120:123]
	v_mfma_f32_16x16x32_bf16 v[108:111], v[172:175], v[196:199], v[108:111]
	v_mfma_f32_16x16x32_bf16 v[100:103], v[180:183], v[196:199], v[100:103]
	v_mfma_f32_16x16x32_bf16 v[92:95], v[172:175], v[204:207], v[92:95]
	v_mfma_f32_16x16x32_bf16 v[84:87], v[180:183], v[204:207], v[84:87]
	v_mfma_f32_16x16x32_bf16 v[76:79], v[172:175], v[212:215], v[76:79]
	v_mfma_f32_16x16x32_bf16 v[68:71], v[180:183], v[212:215], v[68:71]
	s_barrier
	s_add_i32 s56, s69, s58
	v_lshl_add_u64 v[216:217], v[216:217], 0, s[20:21]
	s_mov_b32 m0, s56
	ds_read_b128 v[184:187], v153 offset:49152
	ds_read_b128 v[188:191], v153 offset:50176
	ds_read_b128 v[192:195], v153 offset:51200
	ds_read_b128 v[196:199], v153 offset:52224
	ds_read_b128 v[200:203], v153 offset:53248
	ds_read_b128 v[204:207], v153 offset:54272
	ds_read_b128 v[208:211], v153 offset:55296
	ds_read_b128 v[212:215], v153 offset:56320
	global_load_lds_dwordx4 v[216:217], off
	s_add_i32 m0, s56, 0x2000
	s_add_u32 s54, s54, 0x80080
	v_lshl_add_u64 v[216:217], v[218:219], 0, s[20:21]
	s_addc_u32 s55, s55, 0
	s_add_i32 s56, s70, s58
	global_load_lds_dwordx4 v[216:217], off
	v_lshl_add_u64 v[216:217], s[54:55], 0, v[130:131]
	s_mov_b32 m0, s56
	s_nop 0
	global_load_lds_dwordx4 v[216:217], off
	v_lshl_add_u64 v[216:217], s[54:55], 0, v[134:135]
	s_add_i32 m0, s56, 0x2000
	s_nop 0
	global_load_lds_dwordx4 v[216:217], off
	v_lshl_add_u64 v[216:217], v[220:221], 0, s[20:21]
	s_mov_b32 m0, s62
	s_nop 0
	global_load_lds_dwordx4 v[216:217], off
	v_lshl_add_u64 v[216:217], v[222:223], 0, s[20:21]
	s_mov_b32 m0, s63
	s_nop 0
	global_load_lds_dwordx4 v[216:217], off
	s_waitcnt vmcnt(8)
	s_waitcnt lgkmcnt(0)
	s_barrier
	v_mfma_f32_16x16x32_bf16 v[56:59], v[144:147], v[184:187], v[56:59]
	v_mfma_f32_16x16x32_bf16 v[48:51], v[160:163], v[184:187], v[48:51]
	v_mfma_f32_16x16x32_bf16 v[40:43], v[144:147], v[192:195], v[40:43]
	v_mfma_f32_16x16x32_bf16 v[32:35], v[160:163], v[192:195], v[32:35]
	v_mfma_f32_16x16x32_bf16 v[24:27], v[144:147], v[200:203], v[24:27]
	v_mfma_f32_16x16x32_bf16 v[16:19], v[160:163], v[200:203], v[16:19]
	v_mfma_f32_16x16x32_bf16 v[8:11], v[144:147], v[208:211], v[8:11]
	v_mfma_f32_16x16x32_bf16 v[0:3], v[160:163], v[208:211], v[0:3]
	v_mfma_f32_16x16x32_bf16 v[56:59], v[156:159], v[188:191], v[56:59]
	v_mfma_f32_16x16x32_bf16 v[48:51], v[164:167], v[188:191], v[48:51]
	v_mfma_f32_16x16x32_bf16 v[40:43], v[156:159], v[196:199], v[40:43]
	v_mfma_f32_16x16x32_bf16 v[32:35], v[164:167], v[196:199], v[32:35]
	v_mfma_f32_16x16x32_bf16 v[24:27], v[156:159], v[204:207], v[24:27]
	v_mfma_f32_16x16x32_bf16 v[16:19], v[164:167], v[204:207], v[16:19]
	v_mfma_f32_16x16x32_bf16 v[8:11], v[156:159], v[212:215], v[8:11]
	v_mfma_f32_16x16x32_bf16 v[0:3], v[164:167], v[212:215], v[0:3]
	v_mfma_f32_16x16x32_bf16 v[60:63], v[168:171], v[184:187], v[60:63]
	v_mfma_f32_16x16x32_bf16 v[52:55], v[176:179], v[184:187], v[52:55]
	v_mfma_f32_16x16x32_bf16 v[44:47], v[168:171], v[192:195], v[44:47]
	v_mfma_f32_16x16x32_bf16 v[36:39], v[176:179], v[192:195], v[36:39]
	v_mfma_f32_16x16x32_bf16 v[28:31], v[168:171], v[200:203], v[28:31]
	v_mfma_f32_16x16x32_bf16 v[20:23], v[176:179], v[200:203], v[20:23]
	v_mfma_f32_16x16x32_bf16 v[12:15], v[168:171], v[208:211], v[12:15]
	v_mfma_f32_16x16x32_bf16 v[4:7], v[176:179], v[208:211], v[4:7]
	v_mfma_f32_16x16x32_bf16 v[60:63], v[172:175], v[188:191], v[60:63]
	v_mfma_f32_16x16x32_bf16 v[52:55], v[180:183], v[188:191], v[52:55]
	v_mfma_f32_16x16x32_bf16 v[44:47], v[172:175], v[196:199], v[44:47]
	v_mfma_f32_16x16x32_bf16 v[36:39], v[180:183], v[196:199], v[36:39]
	v_mfma_f32_16x16x32_bf16 v[28:31], v[172:175], v[204:207], v[28:31]
	v_mfma_f32_16x16x32_bf16 v[20:23], v[180:183], v[204:207], v[20:23]
	v_mfma_f32_16x16x32_bf16 v[12:15], v[172:175], v[212:215], v[12:15]
	v_mfma_f32_16x16x32_bf16 v[4:7], v[180:183], v[212:215], v[4:7]
	s_barrier
	s_add_i32 s68, s68, 2
	s_add_u32 s47, s47, 0x100
	s_addc_u32 s67, s67, 0
	s_add_u32 s52, s52, 0x100
	s_addc_u32 s53, s53, 0
	s_cmp_gt_u32 s68, 29
	s_cbranch_scc0 .LBB0_952
	s_and_b64 vcc, exec, s[22:23]
	s_cbranch_vccz .LBB0_955
	s_barrier

.LBB0_1049:
	ds_read_b128 v[148:151], v222
	ds_read_b128 v[152:155], v222 offset:1024
	ds_read_b128 v[156:159], v222 offset:2048
	ds_read_b128 v[160:163], v222 offset:3072
	ds_read_b128 v[132:135], v223
	ds_read_b128 v[136:139], v223 offset:1024
	ds_read_b128 v[140:143], v223 offset:2048
	ds_read_b128 v[144:147], v223 offset:3072
	s_add_u32 s8, s48, 0xfff80080
	s_addc_u32 s9, s49, -1
	s_cmp_eq_u32 s81, 28
	s_cselect_b32 s53, s23, s9
	s_cselect_b32 s52, s46, s8
	s_cselect_b32 s51, s21, s80
	s_cselect_b32 s50, s47, s79
	v_lshl_add_u64 v[2:3], s[48:49], 0, v[208:209]
	s_add_i32 m0, s35, 0xc000
	s_waitcnt lgkmcnt(0)
	ds_read_b128 v[164:167], v224
	ds_read_b128 v[168:171], v224 offset:1024
	ds_read_b128 v[172:175], v224 offset:2048
	ds_read_b128 v[176:179], v224 offset:3072
	ds_read_b128 v[180:183], v224 offset:4096
	ds_read_b128 v[184:187], v224 offset:5120
	ds_read_b128 v[188:191], v224 offset:6144
	ds_read_b128 v[192:195], v224 offset:7168
	global_load_lds_dwordx4 v[2:3], off
	v_lshl_add_u64 v[2:3], s[48:49], 0, v[206:207]
	s_add_i32 m0, s35, 0xe000
	s_nop 0
	global_load_lds_dwordx4 v[2:3], off
	s_waitcnt vmcnt(8)
	s_waitcnt lgkmcnt(0)
	s_barrier
	v_mfma_f32_16x16x32_bf16 v[124:127], v[148:151], v[164:167], v[124:127]
	v_mfma_f32_16x16x32_bf16 v[120:123], v[156:159], v[164:167], v[120:123]
	v_mfma_f32_16x16x32_bf16 v[104:107], v[148:151], v[172:175], v[104:107]
	v_mfma_f32_16x16x32_bf16 v[100:103], v[156:159], v[172:175], v[100:103]
	v_mfma_f32_16x16x32_bf16 v[88:91], v[148:151], v[180:183], v[88:91]
	v_mfma_f32_16x16x32_bf16 v[84:87], v[156:159], v[180:183], v[84:87]
	v_mfma_f32_16x16x32_bf16 v[76:79], v[148:151], v[188:191], v[76:79]
	v_mfma_f32_16x16x32_bf16 v[72:75], v[156:159], v[188:191], v[72:75]
	v_mfma_f32_16x16x32_bf16 v[124:127], v[152:155], v[168:171], v[124:127]
	v_mfma_f32_16x16x32_bf16 v[120:123], v[160:163], v[168:171], v[120:123]
	v_mfma_f32_16x16x32_bf16 v[104:107], v[152:155], v[176:179], v[104:107]
	v_mfma_f32_16x16x32_bf16 v[100:103], v[160:163], v[176:179], v[100:103]
	v_mfma_f32_16x16x32_bf16 v[88:91], v[152:155], v[184:187], v[88:91]
	v_mfma_f32_16x16x32_bf16 v[84:87], v[160:163], v[184:187], v[84:87]
	v_mfma_f32_16x16x32_bf16 v[76:79], v[152:155], v[192:195], v[76:79]
	v_mfma_f32_16x16x32_bf16 v[72:75], v[160:163], v[192:195], v[72:75]
	v_mfma_f32_16x16x32_bf16 v[128:131], v[132:135], v[164:167], v[128:131]
	v_mfma_f32_16x16x32_bf16 v[116:119], v[140:143], v[164:167], v[116:119]
	v_mfma_f32_16x16x32_bf16 v[112:115], v[132:135], v[172:175], v[112:115]
	v_mfma_f32_16x16x32_bf16 v[108:111], v[140:143], v[172:175], v[108:111]
	v_mfma_f32_16x16x32_bf16 v[96:99], v[132:135], v[180:183], v[96:99]
	v_mfma_f32_16x16x32_bf16 v[92:95], v[140:143], v[180:183], v[92:95]
	v_mfma_f32_16x16x32_bf16 v[80:83], v[132:135], v[188:191], v[80:83]
	v_mfma_f32_16x16x32_bf16 v[68:71], v[140:143], v[188:191], v[68:71]
	v_mfma_f32_16x16x32_bf16 v[128:131], v[136:139], v[168:171], v[128:131]
	v_mfma_f32_16x16x32_bf16 v[116:119], v[144:147], v[168:171], v[116:119]
	v_mfma_f32_16x16x32_bf16 v[112:115], v[136:139], v[176:179], v[112:115]
	v_mfma_f32_16x16x32_bf16 v[108:111], v[144:147], v[176:179], v[108:111]
	v_mfma_f32_16x16x32_bf16 v[96:99], v[136:139], v[184:187], v[96:99]
	v_mfma_f32_16x16x32_bf16 v[92:95], v[144:147], v[184:187], v[92:95]
	v_mfma_f32_16x16x32_bf16 v[80:83], v[136:139], v[192:195], v[80:83]
	v_mfma_f32_16x16x32_bf16 v[68:71], v[144:147], v[192:195], v[68:71]
	s_barrier
	s_add_i32 s8, s65, s56
	v_lshl_add_u64 v[2:3], s[50:51], 0, v[198:199]
	s_mov_b32 m0, s8
	ds_read_b128 v[188:191], v224 offset:16384
	ds_read_b128 v[192:195], v224 offset:17408
	ds_read_b128 v[180:183], v224 offset:18432
	ds_read_b128 v[184:187], v224 offset:19456
	ds_read_b128 v[172:175], v224 offset:20480
	ds_read_b128 v[176:179], v224 offset:21504
	ds_read_b128 v[164:167], v224 offset:22528
	ds_read_b128 v[168:171], v224 offset:23552
	global_load_lds_dwordx4 v[2:3], off
	s_add_i32 m0, s8, 0x2000
	s_add_u32 s8, s50, 0x80000
	v_lshl_add_u64 v[212:213], s[50:51], 0, v[202:203]
	s_addc_u32 s9, s51, 0
	s_add_i32 s78, s66, s56
	global_load_lds_dwordx4 v[212:213], off
	v_lshl_add_u64 v[214:215], s[8:9], 0, v[198:199]
	s_mov_b32 m0, s78
	v_lshl_add_u64 v[216:217], s[52:53], 0, v[200:201]
	global_load_lds_dwordx4 v[214:215], off
	v_lshl_add_u64 v[214:215], s[8:9], 0, v[202:203]
	s_add_i32 m0, s78, 0x2000
	v_cmp_ne_u32_e64 s[8:9], 1, v227
	global_load_lds_dwordx4 v[214:215], off
	v_lshl_add_u64 v[214:215], s[52:53], 0, v[196:197]
	s_mov_b32 m0, s35
	s_andn2_b64 vcc, exec, s[36:37]
	global_load_lds_dwordx4 v[214:215], off
	s_mov_b32 m0, s58
	s_nop 0
	global_load_lds_dwordx4 v[216:217], off
	s_waitcnt vmcnt(8)
	s_waitcnt lgkmcnt(0)
	s_cbranch_vccnz .Lsegskip_2
	s_barrier
	v_mfma_f32_16x16x32_bf16 v[56:59], v[148:151], v[188:191], v[56:59]
	v_mfma_f32_16x16x32_bf16 v[52:55], v[156:159], v[188:191], v[52:55]
	v_mfma_f32_16x16x32_bf16 v[40:43], v[148:151], v[180:183], v[40:43]
	v_mfma_f32_16x16x32_bf16 v[36:39], v[156:159], v[180:183], v[36:39]
	v_mfma_f32_16x16x32_bf16 v[24:27], v[148:151], v[172:175], v[24:27]
	v_mfma_f32_16x16x32_bf16 v[20:23], v[156:159], v[172:175], v[20:23]
	v_mfma_f32_16x16x32_bf16 v[8:11], v[148:151], v[164:167], v[8:11]
	v_mfma_f32_16x16x32_bf16 v[4:7], v[156:159], v[164:167], v[4:7]
	v_mfma_f32_16x16x32_bf16 v[56:59], v[152:155], v[192:195], v[56:59]
	v_mfma_f32_16x16x32_bf16 v[52:55], v[160:163], v[192:195], v[52:55]
	v_mfma_f32_16x16x32_bf16 v[40:43], v[152:155], v[184:187], v[40:43]
	v_mfma_f32_16x16x32_bf16 v[36:39], v[160:163], v[184:187], v[36:39]
	v_mfma_f32_16x16x32_bf16 v[24:27], v[152:155], v[176:179], v[24:27]
	v_mfma_f32_16x16x32_bf16 v[20:23], v[160:163], v[176:179], v[20:23]
	v_mfma_f32_16x16x32_bf16 v[8:11], v[152:155], v[168:171], v[8:11]
	v_mfma_f32_16x16x32_bf16 v[4:7], v[160:163], v[168:171], v[4:7]
	v_mfma_f32_16x16x32_bf16 v[64:67], v[132:135], v[188:191], v[64:67]
	v_mfma_f32_16x16x32_bf16 v[60:63], v[140:143], v[188:191], v[60:63]
	v_mfma_f32_16x16x32_bf16 v[48:51], v[132:135], v[180:183], v[48:51]
	v_mfma_f32_16x16x32_bf16 v[44:47], v[140:143], v[180:183], v[44:47]
	v_mfma_f32_16x16x32_bf16 v[32:35], v[132:135], v[172:175], v[32:35]
	v_mfma_f32_16x16x32_bf16 v[28:31], v[140:143], v[172:175], v[28:31]
	v_mfma_f32_16x16x32_bf16 v[16:19], v[132:135], v[164:167], v[16:19]
	v_mfma_f32_16x16x32_bf16 v[12:15], v[140:143], v[164:167], v[12:15]
	v_mfma_f32_16x16x32_bf16 v[64:67], v[136:139], v[192:195], v[64:67]
	v_mfma_f32_16x16x32_bf16 v[60:63], v[144:147], v[192:195], v[60:63]
	v_mfma_f32_16x16x32_bf16 v[48:51], v[136:139], v[184:187], v[48:51]
	v_mfma_f32_16x16x32_bf16 v[44:47], v[144:147], v[184:187], v[44:47]
	v_mfma_f32_16x16x32_bf16 v[32:35], v[136:139], v[176:179], v[32:35]
	v_mfma_f32_16x16x32_bf16 v[28:31], v[144:147], v[176:179], v[28:31]
	v_mfma_f32_16x16x32_bf16 v[16:19], v[136:139], v[168:171], v[16:19]
	v_mfma_f32_16x16x32_bf16 v[12:15], v[144:147], v[168:171], v[12:15]
.LBB0_1051:
	s_barrier
	s_add_i32 s78, 0, 0x18000
	v_add_u32_e32 v1, s78, v220
	s_add_i32 s82, 0, 0x1c000
	ds_read_b128 v[148:151], v1
	ds_read_b128 v[152:155], v1 offset:1024
	ds_read_b128 v[156:159], v1 offset:2048
	ds_read_b128 v[160:163], v1 offset:3072
	v_add_u32_e32 v1, s82, v220
	ds_read_b128 v[132:135], v1
	ds_read_b128 v[136:139], v1 offset:1024
	ds_read_b128 v[140:143], v1 offset:2048
	ds_read_b128 v[144:147], v1 offset:3072
	s_add_u32 s52, s52, 0x80000
	s_addc_u32 s53, s53, 0
	s_mov_b32 m0, s59
	v_lshl_add_u64 v[228:229], s[52:53], 0, v[196:197]
	s_waitcnt lgkmcnt(0)
	ds_read_b128 v[164:167], v224 offset:32768
	ds_read_b128 v[168:171], v224 offset:33792
	ds_read_b128 v[172:175], v224 offset:34816
	ds_read_b128 v[176:179], v224 offset:35840
	ds_read_b128 v[180:183], v224 offset:36864
	ds_read_b128 v[184:187], v224 offset:37888
	ds_read_b128 v[188:191], v224 offset:38912
	ds_read_b128 v[192:195], v224 offset:39936
	global_load_lds_dwordx4 v[228:229], off
	v_lshl_add_u64 v[228:229], s[52:53], 0, v[200:201]
	s_mov_b32 m0, s60
	s_nop 0
	global_load_lds_dwordx4 v[228:229], off
	s_waitcnt vmcnt(8)
	s_waitcnt lgkmcnt(0)
	s_barrier
	v_mfma_f32_16x16x32_bf16 v[124:127], v[148:151], v[164:167], v[124:127]
	v_mfma_f32_16x16x32_bf16 v[120:123], v[156:159], v[164:167], v[120:123]
	v_mfma_f32_16x16x32_bf16 v[104:107], v[148:151], v[172:175], v[104:107]
	v_mfma_f32_16x16x32_bf16 v[100:103], v[156:159], v[172:175], v[100:103]
	v_mfma_f32_16x16x32_bf16 v[88:91], v[148:151], v[180:183], v[88:91]
	v_mfma_f32_16x16x32_bf16 v[84:87], v[156:159], v[180:183], v[84:87]
	v_mfma_f32_16x16x32_bf16 v[76:79], v[148:151], v[188:191], v[76:79]
	v_mfma_f32_16x16x32_bf16 v[72:75], v[156:159], v[188:191], v[72:75]
	v_mfma_f32_16x16x32_bf16 v[124:127], v[152:155], v[168:171], v[124:127]
	v_mfma_f32_16x16x32_bf16 v[120:123], v[160:163], v[168:171], v[120:123]
	v_mfma_f32_16x16x32_bf16 v[104:107], v[152:155], v[176:179], v[104:107]
	v_mfma_f32_16x16x32_bf16 v[100:103], v[160:163], v[176:179], v[100:103]
	v_mfma_f32_16x16x32_bf16 v[88:91], v[152:155], v[184:187], v[88:91]
	v_mfma_f32_16x16x32_bf16 v[84:87], v[160:163], v[184:187], v[84:87]
	v_mfma_f32_16x16x32_bf16 v[76:79], v[152:155], v[192:195], v[76:79]
	v_mfma_f32_16x16x32_bf16 v[72:75], v[160:163], v[192:195], v[72:75]
	v_mfma_f32_16x16x32_bf16 v[128:131], v[132:135], v[164:167], v[128:131]
	v_mfma_f32_16x16x32_bf16 v[116:119], v[140:143], v[164:167], v[116:119]
	v_mfma_f32_16x16x32_bf16 v[112:115], v[132:135], v[172:175], v[112:115]
	v_mfma_f32_16x16x32_bf16 v[108:111], v[140:143], v[172:175], v[108:111]
	v_mfma_f32_16x16x32_bf16 v[96:99], v[132:135], v[180:183], v[96:99]
	v_mfma_f32_16x16x32_bf16 v[92:95], v[140:143], v[180:183], v[92:95]
	v_mfma_f32_16x16x32_bf16 v[80:83], v[132:135], v[188:191], v[80:83]
	v_mfma_f32_16x16x32_bf16 v[68:71], v[140:143], v[188:191], v[68:71]
	v_mfma_f32_16x16x32_bf16 v[128:131], v[136:139], v[168:171], v[128:131]
	v_mfma_f32_16x16x32_bf16 v[116:119], v[144:147], v[168:171], v[116:119]
	v_mfma_f32_16x16x32_bf16 v[112:115], v[136:139], v[176:179], v[112:115]
	v_mfma_f32_16x16x32_bf16 v[108:111], v[144:147], v[176:179], v[108:111]
	v_mfma_f32_16x16x32_bf16 v[96:99], v[136:139], v[184:187], v[96:99]
	v_mfma_f32_16x16x32_bf16 v[92:95], v[144:147], v[184:187], v[92:95]
	v_mfma_f32_16x16x32_bf16 v[80:83], v[136:139], v[192:195], v[80:83]
	v_mfma_f32_16x16x32_bf16 v[68:71], v[144:147], v[192:195], v[68:71]
	s_barrier
	s_add_i32 s52, s78, s56
	v_lshl_add_u64 v[2:3], v[2:3], 0, s[14:15]
	s_mov_b32 m0, s52
	ds_read_b128 v[188:191], v224 offset:49152
	ds_read_b128 v[192:195], v224 offset:50176
	ds_read_b128 v[180:183], v224 offset:51200
	ds_read_b128 v[184:187], v224 offset:52224
	ds_read_b128 v[172:175], v224 offset:53248
	ds_read_b128 v[176:179], v224 offset:54272
	ds_read_b128 v[164:167], v224 offset:55296
	ds_read_b128 v[168:171], v224 offset:56320
	global_load_lds_dwordx4 v[2:3], off
	s_add_i32 m0, s52, 0x2000
	s_add_u32 s50, s50, 0x80080
	v_lshl_add_u64 v[2:3], v[212:213], 0, s[14:15]
	s_addc_u32 s51, s51, 0
	s_add_i32 s52, s82, s56
	global_load_lds_dwordx4 v[2:3], off
	v_lshl_add_u64 v[2:3], s[50:51], 0, v[198:199]
	s_mov_b32 m0, s52
	s_and_b64 vcc, exec, s[8:9]
	global_load_lds_dwordx4 v[2:3], off
	v_lshl_add_u64 v[2:3], s[50:51], 0, v[202:203]
	s_add_i32 m0, s52, 0x2000
	s_nop 0
	global_load_lds_dwordx4 v[2:3], off
	v_lshl_add_u64 v[2:3], v[214:215], 0, s[14:15]
	s_mov_b32 m0, s61
	s_nop 0
	global_load_lds_dwordx4 v[2:3], off
	v_lshl_add_u64 v[2:3], v[216:217], 0, s[14:15]
	s_mov_b32 m0, s62
	s_nop 0
	global_load_lds_dwordx4 v[2:3], off
	s_waitcnt vmcnt(8)
	s_waitcnt lgkmcnt(0)
	s_cbranch_vccnz .Lsegskip_3
	s_barrier
	v_mfma_f32_16x16x32_bf16 v[56:59], v[148:151], v[188:191], v[56:59]
	v_mfma_f32_16x16x32_bf16 v[52:55], v[156:159], v[188:191], v[52:55]
	v_mfma_f32_16x16x32_bf16 v[40:43], v[148:151], v[180:183], v[40:43]
	v_mfma_f32_16x16x32_bf16 v[36:39], v[156:159], v[180:183], v[36:39]
	v_mfma_f32_16x16x32_bf16 v[24:27], v[148:151], v[172:175], v[24:27]
	v_mfma_f32_16x16x32_bf16 v[20:23], v[156:159], v[172:175], v[20:23]
	v_mfma_f32_16x16x32_bf16 v[8:11], v[148:151], v[164:167], v[8:11]
	v_mfma_f32_16x16x32_bf16 v[2:5], v[156:159], v[164:167], v[4:7]
	v_mfma_f32_16x16x32_bf16 v[56:59], v[152:155], v[192:195], v[56:59]
	v_mfma_f32_16x16x32_bf16 v[52:55], v[160:163], v[192:195], v[52:55]
	v_mfma_f32_16x16x32_bf16 v[40:43], v[152:155], v[184:187], v[40:43]
	v_mfma_f32_16x16x32_bf16 v[36:39], v[160:163], v[184:187], v[36:39]
	v_mfma_f32_16x16x32_bf16 v[24:27], v[152:155], v[176:179], v[24:27]
	v_mfma_f32_16x16x32_bf16 v[20:23], v[160:163], v[176:179], v[20:23]
	v_mfma_f32_16x16x32_bf16 v[8:11], v[152:155], v[168:171], v[8:11]
	v_mfma_f32_16x16x32_bf16 v[4:7], v[160:163], v[168:171], v[2:5]
	v_mfma_f32_16x16x32_bf16 v[64:67], v[132:135], v[188:191], v[64:67]
	v_mfma_f32_16x16x32_bf16 v[60:63], v[140:143], v[188:191], v[60:63]
	v_mfma_f32_16x16x32_bf16 v[48:51], v[132:135], v[180:183], v[48:51]
	v_mfma_f32_16x16x32_bf16 v[44:47], v[140:143], v[180:183], v[44:47]
	v_mfma_f32_16x16x32_bf16 v[32:35], v[132:135], v[172:175], v[32:35]
	v_mfma_f32_16x16x32_bf16 v[28:31], v[140:143], v[172:175], v[28:31]
	v_mfma_f32_16x16x32_bf16 v[16:19], v[132:135], v[164:167], v[16:19]
	v_mfma_f32_16x16x32_bf16 v[12:15], v[140:143], v[164:167], v[12:15]
	v_mfma_f32_16x16x32_bf16 v[64:67], v[136:139], v[192:195], v[64:67]
	v_mfma_f32_16x16x32_bf16 v[60:63], v[144:147], v[192:195], v[60:63]
	v_mfma_f32_16x16x32_bf16 v[48:51], v[136:139], v[184:187], v[48:51]
	v_mfma_f32_16x16x32_bf16 v[44:47], v[144:147], v[184:187], v[44:47]
	v_mfma_f32_16x16x32_bf16 v[32:35], v[136:139], v[176:179], v[32:35]
	v_mfma_f32_16x16x32_bf16 v[28:31], v[144:147], v[176:179], v[28:31]
	v_mfma_f32_16x16x32_bf16 v[16:19], v[136:139], v[168:171], v[16:19]
	v_mfma_f32_16x16x32_bf16 v[12:15], v[144:147], v[168:171], v[12:15]
	s_barrier
	s_branch .Lsegback_3

.LBB0_1137:
	ds_read_b128 v[144:147], v151
	ds_read_b128 v[156:159], v151 offset:1024
	ds_read_b128 v[160:163], v151 offset:2048
	ds_read_b128 v[164:167], v151 offset:3072
	ds_read_b128 v[168:171], v152
	ds_read_b128 v[172:175], v152 offset:1024
	ds_read_b128 v[176:179], v152 offset:2048
	ds_read_b128 v[180:183], v152 offset:3072
	s_add_u32 s34, s30, 0x100
	s_addc_u32 s35, s31, 0
	s_cmpk_eq_i32 s66, 0x54
	s_cselect_b32 s49, s11, s35
	s_cselect_b32 s48, s10, s34
	s_cselect_b32 s37, s27, s47
	s_cselect_b32 s36, s26, s46
	v_lshl_add_u64 v[216:217], s[30:31], 0, v[138:139]
	s_add_i32 m0, s53, 0xc000
	ds_read_b128 v[184:187], v153
	ds_read_b128 v[188:191], v153 offset:1024
	ds_read_b128 v[192:195], v153 offset:2048
	ds_read_b128 v[196:199], v153 offset:3072
	ds_read_b128 v[200:203], v153 offset:4096
	ds_read_b128 v[204:207], v153 offset:5120
	ds_read_b128 v[208:211], v153 offset:6144
	ds_read_b128 v[212:215], v153 offset:7168
	global_load_lds_dwordx4 v[216:217], off
	v_lshl_add_u64 v[216:217], s[30:31], 0, v[136:137]
	s_add_i32 m0, s53, 0xe000
	s_nop 0
	global_load_lds_dwordx4 v[216:217], off
	s_waitcnt vmcnt(8)
	s_waitcnt lgkmcnt(0)
	s_barrier
	v_mfma_f32_16x16x32_bf16 v[124:127], v[144:147], v[184:187], v[124:127]
	v_mfma_f32_16x16x32_bf16 v[120:123], v[160:163], v[184:187], v[120:123]
	v_mfma_f32_16x16x32_bf16 v[108:111], v[144:147], v[192:195], v[108:111]
	v_mfma_f32_16x16x32_bf16 v[104:107], v[160:163], v[192:195], v[104:107]
	v_mfma_f32_16x16x32_bf16 v[92:95], v[144:147], v[200:203], v[92:95]
	v_mfma_f32_16x16x32_bf16 v[88:91], v[160:163], v[200:203], v[88:91]
	v_mfma_f32_16x16x32_bf16 v[76:79], v[144:147], v[208:211], v[76:79]
	v_mfma_f32_16x16x32_bf16 v[72:75], v[160:163], v[208:211], v[72:75]
	v_mfma_f32_16x16x32_bf16 v[124:127], v[156:159], v[188:191], v[124:127]
	v_mfma_f32_16x16x32_bf16 v[120:123], v[164:167], v[188:191], v[120:123]
	v_mfma_f32_16x16x32_bf16 v[108:111], v[156:159], v[196:199], v[108:111]
	v_mfma_f32_16x16x32_bf16 v[104:107], v[164:167], v[196:199], v[104:107]
	v_mfma_f32_16x16x32_bf16 v[92:95], v[156:159], v[204:207], v[92:95]
	v_mfma_f32_16x16x32_bf16 v[88:91], v[164:167], v[204:207], v[88:91]
	v_mfma_f32_16x16x32_bf16 v[76:79], v[156:159], v[212:215], v[76:79]
	v_mfma_f32_16x16x32_bf16 v[72:75], v[164:167], v[212:215], v[72:75]
	v_mfma_f32_16x16x32_bf16 v[116:119], v[168:171], v[184:187], v[116:119]
	v_mfma_f32_16x16x32_bf16 v[112:115], v[176:179], v[184:187], v[112:115]
	v_mfma_f32_16x16x32_bf16 v[100:103], v[168:171], v[192:195], v[100:103]
	v_mfma_f32_16x16x32_bf16 v[96:99], v[176:179], v[192:195], v[96:99]
	v_mfma_f32_16x16x32_bf16 v[84:87], v[168:171], v[200:203], v[84:87]
	v_mfma_f32_16x16x32_bf16 v[80:83], v[176:179], v[200:203], v[80:83]
	v_mfma_f32_16x16x32_bf16 v[68:71], v[168:171], v[208:211], v[68:71]
	v_mfma_f32_16x16x32_bf16 v[64:67], v[176:179], v[208:211], v[64:67]
	v_mfma_f32_16x16x32_bf16 v[116:119], v[172:175], v[188:191], v[116:119]
	v_mfma_f32_16x16x32_bf16 v[112:115], v[180:183], v[188:191], v[112:115]
	v_mfma_f32_16x16x32_bf16 v[100:103], v[172:175], v[196:199], v[100:103]
	v_mfma_f32_16x16x32_bf16 v[96:99], v[180:183], v[196:199], v[96:99]
	v_mfma_f32_16x16x32_bf16 v[84:87], v[172:175], v[204:207], v[84:87]
	v_mfma_f32_16x16x32_bf16 v[80:83], v[180:183], v[204:207], v[80:83]
	v_mfma_f32_16x16x32_bf16 v[68:71], v[172:175], v[212:215], v[68:71]
	v_mfma_f32_16x16x32_bf16 v[64:67], v[180:183], v[212:215], v[64:67]
	s_barrier
	s_add_i32 s30, s60, s52
	v_lshl_add_u64 v[216:217], s[36:37], 0, v[130:131]
	s_mov_b32 m0, s30
	ds_read_b128 v[184:187], v153 offset:16384
	ds_read_b128 v[188:191], v153 offset:17408
	ds_read_b128 v[192:195], v153 offset:18432
	ds_read_b128 v[196:199], v153 offset:19456
	ds_read_b128 v[200:203], v153 offset:20480
	ds_read_b128 v[204:207], v153 offset:21504
	ds_read_b128 v[208:211], v153 offset:22528
	ds_read_b128 v[212:215], v153 offset:23552
	global_load_lds_dwordx4 v[216:217], off
	s_add_i32 m0, s30, 0x2000
	s_add_u32 s30, s36, 0x160000
	v_lshl_add_u64 v[218:219], s[36:37], 0, v[134:135]
	s_addc_u32 s31, s37, 0
	s_add_i32 s67, s61, s52
	global_load_lds_dwordx4 v[218:219], off
	v_lshl_add_u64 v[220:221], s[30:31], 0, v[130:131]
	s_mov_b32 m0, s67
	v_lshl_add_u64 v[222:223], s[48:49], 0, v[132:133]
	global_load_lds_dwordx4 v[220:221], off
	v_lshl_add_u64 v[220:221], s[30:31], 0, v[134:135]
	s_add_i32 m0, s67, 0x2000
	s_nop 0
	global_load_lds_dwordx4 v[220:221], off
	v_lshl_add_u64 v[220:221], s[48:49], 0, v[128:129]
	s_mov_b32 m0, s53
	s_nop 0
	global_load_lds_dwordx4 v[220:221], off
	s_mov_b32 m0, s54
	s_nop 0
	global_load_lds_dwordx4 v[222:223], off
	s_waitcnt vmcnt(8)
	s_waitcnt lgkmcnt(0)
	s_barrier
	v_mfma_f32_16x16x32_bf16 v[60:63], v[144:147], v[184:187], v[60:63]
	v_mfma_f32_16x16x32_bf16 v[56:59], v[160:163], v[184:187], v[56:59]
	v_mfma_f32_16x16x32_bf16 v[44:47], v[144:147], v[192:195], v[44:47]
	v_mfma_f32_16x16x32_bf16 v[40:43], v[160:163], v[192:195], v[40:43]
	v_mfma_f32_16x16x32_bf16 v[28:31], v[144:147], v[200:203], v[28:31]
	v_mfma_f32_16x16x32_bf16 v[24:27], v[160:163], v[200:203], v[24:27]
	v_mfma_f32_16x16x32_bf16 v[12:15], v[144:147], v[208:211], v[12:15]
	v_mfma_f32_16x16x32_bf16 v[8:11], v[160:163], v[208:211], v[8:11]
	v_mfma_f32_16x16x32_bf16 v[60:63], v[156:159], v[188:191], v[60:63]
	v_mfma_f32_16x16x32_bf16 v[56:59], v[164:167], v[188:191], v[56:59]
	v_mfma_f32_16x16x32_bf16 v[44:47], v[156:159], v[196:199], v[44:47]
	v_mfma_f32_16x16x32_bf16 v[40:43], v[164:167], v[196:199], v[40:43]
	v_mfma_f32_16x16x32_bf16 v[28:31], v[156:159], v[204:207], v[28:31]
	v_mfma_f32_16x16x32_bf16 v[24:27], v[164:167], v[204:207], v[24:27]
	v_mfma_f32_16x16x32_bf16 v[12:15], v[156:159], v[212:215], v[12:15]
	v_mfma_f32_16x16x32_bf16 v[8:11], v[164:167], v[212:215], v[8:11]
	v_mfma_f32_16x16x32_bf16 v[52:55], v[168:171], v[184:187], v[52:55]
	v_mfma_f32_16x16x32_bf16 v[48:51], v[176:179], v[184:187], v[48:51]
	v_mfma_f32_16x16x32_bf16 v[36:39], v[168:171], v[192:195], v[36:39]
	v_mfma_f32_16x16x32_bf16 v[32:35], v[176:179], v[192:195], v[32:35]
	v_mfma_f32_16x16x32_bf16 v[20:23], v[168:171], v[200:203], v[20:23]
	v_mfma_f32_16x16x32_bf16 v[16:19], v[176:179], v[200:203], v[16:19]
	v_mfma_f32_16x16x32_bf16 v[4:7], v[168:171], v[208:211], v[4:7]
	v_mfma_f32_16x16x32_bf16 v[0:3], v[176:179], v[208:211], v[0:3]
	v_mfma_f32_16x16x32_bf16 v[52:55], v[172:175], v[188:191], v[52:55]
	v_mfma_f32_16x16x32_bf16 v[48:51], v[180:183], v[188:191], v[48:51]
	v_mfma_f32_16x16x32_bf16 v[36:39], v[172:175], v[196:199], v[36:39]
	v_mfma_f32_16x16x32_bf16 v[32:35], v[180:183], v[196:199], v[32:35]
	v_mfma_f32_16x16x32_bf16 v[20:23], v[172:175], v[204:207], v[20:23]
	v_mfma_f32_16x16x32_bf16 v[16:19], v[180:183], v[204:207], v[16:19]
	v_mfma_f32_16x16x32_bf16 v[4:7], v[172:175], v[212:215], v[4:7]
	v_mfma_f32_16x16x32_bf16 v[0:3], v[180:183], v[212:215], v[0:3]
	s_barrier
	s_add_i32 s67, 0, 0x18000
	v_add_u32_e32 v155, s67, v149
	s_add_i32 s68, 0, 0x1c000
	ds_read_b128 v[144:147], v155
	ds_read_b128 v[156:159], v155 offset:1024
	ds_read_b128 v[160:163], v155 offset:2048
	ds_read_b128 v[164:167], v155 offset:3072
	v_add_u32_e32 v155, s68, v149
	ds_read_b128 v[168:171], v155
	ds_read_b128 v[172:175], v155 offset:1024
	ds_read_b128 v[176:179], v155 offset:2048
	ds_read_b128 v[180:183], v155 offset:3072
	s_add_u32 s30, s48, 0x160000
	s_addc_u32 s31, s49, 0
	s_mov_b32 m0, s55
	v_lshl_add_u64 v[224:225], s[30:31], 0, v[128:129]
	ds_read_b128 v[184:187], v153 offset:32768
	ds_read_b128 v[188:191], v153 offset:33792
	ds_read_b128 v[192:195], v153 offset:34816
	ds_read_b128 v[196:199], v153 offset:35840
	ds_read_b128 v[200:203], v153 offset:36864
	ds_read_b128 v[204:207], v153 offset:37888
	ds_read_b128 v[208:211], v153 offset:38912
	ds_read_b128 v[212:215], v153 offset:39936
	global_load_lds_dwordx4 v[224:225], off
	v_lshl_add_u64 v[224:225], s[30:31], 0, v[132:133]
	s_mov_b32 m0, s56
	s_nop 0
	global_load_lds_dwordx4 v[224:225], off
	s_waitcnt vmcnt(8)
	s_waitcnt lgkmcnt(0)
	s_barrier
	v_mfma_f32_16x16x32_bf16 v[124:127], v[144:147], v[184:187], v[124:127]
	v_mfma_f32_16x16x32_bf16 v[120:123], v[160:163], v[184:187], v[120:123]
	v_mfma_f32_16x16x32_bf16 v[108:111], v[144:147], v[192:195], v[108:111]
	v_mfma_f32_16x16x32_bf16 v[104:107], v[160:163], v[192:195], v[104:107]
	v_mfma_f32_16x16x32_bf16 v[92:95], v[144:147], v[200:203], v[92:95]
	v_mfma_f32_16x16x32_bf16 v[88:91], v[160:163], v[200:203], v[88:91]
	v_mfma_f32_16x16x32_bf16 v[76:79], v[144:147], v[208:211], v[76:79]
	v_mfma_f32_16x16x32_bf16 v[72:75], v[160:163], v[208:211], v[72:75]
	v_mfma_f32_16x16x32_bf16 v[124:127], v[156:159], v[188:191], v[124:127]
	v_mfma_f32_16x16x32_bf16 v[120:123], v[164:167], v[188:191], v[120:123]
	v_mfma_f32_16x16x32_bf16 v[108:111], v[156:159], v[196:199], v[108:111]
	v_mfma_f32_16x16x32_bf16 v[104:107], v[164:167], v[196:199], v[104:107]
	v_mfma_f32_16x16x32_bf16 v[92:95], v[156:159], v[204:207], v[92:95]
	v_mfma_f32_16x16x32_bf16 v[88:91], v[164:167], v[204:207], v[88:91]
	v_mfma_f32_16x16x32_bf16 v[76:79], v[156:159], v[212:215], v[76:79]
	v_mfma_f32_16x16x32_bf16 v[72:75], v[164:167], v[212:215], v[72:75]
	v_mfma_f32_16x16x32_bf16 v[116:119], v[168:171], v[184:187], v[116:119]
	v_mfma_f32_16x16x32_bf16 v[112:115], v[176:179], v[184:187], v[112:115]
	v_mfma_f32_16x16x32_bf16 v[100:103], v[168:171], v[192:195], v[100:103]
	v_mfma_f32_16x16x32_bf16 v[96:99], v[176:179], v[192:195], v[96:99]
	v_mfma_f32_16x16x32_bf16 v[84:87], v[168:171], v[200:203], v[84:87]
	v_mfma_f32_16x16x32_bf16 v[80:83], v[176:179], v[200:203], v[80:83]
	v_mfma_f32_16x16x32_bf16 v[68:71], v[168:171], v[208:211], v[68:71]
	v_mfma_f32_16x16x32_bf16 v[64:67], v[176:179], v[208:211], v[64:67]
	v_mfma_f32_16x16x32_bf16 v[116:119], v[172:175], v[188:191], v[116:119]
	v_mfma_f32_16x16x32_bf16 v[112:115], v[180:183], v[188:191], v[112:115]
	v_mfma_f32_16x16x32_bf16 v[100:103], v[172:175], v[196:199], v[100:103]
	v_mfma_f32_16x16x32_bf16 v[96:99], v[180:183], v[196:199], v[96:99]
	v_mfma_f32_16x16x32_bf16 v[84:87], v[172:175], v[204:207], v[84:87]
	v_mfma_f32_16x16x32_bf16 v[80:83], v[180:183], v[204:207], v[80:83]
	v_mfma_f32_16x16x32_bf16 v[68:71], v[172:175], v[212:215], v[68:71]
	v_mfma_f32_16x16x32_bf16 v[64:67], v[180:183], v[212:215], v[64:67]
	s_barrier
	s_add_i32 s30, s67, s52
	v_lshl_add_u64 v[216:217], v[216:217], 0, s[22:23]
	s_mov_b32 m0, s30
	ds_read_b128 v[184:187], v153 offset:49152
	ds_read_b128 v[188:191], v153 offset:50176
	ds_read_b128 v[192:195], v153 offset:51200
	ds_read_b128 v[196:199], v153 offset:52224
	ds_read_b128 v[200:203], v153 offset:53248
	ds_read_b128 v[204:207], v153 offset:54272
	ds_read_b128 v[208:211], v153 offset:55296
	ds_read_b128 v[212:215], v153 offset:56320
	global_load_lds_dwordx4 v[216:217], off
	s_add_i32 m0, s30, 0x2000
	s_add_u32 s30, s36, 0x160080
	v_lshl_add_u64 v[216:217], v[218:219], 0, s[22:23]
	s_addc_u32 s31, s37, 0
	s_add_i32 s36, s68, s52
	global_load_lds_dwordx4 v[216:217], off
	v_lshl_add_u64 v[216:217], s[30:31], 0, v[130:131]
	s_mov_b32 m0, s36
	s_nop 0
	global_load_lds_dwordx4 v[216:217], off
	v_lshl_add_u64 v[216:217], s[30:31], 0, v[134:135]
	s_add_i32 m0, s36, 0x2000
	s_nop 0
	global_load_lds_dwordx4 v[216:217], off
	v_lshl_add_u64 v[216:217], v[220:221], 0, s[22:23]
	s_mov_b32 m0, s58
	s_nop 0
	global_load_lds_dwordx4 v[216:217], off
	v_lshl_add_u64 v[216:217], v[222:223], 0, s[22:23]
	s_mov_b32 m0, s59
	s_nop 0
	global_load_lds_dwordx4 v[216:217], off
	s_waitcnt vmcnt(8)
	s_waitcnt lgkmcnt(0)
	s_barrier
	v_mfma_f32_16x16x32_bf16 v[60:63], v[144:147], v[184:187], v[60:63]
	v_mfma_f32_16x16x32_bf16 v[56:59], v[160:163], v[184:187], v[56:59]
	v_mfma_f32_16x16x32_bf16 v[44:47], v[144:147], v[192:195], v[44:47]
	v_mfma_f32_16x16x32_bf16 v[40:43], v[160:163], v[192:195], v[40:43]
	v_mfma_f32_16x16x32_bf16 v[28:31], v[144:147], v[200:203], v[28:31]
	v_mfma_f32_16x16x32_bf16 v[24:27], v[160:163], v[200:203], v[24:27]
	v_mfma_f32_16x16x32_bf16 v[12:15], v[144:147], v[208:211], v[12:15]
	v_mfma_f32_16x16x32_bf16 v[8:11], v[160:163], v[208:211], v[8:11]
	v_mfma_f32_16x16x32_bf16 v[60:63], v[156:159], v[188:191], v[60:63]
	v_mfma_f32_16x16x32_bf16 v[56:59], v[164:167], v[188:191], v[56:59]
	v_mfma_f32_16x16x32_bf16 v[44:47], v[156:159], v[196:199], v[44:47]
	v_mfma_f32_16x16x32_bf16 v[40:43], v[164:167], v[196:199], v[40:43]
	v_mfma_f32_16x16x32_bf16 v[28:31], v[156:159], v[204:207], v[28:31]
	v_mfma_f32_16x16x32_bf16 v[24:27], v[164:167], v[204:207], v[24:27]
	v_mfma_f32_16x16x32_bf16 v[12:15], v[156:159], v[212:215], v[12:15]
	v_mfma_f32_16x16x32_bf16 v[8:11], v[164:167], v[212:215], v[8:11]
	v_mfma_f32_16x16x32_bf16 v[52:55], v[168:171], v[184:187], v[52:55]
	v_mfma_f32_16x16x32_bf16 v[48:51], v[176:179], v[184:187], v[48:51]
	v_mfma_f32_16x16x32_bf16 v[36:39], v[168:171], v[192:195], v[36:39]
	v_mfma_f32_16x16x32_bf16 v[32:35], v[176:179], v[192:195], v[32:35]
	v_mfma_f32_16x16x32_bf16 v[20:23], v[168:171], v[200:203], v[20:23]
	v_mfma_f32_16x16x32_bf16 v[16:19], v[176:179], v[200:203], v[16:19]
	v_mfma_f32_16x16x32_bf16 v[4:7], v[168:171], v[208:211], v[4:7]
	v_mfma_f32_16x16x32_bf16 v[0:3], v[176:179], v[208:211], v[0:3]
	v_mfma_f32_16x16x32_bf16 v[52:55], v[172:175], v[188:191], v[52:55]
	v_mfma_f32_16x16x32_bf16 v[48:51], v[180:183], v[188:191], v[48:51]
	v_mfma_f32_16x16x32_bf16 v[36:39], v[172:175], v[196:199], v[36:39]
	v_mfma_f32_16x16x32_bf16 v[32:35], v[180:183], v[196:199], v[32:35]
	v_mfma_f32_16x16x32_bf16 v[20:23], v[172:175], v[204:207], v[20:23]
	v_mfma_f32_16x16x32_bf16 v[16:19], v[180:183], v[204:207], v[16:19]
	v_mfma_f32_16x16x32_bf16 v[4:7], v[172:175], v[212:215], v[4:7]
	v_mfma_f32_16x16x32_bf16 v[0:3], v[180:183], v[212:215], v[0:3]
	s_barrier
	s_add_i32 s66, s66, 2
	s_add_u32 s46, s46, 0x100
	s_addc_u32 s47, s47, 0
	s_cmpk_gt_u32 s66, 0x55
	s_mov_b64 s[30:31], s[34:35]
	s_cbranch_scc0 .LBB0_1137
	s_and_b64 vcc, exec, s[24:25]
	s_cbranch_vccz .LBB0_1140
	s_barrier

.LBB0_1227:
	v_add_u32_e32 v164, s56, v150
	v_add_u32_e32 v180, s57, v150
	s_add_u32 s34, s16, s30
	ds_read_b128 v[152:155], v164
	ds_read_b128 v[156:159], v164 offset:1024
	ds_read_b128 v[160:163], v164 offset:2048
	ds_read_b128 v[164:167], v164 offset:3072
	ds_read_b128 v[168:171], v180
	ds_read_b128 v[172:175], v180 offset:1024
	ds_read_b128 v[176:179], v180 offset:2048
	ds_read_b128 v[180:183], v180 offset:3072
	s_addc_u32 s35, s17, s31
	s_add_u32 s34, s34, 0x100
	s_addc_u32 s35, s35, 0
	s_add_u32 s64, s59, s30
	s_addc_u32 s65, s60, s31
	s_cmpk_eq_i32 s30, 0xf00
	s_cselect_b32 s37, s23, s35
	s_cselect_b32 s36, s61, s34
	s_cselect_b32 s35, s21, s65
	s_cselect_b32 s34, s62, s64
	v_lshl_add_u64 v[216:217], v[146:147], 0, s[30:31]
	s_add_i32 m0, s48, 0xc000
	ds_read_b128 v[184:187], v151
	ds_read_b128 v[188:191], v151 offset:1024
	ds_read_b128 v[192:195], v151 offset:2048
	ds_read_b128 v[196:199], v151 offset:3072
	ds_read_b128 v[200:203], v151 offset:4096
	ds_read_b128 v[204:207], v151 offset:5120
	ds_read_b128 v[208:211], v151 offset:6144
	ds_read_b128 v[212:215], v151 offset:7168
	global_load_lds_dwordx4 v[216:217], off
	v_lshl_add_u64 v[216:217], v[144:145], 0, s[30:31]
	s_add_i32 m0, s48, 0xe000
	s_nop 0
	global_load_lds_dwordx4 v[216:217], off
	s_waitcnt vmcnt(8)
	s_waitcnt lgkmcnt(0)
	s_barrier
	v_mfma_f32_16x16x32_bf16 v[124:127], v[152:155], v[184:187], v[124:127]
	v_mfma_f32_16x16x32_bf16 v[120:123], v[160:163], v[184:187], v[120:123]
	v_mfma_f32_16x16x32_bf16 v[108:111], v[152:155], v[192:195], v[108:111]
	v_mfma_f32_16x16x32_bf16 v[104:107], v[160:163], v[192:195], v[104:107]
	v_mfma_f32_16x16x32_bf16 v[92:95], v[152:155], v[200:203], v[92:95]
	v_mfma_f32_16x16x32_bf16 v[88:91], v[160:163], v[200:203], v[88:91]
	v_mfma_f32_16x16x32_bf16 v[76:79], v[152:155], v[208:211], v[76:79]
	v_mfma_f32_16x16x32_bf16 v[72:75], v[160:163], v[208:211], v[72:75]
	v_mfma_f32_16x16x32_bf16 v[124:127], v[156:159], v[188:191], v[124:127]
	v_mfma_f32_16x16x32_bf16 v[120:123], v[164:167], v[188:191], v[120:123]
	v_mfma_f32_16x16x32_bf16 v[108:111], v[156:159], v[196:199], v[108:111]
	v_mfma_f32_16x16x32_bf16 v[104:107], v[164:167], v[196:199], v[104:107]
	v_mfma_f32_16x16x32_bf16 v[92:95], v[156:159], v[204:207], v[92:95]
	v_mfma_f32_16x16x32_bf16 v[88:91], v[164:167], v[204:207], v[88:91]
	v_mfma_f32_16x16x32_bf16 v[76:79], v[156:159], v[212:215], v[76:79]
	v_mfma_f32_16x16x32_bf16 v[72:75], v[164:167], v[212:215], v[72:75]
	v_mfma_f32_16x16x32_bf16 v[116:119], v[168:171], v[184:187], v[116:119]
	v_mfma_f32_16x16x32_bf16 v[112:115], v[176:179], v[184:187], v[112:115]
	v_mfma_f32_16x16x32_bf16 v[100:103], v[168:171], v[192:195], v[100:103]
	v_mfma_f32_16x16x32_bf16 v[96:99], v[176:179], v[192:195], v[96:99]
	v_mfma_f32_16x16x32_bf16 v[84:87], v[168:171], v[200:203], v[84:87]
	v_mfma_f32_16x16x32_bf16 v[80:83], v[176:179], v[200:203], v[80:83]
	v_mfma_f32_16x16x32_bf16 v[68:71], v[168:171], v[208:211], v[68:71]
	v_mfma_f32_16x16x32_bf16 v[64:67], v[176:179], v[208:211], v[64:67]
	v_mfma_f32_16x16x32_bf16 v[116:119], v[172:175], v[188:191], v[116:119]
	v_mfma_f32_16x16x32_bf16 v[112:115], v[180:183], v[188:191], v[112:115]
	v_mfma_f32_16x16x32_bf16 v[100:103], v[172:175], v[196:199], v[100:103]
	v_mfma_f32_16x16x32_bf16 v[96:99], v[180:183], v[196:199], v[96:99]
	v_mfma_f32_16x16x32_bf16 v[84:87], v[172:175], v[204:207], v[84:87]
	v_mfma_f32_16x16x32_bf16 v[80:83], v[180:183], v[204:207], v[80:83]
	v_mfma_f32_16x16x32_bf16 v[68:71], v[172:175], v[212:215], v[68:71]
	v_mfma_f32_16x16x32_bf16 v[64:67], v[180:183], v[212:215], v[64:67]
	s_barrier
	s_add_i32 s64, s56, s47
	v_lshl_add_u64 v[216:217], s[34:35], 0, v[130:131]
	s_mov_b32 m0, s64
	ds_read_b128 v[184:187], v151 offset:16384
	ds_read_b128 v[188:191], v151 offset:17408
	ds_read_b128 v[192:195], v151 offset:18432
	ds_read_b128 v[196:199], v151 offset:19456
	ds_read_b128 v[200:203], v151 offset:20480
	ds_read_b128 v[204:207], v151 offset:21504
	ds_read_b128 v[208:211], v151 offset:22528
	ds_read_b128 v[212:215], v151 offset:23552
	global_load_lds_dwordx4 v[216:217], off
	s_add_i32 m0, s64, 0x2000
	s_add_u32 s64, s34, 0x80000
	v_lshl_add_u64 v[218:219], s[34:35], 0, v[134:135]
	s_addc_u32 s65, s35, 0
	s_add_i32 s66, s57, s47
	global_load_lds_dwordx4 v[218:219], off
	v_lshl_add_u64 v[220:221], s[64:65], 0, v[130:131]
	s_mov_b32 m0, s66
	v_lshl_add_u64 v[222:223], s[36:37], 0, v[132:133]
	global_load_lds_dwordx4 v[220:221], off
	v_lshl_add_u64 v[220:221], s[64:65], 0, v[134:135]
	s_add_i32 m0, s66, 0x2000
	s_nop 0
	global_load_lds_dwordx4 v[220:221], off
	v_lshl_add_u64 v[220:221], s[36:37], 0, v[128:129]
	s_mov_b32 m0, s48
	s_nop 0
	global_load_lds_dwordx4 v[220:221], off
	s_mov_b32 m0, s49
	s_nop 0
	global_load_lds_dwordx4 v[222:223], off
	s_waitcnt vmcnt(8)
	s_waitcnt lgkmcnt(0)
	s_barrier
	v_mfma_f32_16x16x32_bf16 v[60:63], v[152:155], v[184:187], v[60:63]
	v_mfma_f32_16x16x32_bf16 v[56:59], v[160:163], v[184:187], v[56:59]
	v_mfma_f32_16x16x32_bf16 v[44:47], v[152:155], v[192:195], v[44:47]
	v_mfma_f32_16x16x32_bf16 v[40:43], v[160:163], v[192:195], v[40:43]
	v_mfma_f32_16x16x32_bf16 v[28:31], v[152:155], v[200:203], v[28:31]
	v_mfma_f32_16x16x32_bf16 v[24:27], v[160:163], v[200:203], v[24:27]
	v_mfma_f32_16x16x32_bf16 v[12:15], v[152:155], v[208:211], v[12:15]
	v_mfma_f32_16x16x32_bf16 v[8:11], v[160:163], v[208:211], v[8:11]
	v_mfma_f32_16x16x32_bf16 v[60:63], v[156:159], v[188:191], v[60:63]
	v_mfma_f32_16x16x32_bf16 v[56:59], v[164:167], v[188:191], v[56:59]
	v_mfma_f32_16x16x32_bf16 v[44:47], v[156:159], v[196:199], v[44:47]
	v_mfma_f32_16x16x32_bf16 v[40:43], v[164:167], v[196:199], v[40:43]
	v_mfma_f32_16x16x32_bf16 v[28:31], v[156:159], v[204:207], v[28:31]
	v_mfma_f32_16x16x32_bf16 v[24:27], v[164:167], v[204:207], v[24:27]
	v_mfma_f32_16x16x32_bf16 v[12:15], v[156:159], v[212:215], v[12:15]
	v_mfma_f32_16x16x32_bf16 v[8:11], v[164:167], v[212:215], v[8:11]
	v_mfma_f32_16x16x32_bf16 v[52:55], v[168:171], v[184:187], v[52:55]
	v_mfma_f32_16x16x32_bf16 v[48:51], v[176:179], v[184:187], v[48:51]
	v_mfma_f32_16x16x32_bf16 v[36:39], v[168:171], v[192:195], v[36:39]
	v_mfma_f32_16x16x32_bf16 v[32:35], v[176:179], v[192:195], v[32:35]
	v_mfma_f32_16x16x32_bf16 v[20:23], v[168:171], v[200:203], v[20:23]
	v_mfma_f32_16x16x32_bf16 v[16:19], v[176:179], v[200:203], v[16:19]
	v_mfma_f32_16x16x32_bf16 v[4:7], v[168:171], v[208:211], v[4:7]
	v_mfma_f32_16x16x32_bf16 v[0:3], v[176:179], v[208:211], v[0:3]
	v_mfma_f32_16x16x32_bf16 v[52:55], v[172:175], v[188:191], v[52:55]
	v_mfma_f32_16x16x32_bf16 v[48:51], v[180:183], v[188:191], v[48:51]
	v_mfma_f32_16x16x32_bf16 v[36:39], v[172:175], v[196:199], v[36:39]
	v_mfma_f32_16x16x32_bf16 v[32:35], v[180:183], v[196:199], v[32:35]
	v_mfma_f32_16x16x32_bf16 v[20:23], v[172:175], v[204:207], v[20:23]
	v_mfma_f32_16x16x32_bf16 v[16:19], v[180:183], v[204:207], v[16:19]
	v_mfma_f32_16x16x32_bf16 v[4:7], v[172:175], v[212:215], v[4:7]
	v_mfma_f32_16x16x32_bf16 v[0:3], v[180:183], v[212:215], v[0:3]
	s_barrier
	s_add_i32 s64, 0, 0x18000
	s_add_i32 s65, 0, 0x1c000
	v_add_u32_e32 v164, s64, v150
	v_add_u32_e32 v180, s65, v150
	ds_read_b128 v[152:155], v164
	ds_read_b128 v[156:159], v164 offset:1024
	ds_read_b128 v[160:163], v164 offset:2048
	ds_read_b128 v[164:167], v164 offset:3072
	ds_read_b128 v[168:171], v180
	ds_read_b128 v[172:175], v180 offset:1024
	ds_read_b128 v[176:179], v180 offset:2048
	ds_read_b128 v[180:183], v180 offset:3072
	s_add_u32 s36, s36, 0x80000
	s_addc_u32 s37, s37, 0
	s_mov_b32 m0, s50
	v_lshl_add_u64 v[224:225], s[36:37], 0, v[128:129]
	ds_read_b128 v[184:187], v151 offset:32768
	ds_read_b128 v[188:191], v151 offset:33792
	ds_read_b128 v[192:195], v151 offset:34816
	ds_read_b128 v[196:199], v151 offset:35840
	ds_read_b128 v[200:203], v151 offset:36864
	ds_read_b128 v[204:207], v151 offset:37888
	ds_read_b128 v[208:211], v151 offset:38912
	ds_read_b128 v[212:215], v151 offset:39936
	global_load_lds_dwordx4 v[224:225], off
	v_lshl_add_u64 v[224:225], s[36:37], 0, v[132:133]
	s_mov_b32 m0, s51
	s_nop 0
	global_load_lds_dwordx4 v[224:225], off
	s_waitcnt vmcnt(8)
	s_waitcnt lgkmcnt(0)
	s_barrier
	v_mfma_f32_16x16x32_bf16 v[124:127], v[152:155], v[184:187], v[124:127]
	v_mfma_f32_16x16x32_bf16 v[120:123], v[160:163], v[184:187], v[120:123]
	v_mfma_f32_16x16x32_bf16 v[108:111], v[152:155], v[192:195], v[108:111]
	v_mfma_f32_16x16x32_bf16 v[104:107], v[160:163], v[192:195], v[104:107]
	v_mfma_f32_16x16x32_bf16 v[92:95], v[152:155], v[200:203], v[92:95]
	v_mfma_f32_16x16x32_bf16 v[88:91], v[160:163], v[200:203], v[88:91]
	v_mfma_f32_16x16x32_bf16 v[76:79], v[152:155], v[208:211], v[76:79]
	v_mfma_f32_16x16x32_bf16 v[72:75], v[160:163], v[208:211], v[72:75]
	v_mfma_f32_16x16x32_bf16 v[124:127], v[156:159], v[188:191], v[124:127]
	v_mfma_f32_16x16x32_bf16 v[120:123], v[164:167], v[188:191], v[120:123]
	v_mfma_f32_16x16x32_bf16 v[108:111], v[156:159], v[196:199], v[108:111]
	v_mfma_f32_16x16x32_bf16 v[104:107], v[164:167], v[196:199], v[104:107]
	v_mfma_f32_16x16x32_bf16 v[92:95], v[156:159], v[204:207], v[92:95]
	v_mfma_f32_16x16x32_bf16 v[88:91], v[164:167], v[204:207], v[88:91]
	v_mfma_f32_16x16x32_bf16 v[76:79], v[156:159], v[212:215], v[76:79]
	v_mfma_f32_16x16x32_bf16 v[72:75], v[164:167], v[212:215], v[72:75]
	v_mfma_f32_16x16x32_bf16 v[116:119], v[168:171], v[184:187], v[116:119]
	v_mfma_f32_16x16x32_bf16 v[112:115], v[176:179], v[184:187], v[112:115]
	v_mfma_f32_16x16x32_bf16 v[100:103], v[168:171], v[192:195], v[100:103]
	v_mfma_f32_16x16x32_bf16 v[96:99], v[176:179], v[192:195], v[96:99]
	v_mfma_f32_16x16x32_bf16 v[84:87], v[168:171], v[200:203], v[84:87]
	v_mfma_f32_16x16x32_bf16 v[80:83], v[176:179], v[200:203], v[80:83]
	v_mfma_f32_16x16x32_bf16 v[68:71], v[168:171], v[208:211], v[68:71]
	v_mfma_f32_16x16x32_bf16 v[64:67], v[176:179], v[208:211], v[64:67]
	v_mfma_f32_16x16x32_bf16 v[116:119], v[172:175], v[188:191], v[116:119]
	v_mfma_f32_16x16x32_bf16 v[112:115], v[180:183], v[188:191], v[112:115]
	v_mfma_f32_16x16x32_bf16 v[100:103], v[172:175], v[196:199], v[100:103]
	v_mfma_f32_16x16x32_bf16 v[96:99], v[180:183], v[196:199], v[96:99]
	v_mfma_f32_16x16x32_bf16 v[84:87], v[172:175], v[204:207], v[84:87]
	v_mfma_f32_16x16x32_bf16 v[80:83], v[180:183], v[204:207], v[80:83]
	v_mfma_f32_16x16x32_bf16 v[68:71], v[172:175], v[212:215], v[68:71]
	v_mfma_f32_16x16x32_bf16 v[64:67], v[180:183], v[212:215], v[64:67]
	s_barrier
	s_add_i32 s36, s64, s47
	v_lshl_add_u64 v[216:217], v[216:217], 0, s[18:19]
	s_mov_b32 m0, s36
	ds_read_b128 v[184:187], v151 offset:49152
	ds_read_b128 v[188:191], v151 offset:50176
	ds_read_b128 v[192:195], v151 offset:51200
	ds_read_b128 v[196:199], v151 offset:52224
	ds_read_b128 v[200:203], v151 offset:53248
	ds_read_b128 v[204:207], v151 offset:54272
	ds_read_b128 v[208:211], v151 offset:55296
	ds_read_b128 v[212:215], v151 offset:56320
	global_load_lds_dwordx4 v[216:217], off
	s_add_i32 m0, s36, 0x2000
	s_add_u32 s34, s34, 0x80080
	v_lshl_add_u64 v[216:217], v[218:219], 0, s[18:19]
	s_addc_u32 s35, s35, 0
	s_add_i32 s36, s65, s47
	global_load_lds_dwordx4 v[216:217], off
	v_lshl_add_u64 v[216:217], s[34:35], 0, v[130:131]
	s_mov_b32 m0, s36
	s_nop 0
	global_load_lds_dwordx4 v[216:217], off
	v_lshl_add_u64 v[216:217], s[34:35], 0, v[134:135]
	s_add_i32 m0, s36, 0x2000
	s_nop 0
	global_load_lds_dwordx4 v[216:217], off
	v_lshl_add_u64 v[216:217], v[220:221], 0, s[18:19]
	s_mov_b32 m0, s54
	s_nop 0
	global_load_lds_dwordx4 v[216:217], off
	v_lshl_add_u64 v[216:217], v[222:223], 0, s[18:19]
	s_mov_b32 m0, s55
	s_nop 0
	global_load_lds_dwordx4 v[216:217], off
	s_waitcnt vmcnt(8)
	s_waitcnt lgkmcnt(0)
	s_barrier
	v_mfma_f32_16x16x32_bf16 v[60:63], v[152:155], v[184:187], v[60:63]
	v_mfma_f32_16x16x32_bf16 v[56:59], v[160:163], v[184:187], v[56:59]
	v_mfma_f32_16x16x32_bf16 v[44:47], v[152:155], v[192:195], v[44:47]
	v_mfma_f32_16x16x32_bf16 v[40:43], v[160:163], v[192:195], v[40:43]
	v_mfma_f32_16x16x32_bf16 v[28:31], v[152:155], v[200:203], v[28:31]
	v_mfma_f32_16x16x32_bf16 v[24:27], v[160:163], v[200:203], v[24:27]
	v_mfma_f32_16x16x32_bf16 v[12:15], v[152:155], v[208:211], v[12:15]
	v_mfma_f32_16x16x32_bf16 v[8:11], v[160:163], v[208:211], v[8:11]
	v_mfma_f32_16x16x32_bf16 v[60:63], v[156:159], v[188:191], v[60:63]
	v_mfma_f32_16x16x32_bf16 v[56:59], v[164:167], v[188:191], v[56:59]
	v_mfma_f32_16x16x32_bf16 v[44:47], v[156:159], v[196:199], v[44:47]
	v_mfma_f32_16x16x32_bf16 v[40:43], v[164:167], v[196:199], v[40:43]
	v_mfma_f32_16x16x32_bf16 v[28:31], v[156:159], v[204:207], v[28:31]
	v_mfma_f32_16x16x32_bf16 v[24:27], v[164:167], v[204:207], v[24:27]
	v_mfma_f32_16x16x32_bf16 v[12:15], v[156:159], v[212:215], v[12:15]
	v_mfma_f32_16x16x32_bf16 v[8:11], v[164:167], v[212:215], v[8:11]
	v_mfma_f32_16x16x32_bf16 v[52:55], v[168:171], v[184:187], v[52:55]
	v_mfma_f32_16x16x32_bf16 v[48:51], v[176:179], v[184:187], v[48:51]
	v_mfma_f32_16x16x32_bf16 v[36:39], v[168:171], v[192:195], v[36:39]
	v_mfma_f32_16x16x32_bf16 v[32:35], v[176:179], v[192:195], v[32:35]
	v_mfma_f32_16x16x32_bf16 v[20:23], v[168:171], v[200:203], v[20:23]
	v_mfma_f32_16x16x32_bf16 v[16:19], v[176:179], v[200:203], v[16:19]
	v_mfma_f32_16x16x32_bf16 v[4:7], v[168:171], v[208:211], v[4:7]
	v_mfma_f32_16x16x32_bf16 v[0:3], v[176:179], v[208:211], v[0:3]
	v_mfma_f32_16x16x32_bf16 v[52:55], v[172:175], v[188:191], v[52:55]
	v_mfma_f32_16x16x32_bf16 v[48:51], v[180:183], v[188:191], v[48:51]
	v_mfma_f32_16x16x32_bf16 v[36:39], v[172:175], v[196:199], v[36:39]
	v_mfma_f32_16x16x32_bf16 v[32:35], v[180:183], v[196:199], v[32:35]
	v_mfma_f32_16x16x32_bf16 v[20:23], v[172:175], v[204:207], v[20:23]
	v_mfma_f32_16x16x32_bf16 v[16:19], v[180:183], v[204:207], v[16:19]
	v_mfma_f32_16x16x32_bf16 v[4:7], v[172:175], v[212:215], v[4:7]
	v_mfma_f32_16x16x32_bf16 v[0:3], v[180:183], v[212:215], v[0:3]
	s_barrier
	s_add_i32 s63, s63, 2
	s_add_u32 s30, s30, 0x100
	s_addc_u32 s31, s31, 0
	s_cmp_gt_u32 s63, 29
	s_cbranch_scc0 .LBB0_1227
	s_add_u32 s30, s59, 0xffffff00
	s_addc_u32 s31, s60, -1
	s_andn2_b64 vcc, exec, s[4:5]
	s_cbranch_vccnz .LBB0_1230
	v_mov_b32_e32 v0, 0
	s_mov_b32 s15, s20
	s_mov_b32 s14, s22
	s_mov_b64 s[16:17], s[26:27]
	s_mov_b32 s53, s58
	v_mov_b32_e32 v1, v0
	v_pk_mov_b32 v[2:3], 0, 0
	v_pk_mov_b32 v[4:5], 0, 0
	v_pk_mov_b32 v[6:7], 0, 0
	v_pk_mov_b32 v[16:17], 0, 0
	v_pk_mov_b32 v[18:19], 0, 0
	v_pk_mov_b32 v[20:21], 0, 0
	v_pk_mov_b32 v[22:23], 0, 0
	v_pk_mov_b32 v[32:33], 0, 0
	v_pk_mov_b32 v[34:35], 0, 0
	v_pk_mov_b32 v[36:37], 0, 0
	v_pk_mov_b32 v[38:39], 0, 0
	v_pk_mov_b32 v[48:49], 0, 0
	v_pk_mov_b32 v[50:51], 0, 0
	v_pk_mov_b32 v[52:53], 0, 0
	v_pk_mov_b32 v[54:55], 0, 0
	v_pk_mov_b32 v[8:9], 0, 0
	v_pk_mov_b32 v[10:11], 0, 0
	v_pk_mov_b32 v[12:13], 0, 0
	v_pk_mov_b32 v[14:15], 0, 0
	v_pk_mov_b32 v[24:25], 0, 0
	v_pk_mov_b32 v[26:27], 0, 0
	v_pk_mov_b32 v[28:29], 0, 0
	v_pk_mov_b32 v[30:31], 0, 0
	v_pk_mov_b32 v[40:41], 0, 0
	v_pk_mov_b32 v[42:43], 0, 0
	v_pk_mov_b32 v[44:45], 0, 0
	v_pk_mov_b32 v[46:47], 0, 0
	v_pk_mov_b32 v[56:57], 0, 0
	v_pk_mov_b32 v[58:59], 0, 0
	v_pk_mov_b32 v[60:61], 0, 0
	v_pk_mov_b32 v[62:63], 0, 0
	v_pk_mov_b32 v[64:65], 0, 0
	v_pk_mov_b32 v[66:67], 0, 0
	v_pk_mov_b32 v[68:69], 0, 0
	v_pk_mov_b32 v[70:71], 0, 0
	v_pk_mov_b32 v[80:81], 0, 0
	v_pk_mov_b32 v[82:83], 0, 0
	v_pk_mov_b32 v[84:85], 0, 0
	v_pk_mov_b32 v[86:87], 0, 0
	v_pk_mov_b32 v[96:97], 0, 0
	v_pk_mov_b32 v[98:99], 0, 0
	v_pk_mov_b32 v[100:101], 0, 0
	v_pk_mov_b32 v[102:103], 0, 0
	v_pk_mov_b32 v[112:113], 0, 0
	v_pk_mov_b32 v[114:115], 0, 0
	v_pk_mov_b32 v[116:117], 0, 0
	v_pk_mov_b32 v[118:119], 0, 0
	v_pk_mov_b32 v[72:73], 0, 0
	v_pk_mov_b32 v[74:75], 0, 0
	v_pk_mov_b32 v[76:77], 0, 0
	v_pk_mov_b32 v[78:79], 0, 0
	v_pk_mov_b32 v[88:89], 0, 0
	v_pk_mov_b32 v[90:91], 0, 0
	v_pk_mov_b32 v[92:93], 0, 0
	v_pk_mov_b32 v[94:95], 0, 0
	v_pk_mov_b32 v[104:105], 0, 0
	v_pk_mov_b32 v[106:107], 0, 0
	v_pk_mov_b32 v[108:109], 0, 0
	v_pk_mov_b32 v[110:111], 0, 0
	v_pk_mov_b32 v[120:121], 0, 0
	v_pk_mov_b32 v[122:123], 0, 0
	v_pk_mov_b32 v[124:125], 0, 0
	v_pk_mov_b32 v[126:127], 0, 0
	s_andn2_b64 vcc, exec, s[0:1]
	s_cbranch_vccnz .LBB0_1231
	s_branch .LBB0_1232
